# v34 + all 16-byte global stores made write-through (sc1) so the grid-barrier release fence finds a clean L2
# speedup vs baseline: 1.0034x; 1.0034x over previous
.LBB0_9:
	v_ashrrev_i32_e32 v7, 31, v6
	v_lshl_add_u64 v[8:9], v[6:7], 4, s[2:3]
	v_add_u32_e32 v6, s8, v6
	v_cmp_lt_i32_e32 vcc, s9, v6
	s_or_b64 s[6:7], vcc, s[6:7]
	global_store_dwordx4 v[8:9], v[2:5], off sc1
	s_andn2_b64 exec, exec, s[6:7]
	s_cbranch_execnz .LBB0_9

.LBB0_14:
	s_mul_i32 s47, s47, s43
	s_sub_i32 s36, s45, s47
	s_ashr_i32 s43, s42, 31
	s_lshl_b32 s36, s36, 6
	s_lshl_b64 s[42:43], s[42:43], 2
	s_add_u32 s30, s30, s42
	s_addc_u32 s31, s31, s43
	v_or_b32_e32 v14, s36, v6
	s_ashr_i32 s37, s36, 31
	v_lshl_add_u64 v[18:19], s[30:31], 0, v[2:3]
	s_mul_i32 s42, s34, s37
	v_mul_lo_u32 v16, s35, v14
	v_mad_u64_u32 v[14:15], s[30:31], s34, v14, 0
	v_add_u32_e32 v20, s36, v8
	v_add3_u32 v15, v15, s42, v16
	v_ashrrev_i32_e32 v21, 31, v20
	v_lshl_add_u64 v[14:15], v[14:15], 2, v[18:19]
	v_mul_lo_u32 v22, s34, v21
	v_mul_lo_u32 v23, s35, v20
	v_mad_u64_u32 v[20:21], s[30:31], s34, v20, 0
	global_load_dwordx4 v[14:17], v[14:15], off
	v_add3_u32 v21, v21, v22, v23
	v_lshl_add_u64 v[18:19], v[20:21], 2, v[18:19]
	global_load_dwordx4 v[18:21], v[18:19], off
	v_add_u32_e32 v22, s46, v7
	v_ashrrev_i32_e32 v25, 31, v22
	v_mad_u64_u32 v[22:23], s[30:31], v22, s44, 0
	v_mov_b32_e32 v24, v23
	v_mad_u64_u32 v[24:25], s[30:31], v25, s44, v[24:25]
	v_mov_b32_e32 v23, v24
	v_lshl_add_u64 v[22:23], v[22:23], 1, s[28:29]
	s_add_i32 s41, s41, s72
	v_lshl_add_u64 v[22:23], s[36:37], 1, v[22:23]
	s_cmpk_gt_i32 s41, 0x2c1f
	v_lshl_add_u64 v[22:23], v[22:23], 0, v[4:5]
	s_waitcnt vmcnt(1)
	ds_write2_b32 v9, v14, v15 offset1:1
	ds_write2_b32 v9, v16, v17 offset0:2 offset1:3
	s_waitcnt vmcnt(0)
	ds_write2_b32 v10, v18, v19 offset1:1
	ds_write2_b32 v11, v20, v21 offset1:1
	s_waitcnt lgkmcnt(0)
	s_barrier
	ds_read2_b32 v[14:15], v12 offset1:65
	ds_read2_b32 v[16:17], v12 offset0:130 offset1:195
	ds_read2_b32 v[18:19], v13 offset0:4 offset1:69
	ds_read2_b32 v[20:21], v13 offset0:134 offset1:199
	s_waitcnt lgkmcnt(3)
	v_cvt_pk_bf16_f32 v14, v14, v15
	s_waitcnt lgkmcnt(2)
	v_cvt_pk_bf16_f32 v15, v16, v17
	s_waitcnt lgkmcnt(1)
	v_cvt_pk_bf16_f32 v16, v18, v19
	s_waitcnt lgkmcnt(0)
	v_cvt_pk_bf16_f32 v17, v20, v21
	global_store_dwordx4 v[22:23], v[14:17], off sc1
	s_barrier
	s_cbranch_scc1 .LBB0_34

.LBB0_269:
	ds_read_b128 v[146:149], v152
	ds_read_b128 v[156:159], v152 offset:1024
	ds_read_b128 v[160:163], v152 offset:2048
	ds_read_b128 v[164:167], v152 offset:3072
	s_add_u32 s24, s22, 0xfff80080
	s_addc_u32 s25, s23, -1
	s_cmp_eq_u32 s61, 28
	s_cselect_b32 s27, s9, s25
	s_cselect_b32 s26, s53, s24
	s_cselect_b32 s25, s7, s60
	s_cselect_b32 s24, s58, s59
	v_lshl_add_u64 v[202:203], s[22:23], 0, v[138:139]
	s_add_i32 m0, s21, 0xc000
	ds_read_b128 v[168:171], v153
	ds_read_b128 v[172:175], v153 offset:1024
	ds_read_b128 v[176:179], v153 offset:2048
	ds_read_b128 v[180:183], v153 offset:3072
	ds_read_b128 v[186:189], v153 offset:4096
	ds_read_b128 v[190:193], v153 offset:5120
	ds_read_b128 v[194:197], v153 offset:6144
	ds_read_b128 v[198:201], v153 offset:7168
	global_load_lds_dwordx4 v[202:203], off
	v_lshl_add_u64 v[202:203], s[22:23], 0, v[140:141]
	s_add_i32 m0, s21, 0xe000
	s_nop 0
	global_load_lds_dwordx4 v[202:203], off
	ds_read_b128 v[202:205], v154
	ds_read_b128 v[206:209], v154 offset:1024
	ds_read_b128 v[210:213], v154 offset:2048
	ds_read_b128 v[214:217], v154 offset:3072
	s_waitcnt vmcnt(8)
	s_waitcnt lgkmcnt(0)
	s_barrier
	s_setprio 1
	v_mfma_f32_16x16x32_bf16 v[126:129], v[146:149], v[168:171], v[126:129]
	v_mfma_f32_16x16x32_bf16 v[122:125], v[160:163], v[168:171], v[122:125]
	v_mfma_f32_16x16x32_bf16 v[118:121], v[146:149], v[176:179], v[118:121]
	v_mfma_f32_16x16x32_bf16 v[110:113], v[160:163], v[176:179], v[110:113]
	v_mfma_f32_16x16x32_bf16 v[102:105], v[146:149], v[186:189], v[102:105]
	v_mfma_f32_16x16x32_bf16 v[94:97], v[160:163], v[186:189], v[94:97]
	v_mfma_f32_16x16x32_bf16 v[86:89], v[146:149], v[194:197], v[86:89]
	v_mfma_f32_16x16x32_bf16 v[78:81], v[160:163], v[194:197], v[78:81]
	v_mfma_f32_16x16x32_bf16 v[126:129], v[156:159], v[172:175], v[126:129]
	v_mfma_f32_16x16x32_bf16 v[122:125], v[164:167], v[172:175], v[122:125]
	v_mfma_f32_16x16x32_bf16 v[118:121], v[156:159], v[180:183], v[118:121]
	v_mfma_f32_16x16x32_bf16 v[110:113], v[164:167], v[180:183], v[110:113]
	v_mfma_f32_16x16x32_bf16 v[102:105], v[156:159], v[190:193], v[102:105]
	v_mfma_f32_16x16x32_bf16 v[94:97], v[164:167], v[190:193], v[94:97]
	v_mfma_f32_16x16x32_bf16 v[86:89], v[156:159], v[198:201], v[86:89]
	v_mfma_f32_16x16x32_bf16 v[78:81], v[164:167], v[198:201], v[78:81]
	v_mfma_f32_16x16x32_bf16 v[114:117], v[202:205], v[168:171], v[114:117]
	v_mfma_f32_16x16x32_bf16 v[106:109], v[210:213], v[168:171], v[106:109]
	v_mfma_f32_16x16x32_bf16 v[98:101], v[202:205], v[176:179], v[98:101]
	v_mfma_f32_16x16x32_bf16 v[90:93], v[210:213], v[176:179], v[90:93]
	v_mfma_f32_16x16x32_bf16 v[82:85], v[202:205], v[186:189], v[82:85]
	v_mfma_f32_16x16x32_bf16 v[74:77], v[210:213], v[186:189], v[74:77]
	v_mfma_f32_16x16x32_bf16 v[70:73], v[202:205], v[194:197], v[70:73]
	v_mfma_f32_16x16x32_bf16 v[66:69], v[210:213], v[194:197], v[66:69]
	v_mfma_f32_16x16x32_bf16 v[114:117], v[206:209], v[172:175], v[114:117]
	v_mfma_f32_16x16x32_bf16 v[106:109], v[214:217], v[172:175], v[106:109]
	v_mfma_f32_16x16x32_bf16 v[98:101], v[206:209], v[180:183], v[98:101]
	v_mfma_f32_16x16x32_bf16 v[90:93], v[214:217], v[180:183], v[90:93]
	v_mfma_f32_16x16x32_bf16 v[82:85], v[206:209], v[190:193], v[82:85]
	v_mfma_f32_16x16x32_bf16 v[74:77], v[214:217], v[190:193], v[74:77]
	v_mfma_f32_16x16x32_bf16 v[70:73], v[206:209], v[198:201], v[70:73]
	v_mfma_f32_16x16x32_bf16 v[66:69], v[214:217], v[198:201], v[66:69]
	s_setprio 0
	s_barrier
	s_add_i32 s68, s45, s29
	v_lshl_add_u64 v[218:219], s[24:25], 0, v[134:135]
	s_mov_b32 m0, s68
	global_load_lds_dwordx4 v[218:219], off
	v_lshl_add_u64 v[220:221], s[24:25], 0, v[130:131]
	s_add_i32 m0, s68, 0x2000
	s_nop 0
	global_load_lds_dwordx4 v[220:221], off
	s_mov_b32 m0, s21
	v_lshl_add_u64 v[222:223], s[26:27], 0, v[136:137]
	ds_read_b128 v[168:171], v153 offset:16384
	ds_read_b128 v[172:175], v153 offset:17408
	ds_read_b128 v[176:179], v153 offset:18432
	ds_read_b128 v[180:183], v153 offset:19456
	ds_read_b128 v[186:189], v153 offset:20480
	ds_read_b128 v[190:193], v153 offset:21504
	ds_read_b128 v[194:197], v153 offset:22528
	ds_read_b128 v[198:201], v153 offset:23552
	global_load_lds_dwordx4 v[222:223], off
	v_lshl_add_u64 v[224:225], s[26:27], 0, v[132:133]
	s_mov_b32 m0, s34
	s_nop 0
	global_load_lds_dwordx4 v[224:225], off
	s_waitcnt vmcnt(6)
	s_waitcnt lgkmcnt(0)
	s_barrier
	s_setprio 1
	v_mfma_f32_16x16x32_bf16 v[62:65], v[146:149], v[168:171], v[62:65]
	v_mfma_f32_16x16x32_bf16 v[58:61], v[160:163], v[168:171], v[58:61]
	v_mfma_f32_16x16x32_bf16 v[54:57], v[146:149], v[176:179], v[54:57]
	v_mfma_f32_16x16x32_bf16 v[46:49], v[160:163], v[176:179], v[46:49]
	v_mfma_f32_16x16x32_bf16 v[38:41], v[146:149], v[186:189], v[38:41]
	v_mfma_f32_16x16x32_bf16 v[30:33], v[160:163], v[186:189], v[30:33]
	v_mfma_f32_16x16x32_bf16 v[22:25], v[146:149], v[194:197], v[22:25]
	v_mfma_f32_16x16x32_bf16 v[14:17], v[160:163], v[194:197], v[14:17]
	v_mfma_f32_16x16x32_bf16 v[62:65], v[156:159], v[172:175], v[62:65]
	v_mfma_f32_16x16x32_bf16 v[58:61], v[164:167], v[172:175], v[58:61]
	v_mfma_f32_16x16x32_bf16 v[54:57], v[156:159], v[180:183], v[54:57]
	v_mfma_f32_16x16x32_bf16 v[46:49], v[164:167], v[180:183], v[46:49]
	v_mfma_f32_16x16x32_bf16 v[38:41], v[156:159], v[190:193], v[38:41]
	v_mfma_f32_16x16x32_bf16 v[30:33], v[164:167], v[190:193], v[30:33]
	v_mfma_f32_16x16x32_bf16 v[22:25], v[156:159], v[198:201], v[22:25]
	v_mfma_f32_16x16x32_bf16 v[14:17], v[164:167], v[198:201], v[14:17]
	v_mfma_f32_16x16x32_bf16 v[50:53], v[202:205], v[168:171], v[50:53]
	v_mfma_f32_16x16x32_bf16 v[42:45], v[210:213], v[168:171], v[42:45]
	v_mfma_f32_16x16x32_bf16 v[34:37], v[202:205], v[176:179], v[34:37]
	v_mfma_f32_16x16x32_bf16 v[26:29], v[210:213], v[176:179], v[26:29]
	v_mfma_f32_16x16x32_bf16 v[18:21], v[202:205], v[186:189], v[18:21]
	v_mfma_f32_16x16x32_bf16 v[10:13], v[210:213], v[186:189], v[10:13]
	v_mfma_f32_16x16x32_bf16 v[6:9], v[202:205], v[194:197], v[6:9]
	v_mfma_f32_16x16x32_bf16 v[2:5], v[210:213], v[194:197], v[2:5]
	v_mfma_f32_16x16x32_bf16 v[50:53], v[206:209], v[172:175], v[50:53]
	v_mfma_f32_16x16x32_bf16 v[42:45], v[214:217], v[172:175], v[42:45]
	v_mfma_f32_16x16x32_bf16 v[34:37], v[206:209], v[180:183], v[34:37]
	v_mfma_f32_16x16x32_bf16 v[26:29], v[214:217], v[180:183], v[26:29]
	v_mfma_f32_16x16x32_bf16 v[18:21], v[206:209], v[190:193], v[18:21]
	v_mfma_f32_16x16x32_bf16 v[10:13], v[214:217], v[190:193], v[10:13]
	v_mfma_f32_16x16x32_bf16 v[6:9], v[206:209], v[198:201], v[6:9]
	v_mfma_f32_16x16x32_bf16 v[2:5], v[214:217], v[198:201], v[2:5]
	s_setprio 0
	s_barrier
	s_add_u32 s68, s24, 0x80000
	s_addc_u32 s69, s25, 0
	s_add_i32 s70, s46, s29
	v_lshl_add_u64 v[146:147], s[68:69], 0, v[134:135]
	s_mov_b32 m0, s70
	s_nop 0
	global_load_lds_dwordx4 v[146:147], off
	v_lshl_add_u64 v[146:147], s[68:69], 0, v[130:131]
	s_add_i32 m0, s70, 0x2000
	s_nop 0
	global_load_lds_dwordx4 v[146:147], off
	s_add_i32 s68, 0, 0x18000
	v_add_u32_e32 v155, s68, v150
	ds_read_b128 v[146:149], v155
	ds_read_b128 v[156:159], v155 offset:1024
	ds_read_b128 v[160:163], v155 offset:2048
	ds_read_b128 v[164:167], v155 offset:3072
	s_add_u32 s26, s26, 0x80000
	s_addc_u32 s27, s27, 0
	s_mov_b32 m0, s35
	v_lshl_add_u64 v[202:203], s[26:27], 0, v[136:137]
	ds_read_b128 v[168:171], v153 offset:32768
	ds_read_b128 v[172:175], v153 offset:33792
	ds_read_b128 v[176:179], v153 offset:34816
	ds_read_b128 v[180:183], v153 offset:35840
	ds_read_b128 v[186:189], v153 offset:36864
	ds_read_b128 v[190:193], v153 offset:37888
	ds_read_b128 v[194:197], v153 offset:38912
	ds_read_b128 v[198:201], v153 offset:39936
	global_load_lds_dwordx4 v[202:203], off
	v_lshl_add_u64 v[202:203], s[26:27], 0, v[132:133]
	s_mov_b32 m0, s36
	s_nop 0
	global_load_lds_dwordx4 v[202:203], off
	v_add_u32_e32 v214, 0x1c000, v150
	ds_read_b128 v[202:205], v214
	ds_read_b128 v[206:209], v214 offset:1024
	ds_read_b128 v[210:213], v214 offset:2048
	ds_read_b128 v[214:217], v214 offset:3072
	s_waitcnt vmcnt(8)
	s_waitcnt lgkmcnt(0)
	s_barrier
	s_setprio 1
	v_mfma_f32_16x16x32_bf16 v[126:129], v[146:149], v[168:171], v[126:129]
	v_mfma_f32_16x16x32_bf16 v[122:125], v[160:163], v[168:171], v[122:125]
	v_mfma_f32_16x16x32_bf16 v[118:121], v[146:149], v[176:179], v[118:121]
	v_mfma_f32_16x16x32_bf16 v[110:113], v[160:163], v[176:179], v[110:113]
	v_mfma_f32_16x16x32_bf16 v[102:105], v[146:149], v[186:189], v[102:105]
	v_mfma_f32_16x16x32_bf16 v[94:97], v[160:163], v[186:189], v[94:97]
	v_mfma_f32_16x16x32_bf16 v[86:89], v[146:149], v[194:197], v[86:89]
	v_mfma_f32_16x16x32_bf16 v[78:81], v[160:163], v[194:197], v[78:81]
	v_mfma_f32_16x16x32_bf16 v[126:129], v[156:159], v[172:175], v[126:129]
	v_mfma_f32_16x16x32_bf16 v[122:125], v[164:167], v[172:175], v[122:125]
	v_mfma_f32_16x16x32_bf16 v[118:121], v[156:159], v[180:183], v[118:121]
	v_mfma_f32_16x16x32_bf16 v[110:113], v[164:167], v[180:183], v[110:113]
	v_mfma_f32_16x16x32_bf16 v[102:105], v[156:159], v[190:193], v[102:105]
	v_mfma_f32_16x16x32_bf16 v[94:97], v[164:167], v[190:193], v[94:97]
	v_mfma_f32_16x16x32_bf16 v[86:89], v[156:159], v[198:201], v[86:89]
	v_mfma_f32_16x16x32_bf16 v[78:81], v[164:167], v[198:201], v[78:81]
	v_mfma_f32_16x16x32_bf16 v[114:117], v[202:205], v[168:171], v[114:117]
	v_mfma_f32_16x16x32_bf16 v[106:109], v[210:213], v[168:171], v[106:109]
	v_mfma_f32_16x16x32_bf16 v[98:101], v[202:205], v[176:179], v[98:101]
	v_mfma_f32_16x16x32_bf16 v[90:93], v[210:213], v[176:179], v[90:93]
	v_mfma_f32_16x16x32_bf16 v[82:85], v[202:205], v[186:189], v[82:85]
	v_mfma_f32_16x16x32_bf16 v[74:77], v[210:213], v[186:189], v[74:77]
	v_mfma_f32_16x16x32_bf16 v[70:73], v[202:205], v[194:197], v[70:73]
	v_mfma_f32_16x16x32_bf16 v[66:69], v[210:213], v[194:197], v[66:69]
	v_mfma_f32_16x16x32_bf16 v[114:117], v[206:209], v[172:175], v[114:117]
	v_mfma_f32_16x16x32_bf16 v[106:109], v[214:217], v[172:175], v[106:109]
	v_mfma_f32_16x16x32_bf16 v[98:101], v[206:209], v[180:183], v[98:101]
	v_mfma_f32_16x16x32_bf16 v[90:93], v[214:217], v[180:183], v[90:93]
	v_mfma_f32_16x16x32_bf16 v[82:85], v[206:209], v[190:193], v[82:85]
	v_mfma_f32_16x16x32_bf16 v[74:77], v[214:217], v[190:193], v[74:77]
	v_mfma_f32_16x16x32_bf16 v[70:73], v[206:209], v[198:201], v[70:73]
	v_mfma_f32_16x16x32_bf16 v[66:69], v[214:217], v[198:201], v[66:69]
	s_setprio 0
	s_barrier
	s_add_i32 s26, 0, 0x1c000
	s_add_i32 s27, s68, s29
	v_lshl_add_u64 v[218:219], v[218:219], 0, s[4:5]
	s_mov_b32 m0, s27
	global_load_lds_dwordx4 v[218:219], off
	v_lshl_add_u64 v[218:219], v[220:221], 0, s[4:5]
	s_add_i32 m0, s27, 0x2000
	s_nop 0
	global_load_lds_dwordx4 v[218:219], off
	s_mov_b32 m0, s41
	v_lshl_add_u64 v[218:219], v[222:223], 0, s[4:5]
	ds_read_b128 v[168:171], v153 offset:49152
	ds_read_b128 v[172:175], v153 offset:50176
	ds_read_b128 v[176:179], v153 offset:51200
	ds_read_b128 v[180:183], v153 offset:52224
	ds_read_b128 v[186:189], v153 offset:53248
	ds_read_b128 v[190:193], v153 offset:54272
	ds_read_b128 v[194:197], v153 offset:55296
	ds_read_b128 v[198:201], v153 offset:56320
	global_load_lds_dwordx4 v[218:219], off
	v_lshl_add_u64 v[218:219], v[224:225], 0, s[4:5]
	s_mov_b32 m0, s42
	s_nop 0
	global_load_lds_dwordx4 v[218:219], off
	s_add_u32 s24, s24, 0x80080
	s_addc_u32 s25, s25, 0
	s_add_i32 s26, s26, s29
	v_lshl_add_u64 v[218:219], s[24:25], 0, v[134:135]
	s_mov_b32 m0, s26
	s_nop 0
	global_load_lds_dwordx4 v[218:219], off
	v_lshl_add_u64 v[218:219], s[24:25], 0, v[130:131]
	s_add_i32 m0, s26, 0x2000
	s_nop 0
	global_load_lds_dwordx4 v[218:219], off
	s_waitcnt vmcnt(8)
	s_waitcnt lgkmcnt(0)
	s_barrier
	s_setprio 1
	v_mfma_f32_16x16x32_bf16 v[62:65], v[146:149], v[168:171], v[62:65]
	v_mfma_f32_16x16x32_bf16 v[58:61], v[160:163], v[168:171], v[58:61]
	v_mfma_f32_16x16x32_bf16 v[54:57], v[146:149], v[176:179], v[54:57]
	v_mfma_f32_16x16x32_bf16 v[46:49], v[160:163], v[176:179], v[46:49]
	v_mfma_f32_16x16x32_bf16 v[38:41], v[146:149], v[186:189], v[38:41]
	v_mfma_f32_16x16x32_bf16 v[30:33], v[160:163], v[186:189], v[30:33]
	v_mfma_f32_16x16x32_bf16 v[22:25], v[146:149], v[194:197], v[22:25]
	v_mfma_f32_16x16x32_bf16 v[14:17], v[160:163], v[194:197], v[14:17]
	v_mfma_f32_16x16x32_bf16 v[62:65], v[156:159], v[172:175], v[62:65]
	v_mfma_f32_16x16x32_bf16 v[58:61], v[164:167], v[172:175], v[58:61]
	v_mfma_f32_16x16x32_bf16 v[54:57], v[156:159], v[180:183], v[54:57]
	v_mfma_f32_16x16x32_bf16 v[46:49], v[164:167], v[180:183], v[46:49]
	v_mfma_f32_16x16x32_bf16 v[38:41], v[156:159], v[190:193], v[38:41]
	v_mfma_f32_16x16x32_bf16 v[30:33], v[164:167], v[190:193], v[30:33]
	v_mfma_f32_16x16x32_bf16 v[22:25], v[156:159], v[198:201], v[22:25]
	v_mfma_f32_16x16x32_bf16 v[14:17], v[164:167], v[198:201], v[14:17]
	v_mfma_f32_16x16x32_bf16 v[50:53], v[202:205], v[168:171], v[50:53]
	v_mfma_f32_16x16x32_bf16 v[42:45], v[210:213], v[168:171], v[42:45]
	v_mfma_f32_16x16x32_bf16 v[34:37], v[202:205], v[176:179], v[34:37]
	v_mfma_f32_16x16x32_bf16 v[26:29], v[210:213], v[176:179], v[26:29]
	v_mfma_f32_16x16x32_bf16 v[18:21], v[202:205], v[186:189], v[18:21]
	v_mfma_f32_16x16x32_bf16 v[10:13], v[210:213], v[186:189], v[10:13]
	v_mfma_f32_16x16x32_bf16 v[6:9], v[202:205], v[194:197], v[6:9]
	v_mfma_f32_16x16x32_bf16 v[2:5], v[210:213], v[194:197], v[2:5]
	v_mfma_f32_16x16x32_bf16 v[50:53], v[206:209], v[172:175], v[50:53]
	v_mfma_f32_16x16x32_bf16 v[42:45], v[214:217], v[172:175], v[42:45]
	v_mfma_f32_16x16x32_bf16 v[34:37], v[206:209], v[180:183], v[34:37]
	v_mfma_f32_16x16x32_bf16 v[26:29], v[214:217], v[180:183], v[26:29]
	v_mfma_f32_16x16x32_bf16 v[18:21], v[206:209], v[190:193], v[18:21]
	v_mfma_f32_16x16x32_bf16 v[10:13], v[214:217], v[190:193], v[10:13]
	v_mfma_f32_16x16x32_bf16 v[6:9], v[206:209], v[198:201], v[6:9]
	v_mfma_f32_16x16x32_bf16 v[2:5], v[214:217], v[198:201], v[2:5]
	s_setprio 0
	s_add_i32 s61, s61, 2
	s_add_u32 s22, s22, 0x100
	s_addc_u32 s23, s23, 0
	s_add_u32 s59, s59, 0x100
	s_addc_u32 s60, s60, 0
	s_cmp_gt_u32 s61, 29
	s_barrier
	s_cbranch_scc0 .LBB0_269
	v_lshl_or_b32 v148, s52, 8, v151
	v_lshl_add_u32 v155, s20, 8, v1
	v_ashrrev_i32_e32 v149, 31, v148
	v_mov_b64_e32 v[146:147], s[54:55]
	v_mad_i64_i32 v[156:157], s[22:23], v155, s47, v[146:147]
	v_lshlrev_b64 v[148:149], 1, v[148:149]
	v_lshl_add_u64 v[156:157], v[156:157], 0, v[148:149]
	v_cvt_pk_bf16_f32 v126, v126, v127
	v_cvt_pk_bf16_f32 v127, v128, v129
	v_cvt_pk_bf16_f32 v128, v122, v123
	v_cvt_pk_bf16_f32 v129, v124, v125
	global_store_dwordx4 v[156:157], v[126:129], off sc1
	v_cvt_pk_bf16_f32 v114, v114, v115
	v_cvt_pk_bf16_f32 v115, v116, v117
	v_cvt_pk_bf16_f32 v116, v106, v107
	v_or_b32_e32 v106, 16, v155
	v_mad_i64_i32 v[106:107], s[22:23], v106, s47, v[146:147]
	v_cvt_pk_bf16_f32 v117, v108, v109
	global_store_dwordx4 v[156:157], v[114:117], off offset:256 sc1
	s_and_b64 vcc, exec, s[2:3]
	s_mov_b32 s52, s6
	v_lshl_add_u64 v[114:115], v[106:107], 0, v[148:149]
	v_cvt_pk_bf16_f32 v106, v118, v119
	v_cvt_pk_bf16_f32 v107, v120, v121
	v_cvt_pk_bf16_f32 v108, v110, v111
	v_cvt_pk_bf16_f32 v109, v112, v113
	global_store_dwordx4 v[114:115], v[106:109], off sc1
	v_cvt_pk_bf16_f32 v98, v98, v99
	v_cvt_pk_bf16_f32 v99, v100, v101
	v_cvt_pk_bf16_f32 v100, v90, v91
	v_or_b32_e32 v90, 32, v155
	v_mad_i64_i32 v[90:91], s[22:23], v90, s47, v[146:147]
	v_cvt_pk_bf16_f32 v101, v92, v93
	global_store_dwordx4 v[114:115], v[98:101], off offset:256 sc1
	s_mov_b32 s20, s8
	s_mov_b64 s[24:25], s[18:19]
	v_lshl_add_u64 v[98:99], v[90:91], 0, v[148:149]
	v_cvt_pk_bf16_f32 v90, v102, v103
	v_cvt_pk_bf16_f32 v91, v104, v105
	v_cvt_pk_bf16_f32 v92, v94, v95
	v_cvt_pk_bf16_f32 v93, v96, v97
	global_store_dwordx4 v[98:99], v[90:93], off sc1
	v_cvt_pk_bf16_f32 v82, v82, v83
	v_cvt_pk_bf16_f32 v83, v84, v85
	v_cvt_pk_bf16_f32 v84, v74, v75
	v_or_b32_e32 v74, 48, v155
	v_mad_i64_i32 v[74:75], s[22:23], v74, s47, v[146:147]
	v_cvt_pk_bf16_f32 v85, v76, v77
	global_store_dwordx4 v[98:99], v[82:85], off offset:256 sc1
	s_nop 1
	v_lshl_add_u64 v[82:83], v[74:75], 0, v[148:149]
	v_cvt_pk_bf16_f32 v74, v86, v87
	v_cvt_pk_bf16_f32 v75, v88, v89
	v_cvt_pk_bf16_f32 v76, v78, v79
	v_cvt_pk_bf16_f32 v77, v80, v81
	global_store_dwordx4 v[82:83], v[74:77], off sc1
	v_cvt_pk_bf16_f32 v70, v70, v71
	v_cvt_pk_bf16_f32 v71, v72, v73
	v_cvt_pk_bf16_f32 v72, v66, v67
	v_add_u32_e32 v66, 0x80, v155
	v_mad_i64_i32 v[66:67], s[22:23], v66, s47, v[146:147]
	v_lshl_add_u64 v[66:67], v[66:67], 0, v[148:149]
	v_cvt_pk_bf16_f32 v73, v68, v69
	global_store_dwordx4 v[82:83], v[70:73], off offset:256 sc1
	v_cvt_pk_bf16_f32 v62, v62, v63
	v_cvt_pk_bf16_f32 v63, v64, v65
	v_cvt_pk_bf16_f32 v64, v58, v59
	v_cvt_pk_bf16_f32 v65, v60, v61
	global_store_dwordx4 v[66:67], v[62:65], off sc1
	v_cvt_pk_bf16_f32 v50, v50, v51
	v_cvt_pk_bf16_f32 v51, v52, v53
	v_cvt_pk_bf16_f32 v52, v42, v43
	v_add_u32_e32 v42, 0x90, v155
	v_mad_i64_i32 v[42:43], s[22:23], v42, s47, v[146:147]
	v_cvt_pk_bf16_f32 v53, v44, v45
	global_store_dwordx4 v[66:67], v[50:53], off offset:256 sc1
	s_nop 1
	v_lshl_add_u64 v[50:51], v[42:43], 0, v[148:149]
	v_cvt_pk_bf16_f32 v42, v54, v55
	v_cvt_pk_bf16_f32 v43, v56, v57
	v_cvt_pk_bf16_f32 v44, v46, v47
	v_cvt_pk_bf16_f32 v45, v48, v49
	global_store_dwordx4 v[50:51], v[42:45], off sc1
	v_cvt_pk_bf16_f32 v34, v34, v35
	v_cvt_pk_bf16_f32 v35, v36, v37
	v_cvt_pk_bf16_f32 v36, v26, v27
	v_add_u32_e32 v26, 0xa0, v155
	v_mad_i64_i32 v[26:27], s[22:23], v26, s47, v[146:147]
	v_cvt_pk_bf16_f32 v37, v28, v29
	global_store_dwordx4 v[50:51], v[34:37], off offset:256 sc1
	s_nop 1
	v_lshl_add_u64 v[34:35], v[26:27], 0, v[148:149]
	v_cvt_pk_bf16_f32 v26, v38, v39
	v_cvt_pk_bf16_f32 v27, v40, v41
	v_cvt_pk_bf16_f32 v28, v30, v31
	v_cvt_pk_bf16_f32 v29, v32, v33
	global_store_dwordx4 v[34:35], v[26:29], off sc1
	v_cvt_pk_bf16_f32 v18, v18, v19
	v_cvt_pk_bf16_f32 v19, v20, v21
	v_cvt_pk_bf16_f32 v20, v10, v11
	v_add_u32_e32 v10, 0xb0, v155
	v_mad_i64_i32 v[10:11], s[22:23], v10, s47, v[146:147]
	v_cvt_pk_bf16_f32 v21, v12, v13
	global_store_dwordx4 v[34:35], v[18:21], off offset:256 sc1
	s_mov_b64 s[22:23], s[16:17]
	s_nop 0
	v_lshl_add_u64 v[18:19], v[10:11], 0, v[148:149]
	v_cvt_pk_bf16_f32 v10, v22, v23
	v_cvt_pk_bf16_f32 v11, v24, v25
	v_cvt_pk_bf16_f32 v12, v14, v15
	v_cvt_pk_bf16_f32 v13, v16, v17
	global_store_dwordx4 v[18:19], v[10:13], off sc1
	v_cvt_pk_bf16_f32 v6, v6, v7
	v_cvt_pk_bf16_f32 v7, v8, v9
	v_cvt_pk_bf16_f32 v8, v2, v3
	v_cvt_pk_bf16_f32 v9, v4, v5
	global_store_dwordx4 v[18:19], v[6:9], off offset:256 sc1
	s_cbranch_vccz .LBB0_266
	s_waitcnt vmcnt(0)
	s_cmpk_gt_u32 s28, 0xff
	s_cbranch_scc1 .LBB0_273
	s_barrier

.LBB0_345:
	s_or_b64 exec, exec, s[0:1]
	v_and_b32_e32 v56, 0xffff0000, v10
	v_lshlrev_b32_e32 v20, 16, v10
	v_mul_f32_e32 v58, v56, v56
	v_lshlrev_b32_e32 v60, 16, v11
	v_fmac_f32_e32 v58, v20, v20
	v_and_b32_e32 v61, 0xffff0000, v11
	v_fmac_f32_e32 v58, v60, v60
	v_and_b32_e32 v16, 0xffff0000, v12
	v_lshlrev_b32_e32 v17, 16, v12
	v_fmac_f32_e32 v58, v61, v61
	v_pk_mul_f32 v[48:49], v[16:17], v[16:17]
	s_nop 0
	v_add_f32_e32 v49, v49, v58
	v_add_f32_e32 v62, v48, v49
	v_and_b32_e32 v48, 0xffff0000, v13
	v_lshlrev_b32_e32 v49, 16, v13
	v_pk_mul_f32 v[58:59], v[48:49], v[48:49]
	s_nop 0
	v_add_f32_e32 v59, v59, v62
	v_add_f32_e32 v58, v58, v59
	ds_bpermute_b32 v40, v40, v58
	s_waitcnt lgkmcnt(0)
	v_add_f32_e32 v40, v58, v40
	ds_bpermute_b32 v44, v44, v40
	s_waitcnt lgkmcnt(0)
	v_add_f32_e32 v40, v40, v44
	ds_bpermute_b32 v44, v47, v40
	s_waitcnt lgkmcnt(0)
	v_add_f32_e32 v40, v40, v44
	ds_bpermute_b32 v44, v50, v40
	s_waitcnt lgkmcnt(0)
	v_add_f32_e32 v40, v40, v44
	ds_bpermute_b32 v44, v51, v40
	s_waitcnt lgkmcnt(0)
	v_add_f32_e32 v40, v40, v44
	ds_bpermute_b32 v44, v57, v40
	s_waitcnt lgkmcnt(0)
	v_add_f32_e32 v40, v40, v44
	v_fmamk_f32 v40, v40, 0x3b000000, v27
	v_mul_f32_e32 v44, 0x4b800000, v40
	v_cmp_gt_f32_e32 vcc, s50, v40
	s_nop 1
	v_cndmask_b32_e32 v40, v40, v44, vcc
	v_rsq_f32_e32 v40, v40
	s_nop 0
	v_mul_f32_e32 v44, 0x45800000, v40
	v_cndmask_b32_e32 v40, v40, v44, vcc
	v_mul_f32_e32 v47, v40, v60
	v_mul_f32_e32 v20, v40, v20
	v_mul_f32_e32 v44, v40, v56
	v_mul_f32_e32 v50, v40, v61
	v_mul_f32_e32 v49, v40, v49
	v_mul_f32_e32 v47, v4, v47
	v_mul_f32_e32 v17, v40, v17
	v_mul_f32_e32 v16, v40, v16
	v_mul_f32_e32 v40, v40, v48
	v_mul_f32_e32 v20, v2, v20
	v_mul_f32_e32 v44, v3, v44
	v_mul_f32_e32 v50, v5, v50
	v_mul_f32_e32 v51, v8, v49
	v_cvt_pk_bf16_f32 v48, v20, v44
	v_cvt_pk_bf16_f32 v49, v47, v50
	v_mov_b32_e32 v47, v21
	v_lshl_add_u64 v[14:15], v[14:15], 0, v[46:47]
	v_add_co_u32_e32 v14, vcc, 0x1000, v14
	v_mul_f32_e32 v17, v6, v17
	s_nop 0
	v_addc_co_u32_e32 v15, vcc, 0, v15, vcc
	v_mul_f32_e32 v16, v7, v16
	v_mul_f32_e32 v40, v9, v40
	v_cvt_pk_bf16_f32 v50, v17, v16
	v_cvt_pk_bf16_f32 v51, v51, v40
	global_store_dwordx4 v[14:15], v[48:51], off offset:2048 sc1

.LBB0_359:
	s_or_b64 exec, exec, s[0:1]
	v_and_b32_e32 v62, 0xffff0000, v14
	v_lshlrev_b32_e32 v49, 16, v14
	v_mul_f32_e32 v40, v62, v62
	v_lshlrev_b32_e32 v63, 16, v15
	v_fmac_f32_e32 v40, v49, v49
	v_and_b32_e32 v64, 0xffff0000, v15
	v_fmac_f32_e32 v40, v63, v63
	v_and_b32_e32 v58, 0xffff0000, v16
	v_lshlrev_b32_e32 v59, 16, v16
	v_fmac_f32_e32 v40, v64, v64
	v_pk_mul_f32 v[14:15], v[58:59], v[58:59]
	v_and_b32_e32 v60, 0xffff0000, v17
	v_add_f32_e32 v15, v15, v40
	v_lshlrev_b32_e32 v61, 16, v17
	v_add_f32_e32 v16, v14, v15
	v_pk_mul_f32 v[14:15], v[60:61], v[60:61]
	s_nop 0
	v_add_f32_e32 v15, v15, v16
	v_add_f32_e32 v14, v14, v15
	v_and_b32_e32 v15, 64, v55
	v_add_u32_e32 v15, 64, v15
	v_xor_b32_e32 v16, 32, v55
	v_cmp_lt_i32_e32 vcc, v16, v15
	s_nop 1
	v_cndmask_b32_e32 v16, v55, v16, vcc
	v_lshlrev_b32_e32 v40, 2, v16
	ds_bpermute_b32 v16, v40, v14
	s_waitcnt lgkmcnt(0)
	v_add_f32_e32 v14, v14, v16
	v_xor_b32_e32 v16, 16, v55
	v_cmp_lt_i32_e32 vcc, v16, v15
	s_nop 1
	v_cndmask_b32_e32 v16, v55, v16, vcc
	v_lshlrev_b32_e32 v44, 2, v16
	ds_bpermute_b32 v16, v44, v14
	s_waitcnt lgkmcnt(0)
	v_add_f32_e32 v14, v14, v16
	v_xor_b32_e32 v16, 8, v55
	v_cmp_lt_i32_e32 vcc, v16, v15
	s_nop 1
	v_cndmask_b32_e32 v16, v55, v16, vcc
	v_lshlrev_b32_e32 v47, 2, v16
	ds_bpermute_b32 v16, v47, v14
	s_waitcnt lgkmcnt(0)
	v_add_f32_e32 v14, v14, v16
	v_xor_b32_e32 v16, 4, v55
	v_cmp_lt_i32_e32 vcc, v16, v15
	s_nop 1
	v_cndmask_b32_e32 v16, v55, v16, vcc
	v_lshlrev_b32_e32 v50, 2, v16
	ds_bpermute_b32 v16, v50, v14
	s_waitcnt lgkmcnt(0)
	v_add_f32_e32 v14, v14, v16
	v_xor_b32_e32 v16, 2, v55
	v_cmp_lt_i32_e32 vcc, v16, v15
	s_nop 1
	v_cndmask_b32_e32 v16, v55, v16, vcc
	v_lshlrev_b32_e32 v51, 2, v16
	ds_bpermute_b32 v16, v51, v14
	s_waitcnt lgkmcnt(0)
	v_add_f32_e32 v14, v14, v16
	v_xor_b32_e32 v16, 1, v55
	v_cmp_lt_i32_e32 vcc, v16, v15
	s_nop 1
	v_cndmask_b32_e32 v15, v55, v16, vcc
	v_lshlrev_b32_e32 v57, 2, v15
	ds_bpermute_b32 v15, v57, v14
	s_waitcnt lgkmcnt(0)
	v_add_f32_e32 v14, v14, v15
	v_fmamk_f32 v14, v14, 0x3b000000, v27
	v_mul_f32_e32 v15, 0x4b800000, v14
	v_cmp_gt_f32_e32 vcc, s50, v14
	s_nop 1
	v_cndmask_b32_e32 v14, v14, v15, vcc
	v_rsq_f32_e32 v14, v14
	s_nop 0
	v_mul_f32_e32 v15, 0x45800000, v14
	v_cndmask_b32_e32 v17, v14, v15, vcc
	v_mul_f32_e32 v14, v17, v49
	v_mul_f32_e32 v15, v17, v62
	v_mul_f32_e32 v14, v2, v14
	v_mul_f32_e32 v15, v3, v15
	v_cvt_pk_bf16_f32 v14, v14, v15
	v_mul_f32_e32 v15, v17, v63
	v_mul_f32_e32 v16, v17, v64
	v_mul_f32_e32 v15, v4, v15
	v_mul_f32_e32 v16, v5, v16
	v_cvt_pk_bf16_f32 v15, v15, v16
	v_mul_f32_e32 v16, v17, v59
	v_mul_f32_e32 v49, v17, v58
	v_mul_f32_e32 v16, v6, v16
	v_mul_f32_e32 v49, v7, v49
	v_cvt_pk_bf16_f32 v16, v16, v49
	v_mul_f32_e32 v49, v17, v61
	v_mul_f32_e32 v17, v17, v60
	v_mul_f32_e32 v17, v9, v17
	v_mul_f32_e32 v49, v8, v49
	v_cvt_pk_bf16_f32 v17, v49, v17
	global_store_dwordx4 v[28:29], v[14:17], off sc1
	s_and_saveexec_b64 s[8:9], s[4:5]
	s_cbranch_execz .LBB0_346
	v_and_b32_e32 v14, 0x7ff, v56
	v_add_u32_e32 v15, 0xffffc000, v56
	v_cmp_gt_i32_e32 vcc, s46, v56
	s_nop 1
	v_cndmask_b32_e32 v14, v15, v14, vcc
	v_cvt_f64_i32_e32 v[14:15], v14
	v_mul_f64 v[14:15], v[22:23], v[14:15]
	v_mul_f64 v[16:17], v[14:15], s[28:29]
	v_rndne_f64_e32 v[16:17], v[16:17]
	v_fmac_f64_e32 v[14:15], s[30:31], v[16:17]
	v_cvt_f32_f64_e32 v14, v[14:15]
	v_and_b32_e32 v15, 0x7fffffff, v14
	v_lshrrev_b32_e32 v16, 23, v15
	v_and_b32_e32 v17, 0x7fffff, v15
	v_cmp_nlt_f32_e64 s[34:35], |v14|, s47
	v_add_u32_e32 v58, 0xffffff88, v16
	v_or_b32_e32 v16, 0x800000, v17
	s_and_saveexec_b64 s[0:1], s[34:35]
	s_xor_b64 s[36:37], exec, s[0:1]
	s_cbranch_execz .LBB0_362
	v_mad_u64_u32 v[60:61], s[6:7], v16, s51, 0
	v_mov_b32_e32 v62, v61
	v_mov_b32_e32 v63, v21
	v_mad_u64_u32 v[62:63], s[6:7], v16, s52, v[62:63]
	v_mov_b32_e32 v64, v63
	v_mov_b32_e32 v65, v21
	v_mad_u64_u32 v[64:65], s[6:7], v16, s53, v[64:65]
	v_cmp_lt_u32_e32 vcc, 63, v58
	v_mov_b32_e32 v66, v65
	v_mov_b32_e32 v67, v21
	v_cndmask_b32_e32 v17, 0, v52, vcc
	v_mad_u64_u32 v[66:67], s[6:7], v16, s58, v[66:67]
	v_add_u32_e32 v17, v17, v58
	v_mov_b32_e32 v68, v67
	v_mov_b32_e32 v69, v21
	v_cmp_lt_u32_e64 s[0:1], 31, v17
	v_mad_u64_u32 v[68:69], s[6:7], v16, s59, v[68:69]
	s_nop 0
	v_cndmask_b32_e64 v49, 0, v53, s[0:1]
	v_mov_b32_e32 v70, v69
	v_mov_b32_e32 v71, v21
	v_add_u32_e32 v17, v49, v17
	v_mad_u64_u32 v[70:71], s[6:7], v16, s60, v[70:71]
	v_cmp_lt_u32_e64 s[4:5], 31, v17
	v_mov_b32_e32 v72, v71
	v_mov_b32_e32 v73, v21
	v_cndmask_b32_e64 v49, 0, v53, s[4:5]
	v_mad_u64_u32 v[72:73], s[6:7], v16, s61, v[72:73]
	v_add_u32_e32 v17, v49, v17
	v_cndmask_b32_e32 v49, v70, v66, vcc
	v_cndmask_b32_e32 v59, v72, v68, vcc
	v_cndmask_b32_e32 v63, v73, v70, vcc
	v_cndmask_b32_e64 v61, v59, v49, s[0:1]
	v_cndmask_b32_e64 v59, v63, v59, s[0:1]
	v_cndmask_b32_e32 v63, v68, v64, vcc
	v_cndmask_b32_e64 v49, v49, v63, s[0:1]
	v_cndmask_b32_e64 v59, v59, v61, s[4:5]
	v_cndmask_b32_e64 v61, v61, v49, s[4:5]
	v_sub_u32_e32 v65, 32, v17
	v_alignbit_b32 v67, v59, v61, v65
	v_cmp_eq_u32_e64 s[6:7], 0, v17
	v_cndmask_b32_e32 v60, v64, v60, vcc
	s_nop 0
	v_cndmask_b32_e64 v17, v67, v59, s[6:7]
	v_cndmask_b32_e32 v59, v66, v62, vcc
	v_cndmask_b32_e64 v62, v63, v59, s[0:1]
	v_cndmask_b32_e64 v49, v49, v62, s[4:5]
	v_alignbit_b32 v63, v61, v49, v65
	v_cndmask_b32_e64 v59, v59, v60, s[0:1]
	v_cndmask_b32_e64 v61, v63, v61, s[6:7]
	v_bfe_u32 v67, v17, 29, 1
	v_cndmask_b32_e64 v59, v62, v59, s[4:5]
	v_alignbit_b32 v63, v17, v61, 30
	v_sub_u32_e32 v68, 0, v67
	v_alignbit_b32 v60, v49, v59, v65
	v_xor_b32_e32 v63, v63, v68
	v_cndmask_b32_e64 v49, v60, v49, s[6:7]
	v_alignbit_b32 v60, v61, v49, 30
	v_ffbh_u32_e32 v61, v63
	v_min_u32_e32 v61, 32, v61
	v_alignbit_b32 v49, v49, v59, 30
	v_xor_b32_e32 v60, v60, v68
	v_sub_u32_e32 v62, 31, v61
	v_xor_b32_e32 v49, v49, v68
	v_alignbit_b32 v63, v63, v60, v62
	v_alignbit_b32 v49, v60, v49, v62
	v_alignbit_b32 v59, v63, v49, 9
	v_ffbh_u32_e32 v60, v59
	v_min_u32_e32 v60, 32, v60
	v_lshrrev_b32_e32 v66, 29, v17
	v_not_b32_e32 v62, v60
	v_alignbit_b32 v49, v59, v49, v62
	v_lshlrev_b32_e32 v59, 31, v66
	v_or_b32_e32 v62, 0x33000000, v59
	v_add_lshl_u32 v60, v60, v61, 23
	v_lshrrev_b32_e32 v49, 9, v49
	v_sub_u32_e32 v60, v62, v60
	v_or_b32_e32 v59, 0.5, v59
	v_lshlrev_b32_e32 v61, 23, v61
	v_or_b32_e32 v49, v60, v49
	v_lshrrev_b32_e32 v60, 9, v63
	v_sub_u32_e32 v59, v59, v61
	v_or_b32_e32 v59, v60, v59
	v_mul_f32_e32 v60, 0x3fc90fda, v59
	v_fma_f32 v61, v59, s68, -v60
	v_fmac_f32_e32 v61, 0x33a22168, v59
	v_fmac_f32_e32 v61, 0x3fc90fda, v49
	v_lshrrev_b32_e32 v17, 30, v17
	v_add_f32_e32 v49, v60, v61
	v_add_u32_e32 v17, v67, v17

.LBB0_457:
	ds_read_b128 v[154:157], v150
	ds_read_b128 v[158:161], v150 offset:1024
	ds_read_b128 v[162:165], v150 offset:2048
	ds_read_b128 v[166:169], v150 offset:3072
	s_add_u32 s4, s28, 0x100
	s_addc_u32 s5, s29, 0
	s_cmp_eq_u32 s81, 4
	s_cselect_b32 s35, s25, s5
	s_cselect_b32 s34, s24, s4
	s_cselect_b32 s31, s23, s80
	s_cselect_b32 s30, s78, s79
	v_lshl_add_u64 v[146:147], s[28:29], 0, v[138:139]
	s_add_i32 m0, s46, 0xc000
	ds_read_b128 v[170:173], v151
	ds_read_b128 v[174:177], v151 offset:1024
	ds_read_b128 v[178:181], v151 offset:2048
	ds_read_b128 v[186:189], v151 offset:3072
	ds_read_b128 v[190:193], v151 offset:4096
	ds_read_b128 v[194:197], v151 offset:5120
	ds_read_b128 v[198:201], v151 offset:6144
	ds_read_b128 v[202:205], v151 offset:7168
	global_load_lds_dwordx4 v[146:147], off
	v_lshl_add_u64 v[146:147], s[28:29], 0, v[140:141]
	s_add_i32 m0, s46, 0xe000
	s_nop 0
	global_load_lds_dwordx4 v[146:147], off
	ds_read_b128 v[206:209], v152
	ds_read_b128 v[210:213], v152 offset:1024
	ds_read_b128 v[214:217], v152 offset:2048
	ds_read_b128 v[218:221], v152 offset:3072
	s_waitcnt vmcnt(8)
	s_waitcnt lgkmcnt(0)
	s_barrier
	s_setprio 1
	v_mfma_f32_16x16x32_bf16 v[126:129], v[154:157], v[170:173], v[126:129]
	v_mfma_f32_16x16x32_bf16 v[122:125], v[162:165], v[170:173], v[122:125]
	v_mfma_f32_16x16x32_bf16 v[114:117], v[154:157], v[178:181], v[114:117]
	v_mfma_f32_16x16x32_bf16 v[106:109], v[162:165], v[178:181], v[106:109]
	v_mfma_f32_16x16x32_bf16 v[98:101], v[154:157], v[190:193], v[98:101]
	v_mfma_f32_16x16x32_bf16 v[90:93], v[162:165], v[190:193], v[90:93]
	v_mfma_f32_16x16x32_bf16 v[82:85], v[154:157], v[198:201], v[82:85]
	v_mfma_f32_16x16x32_bf16 v[74:77], v[162:165], v[198:201], v[74:77]
	v_mfma_f32_16x16x32_bf16 v[126:129], v[158:161], v[174:177], v[126:129]
	v_mfma_f32_16x16x32_bf16 v[122:125], v[166:169], v[174:177], v[122:125]
	v_mfma_f32_16x16x32_bf16 v[114:117], v[158:161], v[186:189], v[114:117]
	v_mfma_f32_16x16x32_bf16 v[106:109], v[166:169], v[186:189], v[106:109]
	v_mfma_f32_16x16x32_bf16 v[98:101], v[158:161], v[194:197], v[98:101]
	v_mfma_f32_16x16x32_bf16 v[90:93], v[166:169], v[194:197], v[90:93]
	v_mfma_f32_16x16x32_bf16 v[82:85], v[158:161], v[202:205], v[82:85]
	v_mfma_f32_16x16x32_bf16 v[74:77], v[166:169], v[202:205], v[74:77]
	v_mfma_f32_16x16x32_bf16 v[118:121], v[206:209], v[170:173], v[118:121]
	v_mfma_f32_16x16x32_bf16 v[110:113], v[214:217], v[170:173], v[110:113]
	v_mfma_f32_16x16x32_bf16 v[102:105], v[206:209], v[178:181], v[102:105]
	v_mfma_f32_16x16x32_bf16 v[94:97], v[214:217], v[178:181], v[94:97]
	v_mfma_f32_16x16x32_bf16 v[86:89], v[206:209], v[190:193], v[86:89]
	v_mfma_f32_16x16x32_bf16 v[78:81], v[214:217], v[190:193], v[78:81]
	v_mfma_f32_16x16x32_bf16 v[70:73], v[206:209], v[198:201], v[70:73]
	v_mfma_f32_16x16x32_bf16 v[66:69], v[214:217], v[198:201], v[66:69]
	v_mfma_f32_16x16x32_bf16 v[118:121], v[210:213], v[174:177], v[118:121]
	v_mfma_f32_16x16x32_bf16 v[110:113], v[218:221], v[174:177], v[110:113]
	v_mfma_f32_16x16x32_bf16 v[102:105], v[210:213], v[186:189], v[102:105]
	v_mfma_f32_16x16x32_bf16 v[94:97], v[218:221], v[186:189], v[94:97]
	v_mfma_f32_16x16x32_bf16 v[86:89], v[210:213], v[194:197], v[86:89]
	v_mfma_f32_16x16x32_bf16 v[78:81], v[218:221], v[194:197], v[78:81]
	v_mfma_f32_16x16x32_bf16 v[70:73], v[210:213], v[202:205], v[70:73]
	v_mfma_f32_16x16x32_bf16 v[66:69], v[218:221], v[202:205], v[66:69]
	s_setprio 0
	s_barrier
	s_add_i32 s28, s61, s45
	v_lshl_add_u64 v[146:147], s[30:31], 0, v[132:133]
	s_mov_b32 m0, s28
	global_load_lds_dwordx4 v[146:147], off
	v_lshl_add_u64 v[182:183], s[30:31], 0, v[136:137]
	s_add_i32 m0, s28, 0x2000
	s_nop 0
	global_load_lds_dwordx4 v[182:183], off
	s_mov_b32 m0, s46
	v_lshl_add_u64 v[222:223], s[34:35], 0, v[130:131]
	ds_read_b128 v[170:173], v151 offset:16384
	ds_read_b128 v[174:177], v151 offset:17408
	ds_read_b128 v[178:181], v151 offset:18432
	ds_read_b128 v[186:189], v151 offset:19456
	ds_read_b128 v[190:193], v151 offset:20480
	ds_read_b128 v[194:197], v151 offset:21504
	ds_read_b128 v[198:201], v151 offset:22528
	ds_read_b128 v[202:205], v151 offset:23552
	global_load_lds_dwordx4 v[222:223], off
	v_lshl_add_u64 v[224:225], s[34:35], 0, v[134:135]
	s_mov_b32 m0, s47
	s_nop 0
	global_load_lds_dwordx4 v[224:225], off
	s_waitcnt vmcnt(6)
	s_waitcnt lgkmcnt(0)
	s_barrier
	s_setprio 1
	v_mfma_f32_16x16x32_bf16 v[62:65], v[154:157], v[170:173], v[62:65]
	v_mfma_f32_16x16x32_bf16 v[58:61], v[162:165], v[170:173], v[58:61]
	v_mfma_f32_16x16x32_bf16 v[54:57], v[154:157], v[178:181], v[54:57]
	v_mfma_f32_16x16x32_bf16 v[46:49], v[162:165], v[178:181], v[46:49]
	v_mfma_f32_16x16x32_bf16 v[38:41], v[154:157], v[190:193], v[38:41]
	v_mfma_f32_16x16x32_bf16 v[30:33], v[162:165], v[190:193], v[30:33]
	v_mfma_f32_16x16x32_bf16 v[22:25], v[154:157], v[198:201], v[22:25]
	v_mfma_f32_16x16x32_bf16 v[14:17], v[162:165], v[198:201], v[14:17]
	v_mfma_f32_16x16x32_bf16 v[62:65], v[158:161], v[174:177], v[62:65]
	v_mfma_f32_16x16x32_bf16 v[58:61], v[166:169], v[174:177], v[58:61]
	v_mfma_f32_16x16x32_bf16 v[54:57], v[158:161], v[186:189], v[54:57]
	v_mfma_f32_16x16x32_bf16 v[46:49], v[166:169], v[186:189], v[46:49]
	v_mfma_f32_16x16x32_bf16 v[38:41], v[158:161], v[194:197], v[38:41]
	v_mfma_f32_16x16x32_bf16 v[30:33], v[166:169], v[194:197], v[30:33]
	v_mfma_f32_16x16x32_bf16 v[22:25], v[158:161], v[202:205], v[22:25]
	v_mfma_f32_16x16x32_bf16 v[14:17], v[166:169], v[202:205], v[14:17]
	v_mfma_f32_16x16x32_bf16 v[50:53], v[206:209], v[170:173], v[50:53]
	v_mfma_f32_16x16x32_bf16 v[42:45], v[214:217], v[170:173], v[42:45]
	v_mfma_f32_16x16x32_bf16 v[34:37], v[206:209], v[178:181], v[34:37]
	v_mfma_f32_16x16x32_bf16 v[26:29], v[214:217], v[178:181], v[26:29]
	v_mfma_f32_16x16x32_bf16 v[18:21], v[206:209], v[190:193], v[18:21]
	v_mfma_f32_16x16x32_bf16 v[10:13], v[214:217], v[190:193], v[10:13]
	v_mfma_f32_16x16x32_bf16 v[6:9], v[206:209], v[198:201], v[6:9]
	v_mfma_f32_16x16x32_bf16 v[2:5], v[214:217], v[198:201], v[2:5]
	v_mfma_f32_16x16x32_bf16 v[50:53], v[210:213], v[174:177], v[50:53]
	v_mfma_f32_16x16x32_bf16 v[42:45], v[218:221], v[174:177], v[42:45]
	v_mfma_f32_16x16x32_bf16 v[34:37], v[210:213], v[186:189], v[34:37]
	v_mfma_f32_16x16x32_bf16 v[26:29], v[218:221], v[186:189], v[26:29]
	v_mfma_f32_16x16x32_bf16 v[18:21], v[210:213], v[194:197], v[18:21]
	v_mfma_f32_16x16x32_bf16 v[10:13], v[218:221], v[194:197], v[10:13]
	v_mfma_f32_16x16x32_bf16 v[6:9], v[210:213], v[202:205], v[6:9]
	v_mfma_f32_16x16x32_bf16 v[2:5], v[218:221], v[202:205], v[2:5]
	s_setprio 0
	s_barrier
	s_add_u32 s28, s30, 0x20000
	s_addc_u32 s29, s31, 0
	s_add_i32 s82, s71, s45
	v_lshl_add_u64 v[154:155], s[28:29], 0, v[132:133]
	s_mov_b32 m0, s82
	s_nop 0
	global_load_lds_dwordx4 v[154:155], off
	v_lshl_add_u64 v[154:155], s[28:29], 0, v[136:137]
	s_add_i32 m0, s82, 0x2000
	s_nop 0
	global_load_lds_dwordx4 v[154:155], off
	s_add_i32 s82, 0, 0x18000
	v_add_u32_e32 v153, s82, v148
	ds_read_b128 v[154:157], v153
	ds_read_b128 v[158:161], v153 offset:1024
	ds_read_b128 v[162:165], v153 offset:2048
	ds_read_b128 v[166:169], v153 offset:3072
	s_add_u32 s28, s34, 0xf0000
	s_addc_u32 s29, s35, 0
	s_mov_b32 m0, s50
	v_lshl_add_u64 v[206:207], s[28:29], 0, v[130:131]
	ds_read_b128 v[170:173], v151 offset:32768
	ds_read_b128 v[174:177], v151 offset:33792
	ds_read_b128 v[178:181], v151 offset:34816
	ds_read_b128 v[186:189], v151 offset:35840
	ds_read_b128 v[190:193], v151 offset:36864
	ds_read_b128 v[194:197], v151 offset:37888
	ds_read_b128 v[198:201], v151 offset:38912
	ds_read_b128 v[202:205], v151 offset:39936
	global_load_lds_dwordx4 v[206:207], off
	v_lshl_add_u64 v[206:207], s[28:29], 0, v[134:135]
	s_mov_b32 m0, s51
	s_nop 0
	global_load_lds_dwordx4 v[206:207], off
	v_add_u32_e32 v218, 0x1c000, v148
	ds_read_b128 v[206:209], v218
	ds_read_b128 v[210:213], v218 offset:1024
	ds_read_b128 v[214:217], v218 offset:2048
	ds_read_b128 v[218:221], v218 offset:3072
	s_waitcnt vmcnt(8)
	s_waitcnt lgkmcnt(0)
	s_barrier
	s_setprio 1
	v_mfma_f32_16x16x32_bf16 v[126:129], v[154:157], v[170:173], v[126:129]
	v_mfma_f32_16x16x32_bf16 v[122:125], v[162:165], v[170:173], v[122:125]
	v_mfma_f32_16x16x32_bf16 v[114:117], v[154:157], v[178:181], v[114:117]
	v_mfma_f32_16x16x32_bf16 v[106:109], v[162:165], v[178:181], v[106:109]
	v_mfma_f32_16x16x32_bf16 v[98:101], v[154:157], v[190:193], v[98:101]
	v_mfma_f32_16x16x32_bf16 v[90:93], v[162:165], v[190:193], v[90:93]
	v_mfma_f32_16x16x32_bf16 v[82:85], v[154:157], v[198:201], v[82:85]
	v_mfma_f32_16x16x32_bf16 v[74:77], v[162:165], v[198:201], v[74:77]
	v_mfma_f32_16x16x32_bf16 v[126:129], v[158:161], v[174:177], v[126:129]
	v_mfma_f32_16x16x32_bf16 v[122:125], v[166:169], v[174:177], v[122:125]
	v_mfma_f32_16x16x32_bf16 v[114:117], v[158:161], v[186:189], v[114:117]
	v_mfma_f32_16x16x32_bf16 v[106:109], v[166:169], v[186:189], v[106:109]
	v_mfma_f32_16x16x32_bf16 v[98:101], v[158:161], v[194:197], v[98:101]
	v_mfma_f32_16x16x32_bf16 v[90:93], v[166:169], v[194:197], v[90:93]
	v_mfma_f32_16x16x32_bf16 v[82:85], v[158:161], v[202:205], v[82:85]
	v_mfma_f32_16x16x32_bf16 v[74:77], v[166:169], v[202:205], v[74:77]
	v_mfma_f32_16x16x32_bf16 v[118:121], v[206:209], v[170:173], v[118:121]
	v_mfma_f32_16x16x32_bf16 v[110:113], v[214:217], v[170:173], v[110:113]
	v_mfma_f32_16x16x32_bf16 v[102:105], v[206:209], v[178:181], v[102:105]
	v_mfma_f32_16x16x32_bf16 v[94:97], v[214:217], v[178:181], v[94:97]
	v_mfma_f32_16x16x32_bf16 v[86:89], v[206:209], v[190:193], v[86:89]
	v_mfma_f32_16x16x32_bf16 v[78:81], v[214:217], v[190:193], v[78:81]
	v_mfma_f32_16x16x32_bf16 v[70:73], v[206:209], v[198:201], v[70:73]
	v_mfma_f32_16x16x32_bf16 v[66:69], v[214:217], v[198:201], v[66:69]
	v_mfma_f32_16x16x32_bf16 v[118:121], v[210:213], v[174:177], v[118:121]
	v_mfma_f32_16x16x32_bf16 v[110:113], v[218:221], v[174:177], v[110:113]
	v_mfma_f32_16x16x32_bf16 v[102:105], v[210:213], v[186:189], v[102:105]
	v_mfma_f32_16x16x32_bf16 v[94:97], v[218:221], v[186:189], v[94:97]
	v_mfma_f32_16x16x32_bf16 v[86:89], v[210:213], v[194:197], v[86:89]
	v_mfma_f32_16x16x32_bf16 v[78:81], v[218:221], v[194:197], v[78:81]
	v_mfma_f32_16x16x32_bf16 v[70:73], v[210:213], v[202:205], v[70:73]
	v_mfma_f32_16x16x32_bf16 v[66:69], v[218:221], v[202:205], v[66:69]
	s_setprio 0
	s_barrier
	s_add_i32 s34, 0, 0x1c000
	s_add_i32 s28, s82, s45
	v_lshl_add_u64 v[146:147], v[146:147], 0, s[6:7]
	s_mov_b32 m0, s28
	global_load_lds_dwordx4 v[146:147], off
	v_lshl_add_u64 v[146:147], v[182:183], 0, s[6:7]
	s_add_i32 m0, s28, 0x2000
	s_nop 0
	global_load_lds_dwordx4 v[146:147], off
	s_mov_b32 m0, s53
	v_lshl_add_u64 v[146:147], v[222:223], 0, s[6:7]
	ds_read_b128 v[170:173], v151 offset:49152
	ds_read_b128 v[174:177], v151 offset:50176
	ds_read_b128 v[178:181], v151 offset:51200
	ds_read_b128 v[186:189], v151 offset:52224
	ds_read_b128 v[190:193], v151 offset:53248
	ds_read_b128 v[194:197], v151 offset:54272
	ds_read_b128 v[198:201], v151 offset:55296
	ds_read_b128 v[202:205], v151 offset:56320
	global_load_lds_dwordx4 v[146:147], off
	v_lshl_add_u64 v[146:147], v[224:225], 0, s[6:7]
	s_mov_b32 m0, s58
	s_nop 0
	global_load_lds_dwordx4 v[146:147], off
	s_add_u32 s28, s30, 0x20080
	s_addc_u32 s29, s31, 0
	s_add_i32 s30, s34, s45
	v_lshl_add_u64 v[146:147], s[28:29], 0, v[132:133]
	s_mov_b32 m0, s30
	s_nop 0
	global_load_lds_dwordx4 v[146:147], off
	v_lshl_add_u64 v[146:147], s[28:29], 0, v[136:137]
	s_add_i32 m0, s30, 0x2000
	s_nop 0
	global_load_lds_dwordx4 v[146:147], off
	s_waitcnt vmcnt(8)
	s_waitcnt lgkmcnt(0)
	s_barrier
	s_setprio 1
	v_mfma_f32_16x16x32_bf16 v[62:65], v[154:157], v[170:173], v[62:65]
	v_mfma_f32_16x16x32_bf16 v[58:61], v[162:165], v[170:173], v[58:61]
	v_mfma_f32_16x16x32_bf16 v[54:57], v[154:157], v[178:181], v[54:57]
	v_mfma_f32_16x16x32_bf16 v[46:49], v[162:165], v[178:181], v[46:49]
	v_mfma_f32_16x16x32_bf16 v[38:41], v[154:157], v[190:193], v[38:41]
	v_mfma_f32_16x16x32_bf16 v[30:33], v[162:165], v[190:193], v[30:33]
	v_mfma_f32_16x16x32_bf16 v[22:25], v[154:157], v[198:201], v[22:25]
	v_mfma_f32_16x16x32_bf16 v[14:17], v[162:165], v[198:201], v[14:17]
	v_mfma_f32_16x16x32_bf16 v[62:65], v[158:161], v[174:177], v[62:65]
	v_mfma_f32_16x16x32_bf16 v[58:61], v[166:169], v[174:177], v[58:61]
	v_mfma_f32_16x16x32_bf16 v[54:57], v[158:161], v[186:189], v[54:57]
	v_mfma_f32_16x16x32_bf16 v[46:49], v[166:169], v[186:189], v[46:49]
	v_mfma_f32_16x16x32_bf16 v[38:41], v[158:161], v[194:197], v[38:41]
	v_mfma_f32_16x16x32_bf16 v[30:33], v[166:169], v[194:197], v[30:33]
	v_mfma_f32_16x16x32_bf16 v[22:25], v[158:161], v[202:205], v[22:25]
	v_mfma_f32_16x16x32_bf16 v[14:17], v[166:169], v[202:205], v[14:17]
	v_mfma_f32_16x16x32_bf16 v[50:53], v[206:209], v[170:173], v[50:53]
	v_mfma_f32_16x16x32_bf16 v[42:45], v[214:217], v[170:173], v[42:45]
	v_mfma_f32_16x16x32_bf16 v[34:37], v[206:209], v[178:181], v[34:37]
	v_mfma_f32_16x16x32_bf16 v[26:29], v[214:217], v[178:181], v[26:29]
	v_mfma_f32_16x16x32_bf16 v[18:21], v[206:209], v[190:193], v[18:21]
	v_mfma_f32_16x16x32_bf16 v[10:13], v[214:217], v[190:193], v[10:13]
	v_mfma_f32_16x16x32_bf16 v[6:9], v[206:209], v[198:201], v[6:9]
	v_mfma_f32_16x16x32_bf16 v[2:5], v[214:217], v[198:201], v[2:5]
	v_mfma_f32_16x16x32_bf16 v[50:53], v[210:213], v[174:177], v[50:53]
	v_mfma_f32_16x16x32_bf16 v[42:45], v[218:221], v[174:177], v[42:45]
	v_mfma_f32_16x16x32_bf16 v[34:37], v[210:213], v[186:189], v[34:37]
	v_mfma_f32_16x16x32_bf16 v[26:29], v[218:221], v[186:189], v[26:29]
	v_mfma_f32_16x16x32_bf16 v[18:21], v[210:213], v[194:197], v[18:21]
	v_mfma_f32_16x16x32_bf16 v[10:13], v[218:221], v[194:197], v[10:13]
	v_mfma_f32_16x16x32_bf16 v[6:9], v[210:213], v[202:205], v[6:9]
	v_mfma_f32_16x16x32_bf16 v[2:5], v[218:221], v[202:205], v[2:5]
	s_setprio 0
	s_add_i32 s81, s81, 2
	s_add_u32 s79, s79, 0x100
	s_addc_u32 s80, s80, 0
	s_cmp_gt_u32 s81, 5
	s_mov_b64 s[28:29], s[4:5]
	s_barrier
	s_cbranch_scc0 .LBB0_457
	v_lshl_add_u32 v154, s69, 8, v1
	v_lshl_or_b32 v146, s70, 8, v149
	v_ashrrev_i32_e32 v155, 31, v154
	v_ashrrev_i32_e32 v147, 31, v146
	v_lshlrev_b64 v[156:157], 12, v[154:155]
	v_lshl_add_u64 v[156:157], s[88:89], 0, v[156:157]
	v_lshlrev_b64 v[158:159], 1, v[146:147]
	v_lshl_add_u64 v[146:147], v[156:157], 0, v[158:159]
	v_cvt_pk_bf16_f32 v126, v126, v127
	v_cvt_pk_bf16_f32 v127, v128, v129
	v_cvt_pk_bf16_f32 v128, v122, v123
	v_cvt_pk_bf16_f32 v129, v124, v125
	global_store_dwordx4 v[146:147], v[126:129], off sc1
	v_cvt_pk_bf16_f32 v118, v118, v119
	v_cvt_pk_bf16_f32 v119, v120, v121
	v_cvt_pk_bf16_f32 v120, v110, v111
	v_or_b32_e32 v110, 16, v154
	v_ashrrev_i32_e32 v111, 31, v110
	v_lshlrev_b64 v[110:111], 12, v[110:111]
	v_lshl_add_u64 v[110:111], s[88:89], 0, v[110:111]
	v_cvt_pk_bf16_f32 v121, v112, v113
	global_store_dwordx4 v[146:147], v[118:121], off offset:256 sc1
	s_mov_b32 s70, s22
	s_mov_b32 s69, s68
	v_lshl_add_u64 v[118:119], v[110:111], 0, v[158:159]
	v_cvt_pk_bf16_f32 v110, v114, v115
	v_cvt_pk_bf16_f32 v111, v116, v117
	v_cvt_pk_bf16_f32 v112, v106, v107
	v_cvt_pk_bf16_f32 v113, v108, v109
	global_store_dwordx4 v[118:119], v[110:113], off sc1
	v_cvt_pk_bf16_f32 v102, v102, v103
	v_cvt_pk_bf16_f32 v103, v104, v105
	v_cvt_pk_bf16_f32 v104, v94, v95
	v_or_b32_e32 v94, 32, v154
	v_ashrrev_i32_e32 v95, 31, v94
	v_lshlrev_b64 v[94:95], 12, v[94:95]
	v_lshl_add_u64 v[94:95], s[88:89], 0, v[94:95]
	v_cvt_pk_bf16_f32 v105, v96, v97
	global_store_dwordx4 v[118:119], v[102:105], off offset:256 sc1
	s_mov_b64 s[30:31], s[26:27]
	s_mov_b64 s[28:29], s[24:25]
	v_lshl_add_u64 v[102:103], v[94:95], 0, v[158:159]
	v_cvt_pk_bf16_f32 v94, v98, v99
	v_cvt_pk_bf16_f32 v95, v100, v101
	v_cvt_pk_bf16_f32 v96, v90, v91
	v_cvt_pk_bf16_f32 v97, v92, v93
	global_store_dwordx4 v[102:103], v[94:97], off sc1
	v_cvt_pk_bf16_f32 v86, v86, v87
	v_cvt_pk_bf16_f32 v87, v88, v89
	v_cvt_pk_bf16_f32 v88, v78, v79
	v_or_b32_e32 v78, 48, v154
	v_ashrrev_i32_e32 v79, 31, v78
	v_lshlrev_b64 v[78:79], 12, v[78:79]
	v_lshl_add_u64 v[78:79], s[88:89], 0, v[78:79]
	v_cvt_pk_bf16_f32 v89, v80, v81
	global_store_dwordx4 v[102:103], v[86:89], off offset:256 sc1
	s_nop 1
	v_lshl_add_u64 v[86:87], v[78:79], 0, v[158:159]
	v_cvt_pk_bf16_f32 v78, v82, v83
	v_cvt_pk_bf16_f32 v79, v84, v85
	v_cvt_pk_bf16_f32 v80, v74, v75
	v_cvt_pk_bf16_f32 v81, v76, v77
	global_store_dwordx4 v[86:87], v[78:81], off sc1
	v_cvt_pk_bf16_f32 v70, v70, v71
	v_cvt_pk_bf16_f32 v71, v72, v73
	v_cvt_pk_bf16_f32 v72, v66, v67
	v_cvt_pk_bf16_f32 v73, v68, v69
	global_store_dwordx4 v[86:87], v[70:73], off offset:256 sc1
	v_cvt_pk_bf16_f32 v62, v62, v63
	v_cvt_pk_bf16_f32 v63, v64, v65
	v_cvt_pk_bf16_f32 v64, v58, v59
	v_add_co_u32_e32 v58, vcc, s74, v146
	v_lshl_add_u64 v[66:67], v[146:147], 0, s[8:9]
	s_nop 0
	v_addc_co_u32_e32 v59, vcc, 0, v147, vcc
	v_cvt_pk_bf16_f32 v65, v60, v61
	global_store_dwordx4 v[58:59], v[62:65], off sc1
	v_cvt_pk_bf16_f32 v50, v50, v51
	v_cvt_pk_bf16_f32 v51, v52, v53
	v_cvt_pk_bf16_f32 v52, v42, v43
	v_cvt_pk_bf16_f32 v53, v44, v45
	global_store_dwordx4 v[66:67], v[50:53], off offset:256 sc1
	v_cvt_pk_bf16_f32 v42, v54, v55
	v_cvt_pk_bf16_f32 v43, v56, v57
	v_cvt_pk_bf16_f32 v44, v46, v47
	v_add_co_u32_e32 v46, vcc, s75, v146
	s_nop 0
	v_lshl_add_u64 v[50:51], v[146:147], 0, s[16:17]
	v_addc_co_u32_e32 v47, vcc, 0, v147, vcc
	v_cvt_pk_bf16_f32 v45, v48, v49
	global_store_dwordx4 v[46:47], v[42:45], off sc1
	v_cvt_pk_bf16_f32 v34, v34, v35
	v_cvt_pk_bf16_f32 v35, v36, v37
	v_cvt_pk_bf16_f32 v36, v26, v27
	v_cvt_pk_bf16_f32 v37, v28, v29
	global_store_dwordx4 v[50:51], v[34:37], off offset:256 sc1
	v_cvt_pk_bf16_f32 v26, v38, v39
	v_cvt_pk_bf16_f32 v27, v40, v41
	v_cvt_pk_bf16_f32 v28, v30, v31
	v_add_co_u32_e32 v30, vcc, s76, v146
	s_nop 0
	v_lshl_add_u64 v[34:35], v[146:147], 0, s[18:19]
	v_addc_co_u32_e32 v31, vcc, 0, v147, vcc
	v_cvt_pk_bf16_f32 v29, v32, v33
	global_store_dwordx4 v[30:31], v[26:29], off sc1
	v_cvt_pk_bf16_f32 v18, v18, v19
	v_cvt_pk_bf16_f32 v19, v20, v21
	v_cvt_pk_bf16_f32 v20, v10, v11
	v_cvt_pk_bf16_f32 v21, v12, v13
	global_store_dwordx4 v[34:35], v[18:21], off offset:256 sc1
	v_cvt_pk_bf16_f32 v10, v22, v23
	v_cvt_pk_bf16_f32 v11, v24, v25
	v_cvt_pk_bf16_f32 v12, v14, v15
	v_add_co_u32_e32 v14, vcc, s77, v146
	s_nop 0
	v_lshl_add_u64 v[18:19], v[146:147], 0, s[20:21]
	v_addc_co_u32_e32 v15, vcc, 0, v147, vcc
	s_and_b64 vcc, exec, s[2:3]
	v_cvt_pk_bf16_f32 v13, v16, v17
	global_store_dwordx4 v[14:15], v[10:13], off sc1
	v_cvt_pk_bf16_f32 v6, v6, v7
	v_cvt_pk_bf16_f32 v7, v8, v9
	v_cvt_pk_bf16_f32 v8, v2, v3
	v_cvt_pk_bf16_f32 v9, v4, v5
	global_store_dwordx4 v[18:19], v[6:9], off offset:256 sc1
	s_cbranch_vccz .LBB0_448
	s_waitcnt vmcnt(0)
	s_cmpk_gt_u32 s36, 0xff
	s_cbranch_scc1 .LBB0_461
	s_barrier

.LBB0_532:
	s_or_b64 exec, exec, s[0:1]
	s_waitcnt lgkmcnt(0)
	ds_read_b128 v[66:69], v158
	ds_read_b128 v[70:73], v158 offset:32
	v_mul_lo_u32 v82, v167, s78
	v_add_u32_e32 v82, 0, v82
	v_lshlrev_b32_e32 v83, 1, v168
	s_waitcnt lgkmcnt(1)
	v_rcp_f32_e32 v74, v66
	v_mul_u32_u24_e32 v84, 0x440, v169
	v_rcp_f32_e32 v75, v67
	v_rcp_f32_e32 v76, v68
	v_mul_f32_e32 v2, v2, v74
	v_rcp_f32_e32 v77, v69
	s_waitcnt lgkmcnt(0)
	v_rcp_f32_e32 v78, v70
	ds_read_b128 v[66:69], v158 offset:64
	v_rcp_f32_e32 v79, v71
	v_rcp_f32_e32 v80, v72
	v_rcp_f32_e32 v81, v73
	ds_read_b128 v[70:73], v158 offset:96
	s_waitcnt lgkmcnt(0)
	s_barrier
	v_add3_u32 v83, v82, v83, v84
	v_cvt_pk_bf16_f32 v2, v2, v159
	ds_write_b16 v83, v2
	v_mul_f32_e32 v2, v50, v74
	v_cvt_pk_bf16_f32 v2, v2, v159
	ds_write_b16 v83, v2 offset:64
	v_mul_f32_e32 v2, v34, v74
	v_cvt_pk_bf16_f32 v2, v2, v159
	ds_write_b16 v83, v2 offset:128
	v_mul_f32_e32 v2, v18, v74
	v_cvt_pk_bf16_f32 v2, v2, v159
	ds_write_b16 v83, v2 offset:192
	v_mul_f32_e32 v2, v3, v75
	v_cvt_pk_bf16_f32 v2, v2, v159
	ds_write_b16 v83, v2 offset:272
	v_mul_f32_e32 v2, v51, v75
	v_cvt_pk_bf16_f32 v2, v2, v159
	ds_write_b16 v83, v2 offset:336
	v_mul_f32_e32 v2, v35, v75
	v_cvt_pk_bf16_f32 v2, v2, v159
	ds_write_b16 v83, v2 offset:400
	v_mul_f32_e32 v2, v19, v75
	v_cvt_pk_bf16_f32 v2, v2, v159
	ds_write_b16 v83, v2 offset:464
	v_mul_f32_e32 v2, v4, v76
	v_cvt_pk_bf16_f32 v2, v2, v159
	ds_write_b16 v83, v2 offset:544
	v_mul_f32_e32 v2, v52, v76
	v_cvt_pk_bf16_f32 v2, v2, v159
	ds_write_b16 v83, v2 offset:608
	v_mul_f32_e32 v2, v36, v76
	v_cvt_pk_bf16_f32 v2, v2, v159
	ds_write_b16 v83, v2 offset:672
	v_mul_f32_e32 v2, v20, v76
	v_cvt_pk_bf16_f32 v2, v2, v159
	ds_write_b16 v83, v2 offset:736
	v_mul_f32_e32 v2, v5, v77
	v_cvt_pk_bf16_f32 v2, v2, v159
	ds_write_b16 v83, v2 offset:816
	v_mul_f32_e32 v2, v53, v77
	v_cvt_pk_bf16_f32 v2, v2, v159
	ds_write_b16 v83, v2 offset:880
	v_mul_f32_e32 v2, v37, v77
	v_cvt_pk_bf16_f32 v2, v2, v159
	ds_write_b16 v83, v2 offset:944
	v_mul_f32_e32 v2, v21, v77
	v_cvt_pk_bf16_f32 v2, v2, v159
	ds_write_b16 v83, v2 offset:1008
	v_mul_f32_e32 v2, v6, v78
	v_cvt_pk_bf16_f32 v2, v2, v159
	ds_write_b16 v83, v2 offset:2176
	v_mul_f32_e32 v2, v54, v78
	v_cvt_pk_bf16_f32 v2, v2, v159
	ds_write_b16 v83, v2 offset:2240
	v_mul_f32_e32 v2, v38, v78
	v_cvt_pk_bf16_f32 v2, v2, v159
	ds_write_b16 v83, v2 offset:2304
	v_mul_f32_e32 v2, v22, v78
	v_cvt_pk_bf16_f32 v2, v2, v159
	ds_write_b16 v83, v2 offset:2368
	v_mul_f32_e32 v2, v7, v79
	v_cvt_pk_bf16_f32 v2, v2, v159
	ds_write_b16 v83, v2 offset:2448
	v_mul_f32_e32 v2, v55, v79
	v_cvt_pk_bf16_f32 v2, v2, v159
	ds_write_b16 v83, v2 offset:2512
	v_mul_f32_e32 v2, v39, v79
	v_cvt_pk_bf16_f32 v2, v2, v159
	ds_write_b16 v83, v2 offset:2576
	v_mul_f32_e32 v2, v23, v79
	v_cvt_pk_bf16_f32 v2, v2, v159
	ds_write_b16 v83, v2 offset:2640
	v_mul_f32_e32 v2, v8, v80
	v_cvt_pk_bf16_f32 v2, v2, v159
	ds_write_b16 v83, v2 offset:2720
	v_mul_f32_e32 v2, v56, v80
	v_cvt_pk_bf16_f32 v2, v2, v159
	ds_write_b16 v83, v2 offset:2784
	v_mul_f32_e32 v2, v40, v80
	v_cvt_pk_bf16_f32 v2, v2, v159
	ds_write_b16 v83, v2 offset:2848
	v_mul_f32_e32 v2, v24, v80
	v_cvt_pk_bf16_f32 v2, v2, v159
	ds_write_b16 v83, v2 offset:2912
	v_mul_f32_e32 v2, v9, v81
	v_cvt_pk_bf16_f32 v2, v2, v159
	ds_write_b16 v83, v2 offset:2992
	v_mul_f32_e32 v2, v57, v81
	v_cvt_pk_bf16_f32 v2, v2, v159
	v_rcp_f32_e32 v66, v66
	ds_write_b16 v83, v2 offset:3056
	v_mul_f32_e32 v2, v41, v81
	v_cvt_pk_bf16_f32 v2, v2, v159
	ds_write_b16 v83, v2 offset:3120
	v_mul_f32_e32 v2, v25, v81
	v_cvt_pk_bf16_f32 v2, v2, v159
	ds_write_b16 v83, v2 offset:3184
	v_mul_f32_e32 v2, v10, v66
	v_cvt_pk_bf16_f32 v2, v2, v159
	ds_write_b16 v83, v2 offset:4352
	v_mul_f32_e32 v2, v58, v66
	v_cvt_pk_bf16_f32 v2, v2, v159
	v_rcp_f32_e32 v67, v67
	ds_write_b16 v83, v2 offset:4416
	v_mul_f32_e32 v2, v42, v66
	v_cvt_pk_bf16_f32 v2, v2, v159
	ds_write_b16 v83, v2 offset:4480
	v_mul_f32_e32 v2, v26, v66
	v_cvt_pk_bf16_f32 v2, v2, v159
	ds_write_b16 v83, v2 offset:4544
	v_mul_f32_e32 v2, v11, v67
	v_cvt_pk_bf16_f32 v2, v2, v159
	ds_write_b16 v83, v2 offset:4624
	v_mul_f32_e32 v2, v59, v67
	v_cvt_pk_bf16_f32 v2, v2, v159
	v_rcp_f32_e32 v68, v68
	ds_write_b16 v83, v2 offset:4688
	v_mul_f32_e32 v2, v43, v67
	v_cvt_pk_bf16_f32 v2, v2, v159
	ds_write_b16 v83, v2 offset:4752
	v_mul_f32_e32 v2, v27, v67
	v_cvt_pk_bf16_f32 v2, v2, v159
	ds_write_b16 v83, v2 offset:4816
	v_mul_f32_e32 v2, v12, v68
	v_cvt_pk_bf16_f32 v2, v2, v159
	ds_write_b16 v83, v2 offset:4896
	v_mul_f32_e32 v2, v60, v68
	v_cvt_pk_bf16_f32 v2, v2, v159
	v_rcp_f32_e32 v69, v69
	ds_write_b16 v83, v2 offset:4960
	v_mul_f32_e32 v2, v44, v68
	v_cvt_pk_bf16_f32 v2, v2, v159
	ds_write_b16 v83, v2 offset:5024
	v_mul_f32_e32 v2, v28, v68
	v_cvt_pk_bf16_f32 v2, v2, v159
	ds_write_b16 v83, v2 offset:5088
	v_mul_f32_e32 v2, v13, v69
	v_cvt_pk_bf16_f32 v2, v2, v159
	ds_write_b16 v83, v2 offset:5168
	v_mul_f32_e32 v2, v61, v69
	v_cvt_pk_bf16_f32 v2, v2, v159
	v_rcp_f32_e32 v70, v70
	ds_write_b16 v83, v2 offset:5232
	v_mul_f32_e32 v2, v45, v69
	v_cvt_pk_bf16_f32 v2, v2, v159
	ds_write_b16 v83, v2 offset:5296
	v_mul_f32_e32 v2, v29, v69
	v_cvt_pk_bf16_f32 v2, v2, v159
	ds_write_b16 v83, v2 offset:5360
	v_mul_f32_e32 v2, v14, v70
	v_cvt_pk_bf16_f32 v2, v2, v159
	ds_write_b16 v83, v2 offset:6528
	v_mul_f32_e32 v2, v62, v70
	v_cvt_pk_bf16_f32 v2, v2, v159
	v_rcp_f32_e32 v71, v71
	ds_write_b16 v83, v2 offset:6592
	v_mul_f32_e32 v2, v46, v70
	v_cvt_pk_bf16_f32 v2, v2, v159
	ds_write_b16 v83, v2 offset:6656
	v_mul_f32_e32 v2, v30, v70
	v_cvt_pk_bf16_f32 v2, v2, v159
	ds_write_b16 v83, v2 offset:6720
	v_mul_f32_e32 v2, v15, v71
	v_cvt_pk_bf16_f32 v2, v2, v159
	ds_write_b16 v83, v2 offset:6800
	v_mul_f32_e32 v2, v63, v71
	v_cvt_pk_bf16_f32 v2, v2, v159
	v_rcp_f32_e32 v72, v72
	ds_write_b16 v83, v2 offset:6864
	v_mul_f32_e32 v2, v47, v71
	v_cvt_pk_bf16_f32 v2, v2, v159
	ds_write_b16 v83, v2 offset:6928
	v_mul_f32_e32 v2, v31, v71
	v_cvt_pk_bf16_f32 v2, v2, v159
	ds_write_b16 v83, v2 offset:6992
	v_mul_f32_e32 v2, v16, v72
	v_cvt_pk_bf16_f32 v2, v2, v159
	ds_write_b16 v83, v2 offset:7072
	v_mul_f32_e32 v2, v64, v72
	v_cvt_pk_bf16_f32 v2, v2, v159
	v_rcp_f32_e32 v73, v73
	ds_write_b16 v83, v2 offset:7136
	v_mul_f32_e32 v2, v48, v72
	v_cvt_pk_bf16_f32 v2, v2, v159
	ds_write_b16 v83, v2 offset:7200
	v_mul_f32_e32 v2, v32, v72
	v_cvt_pk_bf16_f32 v2, v2, v159
	ds_write_b16 v83, v2 offset:7264
	v_mul_f32_e32 v2, v17, v73
	v_cvt_pk_bf16_f32 v2, v2, v159
	ds_write_b16 v83, v2 offset:7344
	v_mul_f32_e32 v2, v65, v73
	v_cvt_pk_bf16_f32 v2, v2, v159
	ds_write_b16 v83, v2 offset:7408
	v_mul_f32_e32 v2, v49, v73
	v_cvt_pk_bf16_f32 v2, v2, v159
	ds_write_b16 v83, v2 offset:7472
	v_mul_f32_e32 v2, v33, v73
	v_cvt_pk_bf16_f32 v2, v2, v159
	ds_write_b16 v83, v2 offset:7536
	v_lshrrev_b32_e32 v2, 4, v161
	v_or_b32_e32 v8, v166, v2
	v_mul_u32_u24_e32 v2, 0x110, v2
	s_waitcnt lgkmcnt(0)
	v_add3_u32 v14, v82, v2, v160
	v_mov_b64_e32 v[6:7], s[60:61]
	ds_read_b128 v[2:5], v14
	v_mad_i64_i32 v[6:7], s[0:1], v8, s35, v[6:7]
	v_mov_b32_e32 v161, v159
	v_lshl_add_u64 v[10:11], v[6:7], 0, v[160:161]
	ds_read_b128 v[6:9], v14 offset:1088
	s_waitcnt lgkmcnt(1)
	global_store_dwordx4 v[10:11], v[2:5], off offset:2048 sc1
	s_add_i32 s85, s85, s72
	s_add_i32 s84, s84, s72
	v_add_co_u32_e32 v2, vcc, s79, v10
	s_cmpk_gt_i32 s85, 0x3ff
	s_nop 0
	v_addc_co_u32_e32 v3, vcc, 0, v11, vcc
	s_waitcnt lgkmcnt(0)
	global_store_dwordx4 v[2:3], v[6:9], off sc1
	ds_read_b128 v[2:5], v14 offset:2176
	ds_read_b128 v[6:9], v14 offset:3264
	v_add_co_u32_e32 v12, vcc, s80, v10
	s_nop 1
	v_addc_co_u32_e32 v13, vcc, 0, v11, vcc
	s_waitcnt lgkmcnt(1)
	global_store_dwordx4 v[12:13], v[2:5], off offset:2048 sc1
	s_nop 1
	v_add_co_u32_e32 v2, vcc, s81, v10
	s_nop 1
	v_addc_co_u32_e32 v3, vcc, 0, v11, vcc
	s_waitcnt lgkmcnt(0)
	global_store_dwordx4 v[2:3], v[6:9], off sc1
	ds_read_b128 v[2:5], v14 offset:4352
	ds_read_b128 v[6:9], v14 offset:5440
	v_add_co_u32_e32 v12, vcc, s82, v10
	s_nop 1
	v_addc_co_u32_e32 v13, vcc, 0, v11, vcc
	s_waitcnt lgkmcnt(1)
	global_store_dwordx4 v[12:13], v[2:5], off offset:2048 sc1
	s_nop 1
	v_add_co_u32_e32 v2, vcc, s83, v10
	s_nop 1
	v_addc_co_u32_e32 v3, vcc, 0, v11, vcc
	s_waitcnt lgkmcnt(0)
	global_store_dwordx4 v[2:3], v[6:9], off sc1
	ds_read_b128 v[2:5], v14 offset:6528
	ds_read_b128 v[6:9], v14 offset:7616
	v_add_co_u32_e32 v12, vcc, 0x2d000, v10
	s_nop 1
	v_addc_co_u32_e32 v13, vcc, 0, v11, vcc
	s_waitcnt lgkmcnt(1)
	global_store_dwordx4 v[12:13], v[2:5], off offset:2048 sc1
	s_nop 1
	v_add_co_u32_e32 v2, vcc, 0x35000, v10
	s_nop 1
	v_addc_co_u32_e32 v3, vcc, 0, v11, vcc
	s_waitcnt lgkmcnt(0)
	global_store_dwordx4 v[2:3], v[6:9], off sc1
	s_cbranch_scc1 .LBB0_562

.LBB0_563:
	s_or_b64 exec, exec, s[0:1]
	s_waitcnt lgkmcnt(0)
	ds_read_b128 v[66:69], v166
	ds_read_b128 v[70:73], v166 offset:32
	v_mul_lo_u32 v81, v162, s82
	v_add_u32_e32 v81, 0, v81
	v_lshlrev_b32_e32 v82, 1, v160
	s_waitcnt lgkmcnt(1)
	v_rcp_f32_e32 v1, v66
	v_rcp_f32_e32 v74, v67
	v_mul_u32_u24_e32 v83, 0x440, v161
	v_add3_u32 v82, v81, v82, v83
	v_mul_f32_e32 v50, v50, v1
	v_mul_f32_e32 v34, v34, v1
	v_mul_f32_e32 v18, v18, v1
	v_mul_f32_e32 v1, v2, v1
	v_rcp_f32_e32 v75, v68
	v_rcp_f32_e32 v76, v69
	s_waitcnt lgkmcnt(0)
	v_rcp_f32_e32 v77, v70
	ds_read_b128 v[66:69], v166 offset:64
	v_rcp_f32_e32 v78, v71
	v_rcp_f32_e32 v79, v72
	v_rcp_f32_e32 v80, v73
	ds_read_b128 v[70:73], v166 offset:96
	s_waitcnt lgkmcnt(0)
	s_barrier
	v_cvt_pk_bf16_f32 v50, v50, v149
	ds_write_b16 v82, v50
	v_cvt_pk_bf16_f32 v34, v34, v149
	ds_write_b16 v82, v34 offset:64
	v_cvt_pk_bf16_f32 v18, v18, v149
	ds_write_b16 v82, v18 offset:128
	v_cvt_pk_bf16_f32 v1, v1, v149
	ds_write_b16 v82, v1 offset:192
	v_mul_f32_e32 v1, v51, v74
	v_cvt_pk_bf16_f32 v1, v1, v149
	ds_write_b16 v82, v1 offset:272
	v_mul_f32_e32 v1, v35, v74
	v_cvt_pk_bf16_f32 v1, v1, v149
	ds_write_b16 v82, v1 offset:336
	v_mul_f32_e32 v1, v19, v74
	v_cvt_pk_bf16_f32 v1, v1, v149
	ds_write_b16 v82, v1 offset:400
	v_mul_f32_e32 v1, v3, v74
	v_cvt_pk_bf16_f32 v1, v1, v149
	ds_write_b16 v82, v1 offset:464
	v_mul_f32_e32 v1, v52, v75
	v_cvt_pk_bf16_f32 v1, v1, v149
	ds_write_b16 v82, v1 offset:544
	v_mul_f32_e32 v1, v36, v75
	v_cvt_pk_bf16_f32 v1, v1, v149
	ds_write_b16 v82, v1 offset:608
	v_mul_f32_e32 v1, v20, v75
	v_cvt_pk_bf16_f32 v1, v1, v149
	ds_write_b16 v82, v1 offset:672
	v_mul_f32_e32 v1, v4, v75
	v_cvt_pk_bf16_f32 v1, v1, v149
	ds_write_b16 v82, v1 offset:736
	v_mul_f32_e32 v1, v53, v76
	v_cvt_pk_bf16_f32 v1, v1, v149
	ds_write_b16 v82, v1 offset:816
	v_mul_f32_e32 v1, v37, v76
	v_cvt_pk_bf16_f32 v1, v1, v149
	ds_write_b16 v82, v1 offset:880
	v_mul_f32_e32 v1, v21, v76
	v_cvt_pk_bf16_f32 v1, v1, v149
	ds_write_b16 v82, v1 offset:944
	v_mul_f32_e32 v1, v5, v76
	v_cvt_pk_bf16_f32 v1, v1, v149
	ds_write_b16 v82, v1 offset:1008
	v_mul_f32_e32 v1, v54, v77
	v_cvt_pk_bf16_f32 v1, v1, v149
	ds_write_b16 v82, v1 offset:2176
	v_mul_f32_e32 v1, v38, v77
	v_cvt_pk_bf16_f32 v1, v1, v149
	ds_write_b16 v82, v1 offset:2240
	v_mul_f32_e32 v1, v22, v77
	v_cvt_pk_bf16_f32 v1, v1, v149
	ds_write_b16 v82, v1 offset:2304
	v_mul_f32_e32 v1, v6, v77
	v_cvt_pk_bf16_f32 v1, v1, v149
	ds_write_b16 v82, v1 offset:2368
	v_mul_f32_e32 v1, v55, v78
	v_cvt_pk_bf16_f32 v1, v1, v149
	ds_write_b16 v82, v1 offset:2448
	v_mul_f32_e32 v1, v39, v78
	v_cvt_pk_bf16_f32 v1, v1, v149
	ds_write_b16 v82, v1 offset:2512
	v_mul_f32_e32 v1, v23, v78
	v_cvt_pk_bf16_f32 v1, v1, v149
	ds_write_b16 v82, v1 offset:2576
	v_mul_f32_e32 v1, v7, v78
	v_cvt_pk_bf16_f32 v1, v1, v149
	ds_write_b16 v82, v1 offset:2640
	v_mul_f32_e32 v1, v56, v79
	v_cvt_pk_bf16_f32 v1, v1, v149
	ds_write_b16 v82, v1 offset:2720
	v_mul_f32_e32 v1, v40, v79
	v_cvt_pk_bf16_f32 v1, v1, v149
	ds_write_b16 v82, v1 offset:2784
	v_mul_f32_e32 v1, v24, v79
	v_cvt_pk_bf16_f32 v1, v1, v149
	ds_write_b16 v82, v1 offset:2848
	v_mul_f32_e32 v1, v8, v79
	v_cvt_pk_bf16_f32 v1, v1, v149
	ds_write_b16 v82, v1 offset:2912
	v_mul_f32_e32 v1, v57, v80
	v_cvt_pk_bf16_f32 v1, v1, v149
	ds_write_b16 v82, v1 offset:2992
	v_mul_f32_e32 v1, v41, v80
	v_cvt_pk_bf16_f32 v1, v1, v149
	v_rcp_f32_e32 v66, v66
	ds_write_b16 v82, v1 offset:3056
	v_mul_f32_e32 v1, v25, v80
	v_cvt_pk_bf16_f32 v1, v1, v149
	ds_write_b16 v82, v1 offset:3120
	v_mul_f32_e32 v1, v9, v80
	v_cvt_pk_bf16_f32 v1, v1, v149
	ds_write_b16 v82, v1 offset:3184
	v_mul_f32_e32 v1, v58, v66
	v_cvt_pk_bf16_f32 v1, v1, v149
	ds_write_b16 v82, v1 offset:4352
	v_mul_f32_e32 v1, v42, v66
	v_cvt_pk_bf16_f32 v1, v1, v149
	v_rcp_f32_e32 v67, v67
	ds_write_b16 v82, v1 offset:4416
	v_mul_f32_e32 v1, v26, v66
	v_cvt_pk_bf16_f32 v1, v1, v149
	ds_write_b16 v82, v1 offset:4480
	v_mul_f32_e32 v1, v10, v66
	v_cvt_pk_bf16_f32 v1, v1, v149
	ds_write_b16 v82, v1 offset:4544
	v_mul_f32_e32 v1, v59, v67
	v_cvt_pk_bf16_f32 v1, v1, v149
	ds_write_b16 v82, v1 offset:4624
	v_mul_f32_e32 v1, v43, v67
	v_cvt_pk_bf16_f32 v1, v1, v149
	v_rcp_f32_e32 v68, v68
	ds_write_b16 v82, v1 offset:4688
	v_mul_f32_e32 v1, v27, v67
	v_cvt_pk_bf16_f32 v1, v1, v149
	ds_write_b16 v82, v1 offset:4752
	v_mul_f32_e32 v1, v11, v67
	v_cvt_pk_bf16_f32 v1, v1, v149
	ds_write_b16 v82, v1 offset:4816
	v_mul_f32_e32 v1, v60, v68
	v_cvt_pk_bf16_f32 v1, v1, v149
	ds_write_b16 v82, v1 offset:4896
	v_mul_f32_e32 v1, v44, v68
	v_cvt_pk_bf16_f32 v1, v1, v149
	v_rcp_f32_e32 v69, v69
	ds_write_b16 v82, v1 offset:4960
	v_mul_f32_e32 v1, v28, v68
	v_cvt_pk_bf16_f32 v1, v1, v149
	ds_write_b16 v82, v1 offset:5024
	v_mul_f32_e32 v1, v12, v68
	v_cvt_pk_bf16_f32 v1, v1, v149
	ds_write_b16 v82, v1 offset:5088
	v_mul_f32_e32 v1, v61, v69
	v_cvt_pk_bf16_f32 v1, v1, v149
	ds_write_b16 v82, v1 offset:5168
	v_mul_f32_e32 v1, v45, v69
	v_cvt_pk_bf16_f32 v1, v1, v149
	v_rcp_f32_e32 v70, v70
	ds_write_b16 v82, v1 offset:5232
	v_mul_f32_e32 v1, v29, v69
	v_cvt_pk_bf16_f32 v1, v1, v149
	ds_write_b16 v82, v1 offset:5296
	v_mul_f32_e32 v1, v13, v69
	v_cvt_pk_bf16_f32 v1, v1, v149
	ds_write_b16 v82, v1 offset:5360
	v_mul_f32_e32 v1, v62, v70
	v_cvt_pk_bf16_f32 v1, v1, v149
	ds_write_b16 v82, v1 offset:6528
	v_mul_f32_e32 v1, v46, v70
	v_cvt_pk_bf16_f32 v1, v1, v149
	v_rcp_f32_e32 v71, v71
	ds_write_b16 v82, v1 offset:6592
	v_mul_f32_e32 v1, v30, v70
	v_cvt_pk_bf16_f32 v1, v1, v149
	ds_write_b16 v82, v1 offset:6656
	v_mul_f32_e32 v1, v14, v70
	v_cvt_pk_bf16_f32 v1, v1, v149
	ds_write_b16 v82, v1 offset:6720
	v_mul_f32_e32 v1, v63, v71
	v_cvt_pk_bf16_f32 v1, v1, v149
	ds_write_b16 v82, v1 offset:6800
	v_mul_f32_e32 v1, v47, v71
	v_cvt_pk_bf16_f32 v1, v1, v149
	v_rcp_f32_e32 v72, v72
	ds_write_b16 v82, v1 offset:6864
	v_mul_f32_e32 v1, v31, v71
	v_cvt_pk_bf16_f32 v1, v1, v149
	ds_write_b16 v82, v1 offset:6928
	v_mul_f32_e32 v1, v15, v71
	v_cvt_pk_bf16_f32 v1, v1, v149
	ds_write_b16 v82, v1 offset:6992
	v_mul_f32_e32 v1, v64, v72
	v_cvt_pk_bf16_f32 v1, v1, v149
	ds_write_b16 v82, v1 offset:7072
	v_mul_f32_e32 v1, v48, v72
	v_cvt_pk_bf16_f32 v1, v1, v149
	v_rcp_f32_e32 v73, v73
	ds_write_b16 v82, v1 offset:7136
	v_mul_f32_e32 v1, v32, v72
	v_cvt_pk_bf16_f32 v1, v1, v149
	ds_write_b16 v82, v1 offset:7200
	v_mul_f32_e32 v1, v16, v72
	v_cvt_pk_bf16_f32 v1, v1, v149
	ds_write_b16 v82, v1 offset:7264
	v_mul_f32_e32 v1, v65, v73
	v_cvt_pk_bf16_f32 v1, v1, v149
	ds_write_b16 v82, v1 offset:7344
	v_mul_f32_e32 v1, v49, v73
	v_cvt_pk_bf16_f32 v1, v1, v149
	ds_write_b16 v82, v1 offset:7408
	v_mul_f32_e32 v1, v33, v73
	v_cvt_pk_bf16_f32 v1, v1, v149
	ds_write_b16 v82, v1 offset:7472
	v_mul_f32_e32 v1, v17, v73
	v_cvt_pk_bf16_f32 v1, v1, v149
	ds_write_b16 v82, v1 offset:7536
	v_lshrrev_b32_e32 v1, 4, v159
	v_lshlrev_b32_e32 v2, 4, v157
	v_or_b32_e32 v8, v158, v1
	v_and_b32_e32 v148, 0xf0, v2
	v_mul_u32_u24_e32 v1, 0x110, v1
	s_waitcnt lgkmcnt(0)
	v_add3_u32 v1, v81, v1, v148
	v_mov_b64_e32 v[6:7], s[58:59]
	ds_read_b128 v[2:5], v1
	v_mad_i64_i32 v[6:7], s[0:1], v8, s76, v[6:7]
	v_lshl_add_u64 v[10:11], v[6:7], 0, v[148:149]
	ds_read_b128 v[6:9], v1 offset:1088
	s_waitcnt lgkmcnt(1)
	global_store_dwordx4 v[10:11], v[2:5], off sc1
	s_add_i32 s89, s89, s72
	s_add_i32 s47, s47, s60
	v_add_co_u32_e32 v2, vcc, s83, v10
	s_add_i32 s88, s88, s72
	s_nop 0
	v_addc_co_u32_e32 v3, vcc, 0, v11, vcc
	s_waitcnt lgkmcnt(0)
	global_store_dwordx4 v[2:3], v[6:9], off offset:2048 sc1
	ds_read_b128 v[2:5], v1 offset:2176
	ds_read_b128 v[6:9], v1 offset:3264
	v_add_co_u32_e32 v12, vcc, s84, v10
	s_cmpk_lt_i32 s89, 0x400
	s_nop 0
	v_addc_co_u32_e32 v13, vcc, 0, v11, vcc
	s_waitcnt lgkmcnt(1)
	global_store_dwordx4 v[12:13], v[2:5], off sc1
	s_nop 1
	v_add_co_u32_e32 v2, vcc, s85, v10
	s_nop 1
	v_addc_co_u32_e32 v3, vcc, 0, v11, vcc
	s_waitcnt lgkmcnt(0)
	global_store_dwordx4 v[2:3], v[6:9], off offset:2048 sc1
	ds_read_b128 v[2:5], v1 offset:4352
	ds_read_b128 v[6:9], v1 offset:5440
	v_add_co_u32_e32 v12, vcc, s86, v10
	s_nop 1
	v_addc_co_u32_e32 v13, vcc, 0, v11, vcc
	s_waitcnt lgkmcnt(1)
	global_store_dwordx4 v[12:13], v[2:5], off sc1
	s_nop 1
	v_add_co_u32_e32 v2, vcc, s87, v10
	s_nop 1
	v_addc_co_u32_e32 v3, vcc, 0, v11, vcc
	s_waitcnt lgkmcnt(0)
	global_store_dwordx4 v[2:3], v[6:9], off offset:2048 sc1
	ds_read_b128 v[2:5], v1 offset:6528
	ds_read_b128 v[6:9], v1 offset:7616
	v_add_co_u32_e32 v12, vcc, 0x2d000, v10
	s_nop 1
	v_addc_co_u32_e32 v13, vcc, 0, v11, vcc
	s_waitcnt lgkmcnt(1)
	global_store_dwordx4 v[12:13], v[2:5], off sc1
	s_nop 1
	v_add_co_u32_e32 v2, vcc, 0x34000, v10
	s_nop 1
	v_addc_co_u32_e32 v3, vcc, 0, v11, vcc
	s_waitcnt lgkmcnt(0)
	global_store_dwordx4 v[2:3], v[6:9], off offset:2048 sc1
	s_cbranch_scc0 .LBB0_606

.LBB0_696:
	ds_read_b128 v[82:85], v208
	ds_read_b128 v[86:89], v208 offset:1024
	ds_read_b128 v[94:97], v208 offset:2048
	ds_read_b128 v[102:105], v208 offset:3072
	s_add_u32 s8, s2, 0x100
	s_addc_u32 s9, s3, 0
	s_cmp_eq_u32 s68, 28
	s_cselect_b32 s31, s25, s9
	s_cselect_b32 s30, s24, s8
	s_cselect_b32 s29, s1, s63
	s_cselect_b32 s28, s23, s53
	v_lshl_add_u64 v[182:183], s[2:3], 0, v[170:171]
	s_add_i32 m0, s41, 0xc000
	ds_read_b128 v[146:149], v209
	ds_read_b128 v[150:153], v209 offset:1024
	ds_read_b128 v[154:157], v209 offset:2048
	ds_read_b128 v[158:161], v209 offset:3072
	ds_read_b128 v[178:181], v209 offset:4096
	ds_read_b128 v[186:189], v209 offset:5120
	ds_read_b128 v[190:193], v209 offset:6144
	ds_read_b128 v[194:197], v209 offset:7168
	global_load_lds_dwordx4 v[182:183], off
	v_lshl_add_u64 v[182:183], s[2:3], 0, v[172:173]
	s_add_i32 m0, s41, 0xe000
	s_nop 0
	global_load_lds_dwordx4 v[182:183], off
	ds_read_b128 v[198:201], v210
	ds_read_b128 v[202:205], v210 offset:1024
	ds_read_b128 v[212:215], v210 offset:2048
	ds_read_b128 v[216:219], v210 offset:3072
	s_waitcnt vmcnt(8)
	s_waitcnt lgkmcnt(0)
	s_barrier
	s_setprio 1
	v_mfma_f32_16x16x32_bf16 v[142:145], v[82:85], v[146:149], v[142:145]
	v_mfma_f32_16x16x32_bf16 v[138:141], v[94:97], v[146:149], v[138:141]
	v_mfma_f32_16x16x32_bf16 v[126:129], v[82:85], v[154:157], v[126:129]
	v_mfma_f32_16x16x32_bf16 v[122:125], v[94:97], v[154:157], v[122:125]
	v_mfma_f32_16x16x32_bf16 v[110:113], v[82:85], v[178:181], v[110:113]
	v_mfma_f32_16x16x32_bf16 v[106:109], v[94:97], v[178:181], v[106:109]
	v_mfma_f32_16x16x32_bf16 v[78:81], v[82:85], v[190:193], v[78:81]
	v_mfma_f32_16x16x32_bf16 v[74:77], v[94:97], v[190:193], v[74:77]
	v_mfma_f32_16x16x32_bf16 v[142:145], v[86:89], v[150:153], v[142:145]
	v_mfma_f32_16x16x32_bf16 v[138:141], v[102:105], v[150:153], v[138:141]
	v_mfma_f32_16x16x32_bf16 v[126:129], v[86:89], v[158:161], v[126:129]
	v_mfma_f32_16x16x32_bf16 v[122:125], v[102:105], v[158:161], v[122:125]
	v_mfma_f32_16x16x32_bf16 v[110:113], v[86:89], v[186:189], v[110:113]
	v_mfma_f32_16x16x32_bf16 v[106:109], v[102:105], v[186:189], v[106:109]
	v_mfma_f32_16x16x32_bf16 v[78:81], v[86:89], v[194:197], v[78:81]
	v_mfma_f32_16x16x32_bf16 v[74:77], v[102:105], v[194:197], v[74:77]
	v_mfma_f32_16x16x32_bf16 v[134:137], v[198:201], v[146:149], v[134:137]
	v_mfma_f32_16x16x32_bf16 v[130:133], v[212:215], v[146:149], v[130:133]
	v_mfma_f32_16x16x32_bf16 v[118:121], v[198:201], v[154:157], v[118:121]
	v_mfma_f32_16x16x32_bf16 v[114:117], v[212:215], v[154:157], v[114:117]
	v_mfma_f32_16x16x32_bf16 v[98:101], v[198:201], v[178:181], v[98:101]
	v_mfma_f32_16x16x32_bf16 v[90:93], v[212:215], v[178:181], v[90:93]
	v_mfma_f32_16x16x32_bf16 v[70:73], v[198:201], v[190:193], v[70:73]
	v_mfma_f32_16x16x32_bf16 v[66:69], v[212:215], v[190:193], v[66:69]
	v_mfma_f32_16x16x32_bf16 v[134:137], v[202:205], v[150:153], v[134:137]
	v_mfma_f32_16x16x32_bf16 v[130:133], v[216:219], v[150:153], v[130:133]
	v_mfma_f32_16x16x32_bf16 v[118:121], v[202:205], v[158:161], v[118:121]
	v_mfma_f32_16x16x32_bf16 v[114:117], v[216:219], v[158:161], v[114:117]
	v_mfma_f32_16x16x32_bf16 v[98:101], v[202:205], v[186:189], v[98:101]
	v_mfma_f32_16x16x32_bf16 v[90:93], v[216:219], v[186:189], v[90:93]
	v_mfma_f32_16x16x32_bf16 v[70:73], v[202:205], v[194:197], v[70:73]
	v_mfma_f32_16x16x32_bf16 v[66:69], v[216:219], v[194:197], v[66:69]
	s_setprio 0
	s_barrier
	s_add_i32 s2, s59, s37
	v_lshl_add_u64 v[182:183], s[28:29], 0, v[164:165]
	s_mov_b32 m0, s2
	global_load_lds_dwordx4 v[182:183], off
	v_lshl_add_u64 v[220:221], s[28:29], 0, v[168:169]
	s_add_i32 m0, s2, 0x2000
	s_nop 0
	global_load_lds_dwordx4 v[220:221], off
	s_mov_b32 m0, s41
	v_lshl_add_u64 v[222:223], s[30:31], 0, v[162:163]
	ds_read_b128 v[146:149], v209 offset:16384
	ds_read_b128 v[150:153], v209 offset:17408
	ds_read_b128 v[154:157], v209 offset:18432
	ds_read_b128 v[158:161], v209 offset:19456
	ds_read_b128 v[178:181], v209 offset:20480
	ds_read_b128 v[186:189], v209 offset:21504
	ds_read_b128 v[190:193], v209 offset:22528
	ds_read_b128 v[194:197], v209 offset:23552
	global_load_lds_dwordx4 v[222:223], off
	v_lshl_add_u64 v[224:225], s[30:31], 0, v[166:167]
	s_mov_b32 m0, s42
	s_nop 0
	global_load_lds_dwordx4 v[224:225], off
	s_waitcnt vmcnt(6)
	s_waitcnt lgkmcnt(0)
	s_barrier
	s_setprio 1
	v_mfma_f32_16x16x32_bf16 v[62:65], v[82:85], v[146:149], v[62:65]
	v_mfma_f32_16x16x32_bf16 v[58:61], v[94:97], v[146:149], v[58:61]
	v_mfma_f32_16x16x32_bf16 v[46:49], v[82:85], v[154:157], v[46:49]
	v_mfma_f32_16x16x32_bf16 v[42:45], v[94:97], v[154:157], v[42:45]
	v_mfma_f32_16x16x32_bf16 v[30:33], v[82:85], v[178:181], v[30:33]
	v_mfma_f32_16x16x32_bf16 v[26:29], v[94:97], v[178:181], v[26:29]
	v_mfma_f32_16x16x32_bf16 v[14:17], v[82:85], v[190:193], v[14:17]
	v_mfma_f32_16x16x32_bf16 v[10:13], v[94:97], v[190:193], v[10:13]
	v_mfma_f32_16x16x32_bf16 v[62:65], v[86:89], v[150:153], v[62:65]
	v_mfma_f32_16x16x32_bf16 v[58:61], v[102:105], v[150:153], v[58:61]
	v_mfma_f32_16x16x32_bf16 v[46:49], v[86:89], v[158:161], v[46:49]
	v_mfma_f32_16x16x32_bf16 v[42:45], v[102:105], v[158:161], v[42:45]
	v_mfma_f32_16x16x32_bf16 v[30:33], v[86:89], v[186:189], v[30:33]
	v_mfma_f32_16x16x32_bf16 v[26:29], v[102:105], v[186:189], v[26:29]
	v_mfma_f32_16x16x32_bf16 v[14:17], v[86:89], v[194:197], v[14:17]
	v_mfma_f32_16x16x32_bf16 v[10:13], v[102:105], v[194:197], v[10:13]
	v_mfma_f32_16x16x32_bf16 v[54:57], v[198:201], v[146:149], v[54:57]
	v_mfma_f32_16x16x32_bf16 v[50:53], v[212:215], v[146:149], v[50:53]
	v_mfma_f32_16x16x32_bf16 v[38:41], v[198:201], v[154:157], v[38:41]
	v_mfma_f32_16x16x32_bf16 v[34:37], v[212:215], v[154:157], v[34:37]
	v_mfma_f32_16x16x32_bf16 v[22:25], v[198:201], v[178:181], v[22:25]
	v_mfma_f32_16x16x32_bf16 v[18:21], v[212:215], v[178:181], v[18:21]
	v_mfma_f32_16x16x32_bf16 v[6:9], v[198:201], v[190:193], v[6:9]
	v_mfma_f32_16x16x32_bf16 v[2:5], v[212:215], v[190:193], v[2:5]
	v_mfma_f32_16x16x32_bf16 v[54:57], v[202:205], v[150:153], v[54:57]
	v_mfma_f32_16x16x32_bf16 v[50:53], v[216:219], v[150:153], v[50:53]
	v_mfma_f32_16x16x32_bf16 v[38:41], v[202:205], v[158:161], v[38:41]
	v_mfma_f32_16x16x32_bf16 v[34:37], v[216:219], v[158:161], v[34:37]
	v_mfma_f32_16x16x32_bf16 v[22:25], v[202:205], v[186:189], v[22:25]
	v_mfma_f32_16x16x32_bf16 v[18:21], v[216:219], v[186:189], v[18:21]
	v_mfma_f32_16x16x32_bf16 v[6:9], v[202:205], v[194:197], v[6:9]
	v_mfma_f32_16x16x32_bf16 v[2:5], v[216:219], v[194:197], v[2:5]
	s_setprio 0
	s_barrier
	s_add_u32 s2, s28, 0x80000
	s_addc_u32 s3, s29, 0
	s_add_i32 s69, s60, s37
	v_lshl_add_u64 v[82:83], s[2:3], 0, v[164:165]
	s_mov_b32 m0, s69
	s_nop 0
	global_load_lds_dwordx4 v[82:83], off
	v_lshl_add_u64 v[82:83], s[2:3], 0, v[168:169]
	s_add_i32 m0, s69, 0x2000
	s_nop 0
	global_load_lds_dwordx4 v[82:83], off
	s_add_i32 s69, 0, 0x18000
	v_add_u32_e32 v102, s69, v206
	ds_read_b128 v[82:85], v102
	ds_read_b128 v[86:89], v102 offset:1024
	ds_read_b128 v[94:97], v102 offset:2048
	ds_read_b128 v[102:105], v102 offset:3072
	s_add_u32 s2, s30, 0xf0000
	s_addc_u32 s3, s31, 0
	s_mov_b32 m0, s43
	v_lshl_add_u64 v[198:199], s[2:3], 0, v[162:163]
	ds_read_b128 v[146:149], v209 offset:32768
	ds_read_b128 v[150:153], v209 offset:33792
	ds_read_b128 v[154:157], v209 offset:34816
	ds_read_b128 v[158:161], v209 offset:35840
	ds_read_b128 v[178:181], v209 offset:36864
	ds_read_b128 v[186:189], v209 offset:37888
	ds_read_b128 v[190:193], v209 offset:38912
	ds_read_b128 v[194:197], v209 offset:39936
	global_load_lds_dwordx4 v[198:199], off
	v_lshl_add_u64 v[198:199], s[2:3], 0, v[166:167]
	s_mov_b32 m0, s44
	s_nop 0
	global_load_lds_dwordx4 v[198:199], off
	v_add_u32_e32 v216, 0x1c000, v206
	ds_read_b128 v[198:201], v216
	ds_read_b128 v[202:205], v216 offset:1024
	ds_read_b128 v[212:215], v216 offset:2048
	ds_read_b128 v[216:219], v216 offset:3072
	s_waitcnt vmcnt(8)
	s_waitcnt lgkmcnt(0)
	s_barrier
	s_setprio 1
	v_mfma_f32_16x16x32_bf16 v[142:145], v[82:85], v[146:149], v[142:145]
	v_mfma_f32_16x16x32_bf16 v[138:141], v[94:97], v[146:149], v[138:141]
	v_mfma_f32_16x16x32_bf16 v[126:129], v[82:85], v[154:157], v[126:129]
	v_mfma_f32_16x16x32_bf16 v[122:125], v[94:97], v[154:157], v[122:125]
	v_mfma_f32_16x16x32_bf16 v[110:113], v[82:85], v[178:181], v[110:113]
	v_mfma_f32_16x16x32_bf16 v[106:109], v[94:97], v[178:181], v[106:109]
	v_mfma_f32_16x16x32_bf16 v[78:81], v[82:85], v[190:193], v[78:81]
	v_mfma_f32_16x16x32_bf16 v[74:77], v[94:97], v[190:193], v[74:77]
	v_mfma_f32_16x16x32_bf16 v[142:145], v[86:89], v[150:153], v[142:145]
	v_mfma_f32_16x16x32_bf16 v[138:141], v[102:105], v[150:153], v[138:141]
	v_mfma_f32_16x16x32_bf16 v[126:129], v[86:89], v[158:161], v[126:129]
	v_mfma_f32_16x16x32_bf16 v[122:125], v[102:105], v[158:161], v[122:125]
	v_mfma_f32_16x16x32_bf16 v[110:113], v[86:89], v[186:189], v[110:113]
	v_mfma_f32_16x16x32_bf16 v[106:109], v[102:105], v[186:189], v[106:109]
	v_mfma_f32_16x16x32_bf16 v[78:81], v[86:89], v[194:197], v[78:81]
	v_mfma_f32_16x16x32_bf16 v[74:77], v[102:105], v[194:197], v[74:77]
	v_mfma_f32_16x16x32_bf16 v[134:137], v[198:201], v[146:149], v[134:137]
	v_mfma_f32_16x16x32_bf16 v[130:133], v[212:215], v[146:149], v[130:133]
	v_mfma_f32_16x16x32_bf16 v[118:121], v[198:201], v[154:157], v[118:121]
	v_mfma_f32_16x16x32_bf16 v[114:117], v[212:215], v[154:157], v[114:117]
	v_mfma_f32_16x16x32_bf16 v[98:101], v[198:201], v[178:181], v[98:101]
	v_mfma_f32_16x16x32_bf16 v[90:93], v[212:215], v[178:181], v[90:93]
	v_mfma_f32_16x16x32_bf16 v[70:73], v[198:201], v[190:193], v[70:73]
	v_mfma_f32_16x16x32_bf16 v[66:69], v[212:215], v[190:193], v[66:69]
	v_mfma_f32_16x16x32_bf16 v[134:137], v[202:205], v[150:153], v[134:137]
	v_mfma_f32_16x16x32_bf16 v[130:133], v[216:219], v[150:153], v[130:133]
	v_mfma_f32_16x16x32_bf16 v[118:121], v[202:205], v[158:161], v[118:121]
	v_mfma_f32_16x16x32_bf16 v[114:117], v[216:219], v[158:161], v[114:117]
	v_mfma_f32_16x16x32_bf16 v[98:101], v[202:205], v[186:189], v[98:101]
	v_mfma_f32_16x16x32_bf16 v[90:93], v[216:219], v[186:189], v[90:93]
	v_mfma_f32_16x16x32_bf16 v[70:73], v[202:205], v[194:197], v[70:73]
	v_mfma_f32_16x16x32_bf16 v[66:69], v[216:219], v[194:197], v[66:69]
	s_setprio 0
	s_barrier
	s_add_i32 s30, 0, 0x1c000
	s_add_i32 s2, s69, s37
	v_lshl_add_u64 v[182:183], v[182:183], 0, s[20:21]
	s_mov_b32 m0, s2
	global_load_lds_dwordx4 v[182:183], off
	v_lshl_add_u64 v[182:183], v[220:221], 0, s[20:21]
	s_add_i32 m0, s2, 0x2000
	s_nop 0
	global_load_lds_dwordx4 v[182:183], off
	s_mov_b32 m0, s47
	v_lshl_add_u64 v[182:183], v[222:223], 0, s[20:21]
	ds_read_b128 v[146:149], v209 offset:49152
	ds_read_b128 v[150:153], v209 offset:50176
	ds_read_b128 v[154:157], v209 offset:51200
	ds_read_b128 v[158:161], v209 offset:52224
	ds_read_b128 v[178:181], v209 offset:53248
	ds_read_b128 v[186:189], v209 offset:54272
	ds_read_b128 v[190:193], v209 offset:55296
	ds_read_b128 v[194:197], v209 offset:56320
	global_load_lds_dwordx4 v[182:183], off
	v_lshl_add_u64 v[182:183], v[224:225], 0, s[20:21]
	s_mov_b32 m0, s48
	s_nop 0
	global_load_lds_dwordx4 v[182:183], off
	s_add_u32 s2, s28, 0x80080
	s_addc_u32 s3, s29, 0
	s_add_i32 s28, s30, s37
	v_lshl_add_u64 v[182:183], s[2:3], 0, v[164:165]
	s_mov_b32 m0, s28
	s_nop 0
	global_load_lds_dwordx4 v[182:183], off
	v_lshl_add_u64 v[182:183], s[2:3], 0, v[168:169]
	s_add_i32 m0, s28, 0x2000
	s_nop 0
	global_load_lds_dwordx4 v[182:183], off
	s_waitcnt vmcnt(8)
	s_waitcnt lgkmcnt(0)
	s_barrier
	s_setprio 1
	v_mfma_f32_16x16x32_bf16 v[62:65], v[82:85], v[146:149], v[62:65]
	v_mfma_f32_16x16x32_bf16 v[58:61], v[94:97], v[146:149], v[58:61]
	v_mfma_f32_16x16x32_bf16 v[46:49], v[82:85], v[154:157], v[46:49]
	v_mfma_f32_16x16x32_bf16 v[42:45], v[94:97], v[154:157], v[42:45]
	v_mfma_f32_16x16x32_bf16 v[30:33], v[82:85], v[178:181], v[30:33]
	v_mfma_f32_16x16x32_bf16 v[26:29], v[94:97], v[178:181], v[26:29]
	v_mfma_f32_16x16x32_bf16 v[14:17], v[82:85], v[190:193], v[14:17]
	v_mfma_f32_16x16x32_bf16 v[10:13], v[94:97], v[190:193], v[10:13]
	v_mfma_f32_16x16x32_bf16 v[62:65], v[86:89], v[150:153], v[62:65]
	v_mfma_f32_16x16x32_bf16 v[58:61], v[102:105], v[150:153], v[58:61]
	v_mfma_f32_16x16x32_bf16 v[46:49], v[86:89], v[158:161], v[46:49]
	v_mfma_f32_16x16x32_bf16 v[42:45], v[102:105], v[158:161], v[42:45]
	v_mfma_f32_16x16x32_bf16 v[30:33], v[86:89], v[186:189], v[30:33]
	v_mfma_f32_16x16x32_bf16 v[26:29], v[102:105], v[186:189], v[26:29]
	v_mfma_f32_16x16x32_bf16 v[14:17], v[86:89], v[194:197], v[14:17]
	v_mfma_f32_16x16x32_bf16 v[10:13], v[102:105], v[194:197], v[10:13]
	v_mfma_f32_16x16x32_bf16 v[54:57], v[198:201], v[146:149], v[54:57]
	v_mfma_f32_16x16x32_bf16 v[50:53], v[212:215], v[146:149], v[50:53]
	v_mfma_f32_16x16x32_bf16 v[38:41], v[198:201], v[154:157], v[38:41]
	v_mfma_f32_16x16x32_bf16 v[34:37], v[212:215], v[154:157], v[34:37]
	v_mfma_f32_16x16x32_bf16 v[22:25], v[198:201], v[178:181], v[22:25]
	v_mfma_f32_16x16x32_bf16 v[18:21], v[212:215], v[178:181], v[18:21]
	v_mfma_f32_16x16x32_bf16 v[6:9], v[198:201], v[190:193], v[6:9]
	v_mfma_f32_16x16x32_bf16 v[2:5], v[212:215], v[190:193], v[2:5]
	v_mfma_f32_16x16x32_bf16 v[54:57], v[202:205], v[150:153], v[54:57]
	v_mfma_f32_16x16x32_bf16 v[50:53], v[216:219], v[150:153], v[50:53]
	v_mfma_f32_16x16x32_bf16 v[38:41], v[202:205], v[158:161], v[38:41]
	v_mfma_f32_16x16x32_bf16 v[34:37], v[216:219], v[158:161], v[34:37]
	v_mfma_f32_16x16x32_bf16 v[22:25], v[202:205], v[186:189], v[22:25]
	v_mfma_f32_16x16x32_bf16 v[18:21], v[216:219], v[186:189], v[18:21]
	v_mfma_f32_16x16x32_bf16 v[6:9], v[202:205], v[194:197], v[6:9]
	v_mfma_f32_16x16x32_bf16 v[2:5], v[216:219], v[194:197], v[2:5]
	s_setprio 0
	s_add_i32 s68, s68, 2
	s_add_u32 s53, s53, 0x100
	s_addc_u32 s63, s63, 0
	s_cmp_gt_u32 s68, 29
	s_mov_b64 s[2:3], s[8:9]
	s_barrier
	s_cbranch_scc0 .LBB0_696
	s_min_i32 s1, s52, 64
	s_ashr_i32 s1, s1, 3
	v_lshl_or_b32 v178, s0, 8, v207
	s_mul_hi_i32 s2, s1, 0xc000
	s_mul_i32 s1, s1, 0xc000
	s_add_u32 s0, s10, s1
	v_ashrrev_i32_e32 v179, 31, v178
	s_addc_u32 s1, s11, s2
	v_lshlrev_b64 v[198:199], 2, v[178:179]
	v_lshl_add_u32 v200, s52, 8, v1
	v_lshl_add_u64 v[82:83], s[0:1], 0, v[198:199]
	v_add_u32_e32 v94, 0xffffc000, v200
	v_ashrrev_i32_e32 v201, 31, v200
	v_cmp_gt_i32_e64 s[0:1], s46, v200
	v_add_co_u32_e32 v84, vcc, s46, v82
	s_nop 0
	v_cndmask_b32_e64 v95, 0, v201, s[0:1]
	v_cndmask_b32_e64 v94, v94, v200, s[0:1]
	v_mov_b32_e32 v152, s15
	v_mov_b32_e32 v153, s13
	v_mov_b32_e32 v154, s14
	v_mov_b32_e32 v155, s12
	v_addc_co_u32_e32 v85, vcc, 0, v83, vcc
	v_cndmask_b32_e64 v97, v152, v153, s[0:1]
	v_cndmask_b32_e64 v96, v154, v155, s[0:1]
	v_lshlrev_b64 v[94:95], 13, v[94:95]
	v_add_co_u32_e32 v82, vcc, s49, v82
	v_lshl_add_u64 v[94:95], v[96:97], 0, v[94:95]
	v_lshl_add_u64 v[146:147], v[94:95], 0, v[198:199]
	v_addc_co_u32_e32 v83, vcc, 0, v83, vcc
	global_load_dwordx4 v[86:89], v[84:85], off
	global_load_dwordx4 v[180:183], v[146:147], off
	global_load_dwordx4 v[186:189], v[82:83], off
	global_load_dwordx4 v[190:193], v[82:83], off offset:64
	global_load_dwordx4 v[194:197], v[82:83], off offset:512
	global_load_dwordx4 v[212:215], v[82:83], off offset:576
	v_lshl_add_u64 v[82:83], s[56:57], 0, v[198:199]
	global_load_dwordx4 v[216:219], v[82:83], off
	global_load_dwordx4 v[220:223], v[82:83], off offset:64
	global_load_dwordx4 v[224:227], v[82:83], off offset:512
	global_load_dwordx4 v[228:231], v[82:83], off offset:576
	global_load_dwordx4 v[232:235], v[146:147], off offset:64
	global_load_dwordx4 v[102:105], v[84:85], off offset:64
	global_load_dwordx4 v[94:97], v[84:85], off offset:512
	global_load_dwordx4 v[236:239], v[146:147], off offset:512
	global_load_dwordx4 v[240:243], v[146:147], off offset:576
	s_nop 0
	global_load_dwordx4 v[82:85], v[84:85], off offset:576
	v_or_b32_e32 v202, 16, v200
	v_add_u32_e32 v150, 0xffffc010, v200
	v_ashrrev_i32_e32 v203, 31, v202
	v_cmp_gt_i32_e32 vcc, s46, v202
	v_lshlrev_b64 v[146:147], 13, v[200:201]
	v_lshl_add_u64 v[146:147], s[66:67], 0, v[146:147]
	v_cndmask_b32_e32 v151, 0, v203, vcc
	v_cndmask_b32_e32 v150, v150, v202, vcc
	v_cndmask_b32_e32 v153, v152, v153, vcc
	v_cndmask_b32_e32 v152, v154, v155, vcc
	v_lshlrev_b64 v[150:151], 13, v[150:151]
	v_lshlrev_b64 v[148:149], 12, v[200:201]
	v_lshl_add_u64 v[204:205], v[146:147], 0, v[198:199]
	v_lshl_add_u64 v[146:147], v[152:153], 0, v[150:151]
	v_lshl_add_u64 v[148:149], s[88:89], 0, v[148:149]
	v_lshl_add_u64 v[146:147], v[146:147], 0, v[198:199]
	v_lshl_add_u64 v[244:245], v[178:179], 1, v[148:149]
	global_load_dwordx4 v[158:161], v[146:147], off
	global_load_dwordx4 v[154:157], v[146:147], off offset:64
	global_load_dwordx4 v[150:153], v[146:147], off offset:512
	s_nop 0
	global_load_dwordx4 v[146:149], v[146:147], off offset:576
	s_waitcnt vmcnt(0)
	v_pk_fma_f32 v[138:139], v[138:139], v[102:103], v[232:233]
	v_pk_fma_f32 v[144:145], v[144:145], v[88:89], v[182:183]
	v_pk_fma_f32 v[142:143], v[142:143], v[86:87], v[180:181]
	v_pk_add_f32 v[180:181], v[188:189], 1.0 op_sel_hi:[1,0]
	v_pk_add_f32 v[182:183], v[186:187], 1.0 op_sel_hi:[1,0]
	v_pk_add_f32 v[212:213], v[212:213], 1.0 op_sel_hi:[1,0]
	v_pk_add_f32 v[246:247], v[196:197], 1.0 op_sel_hi:[1,0]
	v_pk_add_f32 v[248:249], v[194:195], 1.0 op_sel_hi:[1,0]
	v_pk_mul_f32 v[194:195], v[218:219], v[180:181]
	v_pk_mul_f32 v[196:197], v[216:217], v[182:183]
	v_pk_mul_f32 v[180:181], v[228:229], v[212:213]
	v_mul_f32_e32 v212, v143, v143
	global_store_dwordx4 v[204:205], v[142:145], off sc1
	v_fmac_f32_e32 v212, v142, v142
	v_pk_add_f32 v[188:189], v[190:191], 1.0 op_sel_hi:[1,0]
	v_pk_mul_f32 v[142:143], v[196:197], v[142:143]
	v_fmac_f32_e32 v212, v144, v144
	v_cvt_pk_bf16_f32 v142, v142, v143
	v_pk_add_f32 v[186:187], v[192:193], 1.0 op_sel_hi:[1,0]
	v_pk_mul_f32 v[192:193], v[220:221], v[188:189]
	v_fmac_f32_e32 v212, v145, v145
	v_pk_mul_f32 v[144:145], v[194:195], v[144:145]
	v_pk_fma_f32 v[140:141], v[140:141], v[104:105], v[234:235]
	v_cvt_pk_bf16_f32 v143, v144, v145
	global_store_dwordx2 v[244:245], v[142:143], off
	v_mul_f32_e32 v142, v139, v139
	global_store_dwordx4 v[204:205], v[138:141], off offset:64 sc1
	v_fmac_f32_e32 v142, v138, v138
	v_pk_mul_f32 v[190:191], v[222:223], v[186:187]
	v_pk_mul_f32 v[138:139], v[192:193], v[138:139]
	v_fmac_f32_e32 v142, v140, v140
	v_cvt_pk_bf16_f32 v138, v138, v139
	v_pk_fma_f32 v[134:135], v[134:135], v[94:95], v[236:237]
	v_fmac_f32_e32 v142, v141, v141
	v_pk_mul_f32 v[140:141], v[190:191], v[140:141]
	v_pk_fma_f32 v[136:137], v[136:137], v[96:97], v[238:239]
	v_cvt_pk_bf16_f32 v139, v140, v141
	global_store_dwordx2 v[244:245], v[138:139], off offset:32
	v_mul_f32_e32 v138, v135, v135
	v_fmac_f32_e32 v138, v134, v134
	v_pk_mul_f32 v[188:189], v[224:225], v[248:249]
	v_fmac_f32_e32 v138, v136, v136
	v_add_f32_e32 v142, v212, v142
	global_store_dwordx4 v[204:205], v[134:137], off offset:512 sc1
	v_fmac_f32_e32 v138, v137, v137
	v_add_f32_e32 v139, v142, v138
	v_pk_mul_f32 v[134:135], v[188:189], v[134:135]
	v_pk_mul_f32 v[186:187], v[226:227], v[246:247]
	v_cvt_pk_bf16_f32 v138, v134, v135
	v_pk_fma_f32 v[134:135], v[132:133], v[84:85], v[242:243]
	v_pk_fma_f32 v[132:133], v[130:131], v[82:83], v[240:241]
	v_xor_b32_e32 v131, 16, v211
	v_mul_f32_e32 v130, v133, v133
	v_fmac_f32_e32 v130, v132, v132
	v_fmac_f32_e32 v130, v134, v134
	v_fmac_f32_e32 v130, v135, v135
	v_add_f32_e32 v130, v139, v130
	v_and_b32_e32 v139, 64, v211
	v_add_u32_e32 v140, 64, v139
	v_cmp_lt_i32_e32 vcc, v131, v140
	v_pk_add_f32 v[214:215], v[214:215], 1.0 op_sel_hi:[1,0]
	v_pk_mul_f32 v[136:137], v[186:187], v[136:137]
	v_cndmask_b32_e32 v131, v211, v131, vcc
	v_lshlrev_b32_e32 v212, 2, v131
	ds_bpermute_b32 v131, v212, v130
	v_cvt_pk_bf16_f32 v139, v136, v137
	v_pk_mul_f32 v[182:183], v[230:231], v[214:215]
	global_store_dwordx2 v[244:245], v[138:139], off offset:256
	global_store_dwordx4 v[204:205], v[132:135], off offset:576 sc1
	s_waitcnt lgkmcnt(0)
	v_add_f32_e32 v130, v130, v131
	v_xor_b32_e32 v131, 32, v211
	v_cmp_lt_i32_e32 vcc, v131, v140
	v_pk_mul_f32 v[132:133], v[180:181], v[132:133]
	v_pk_mul_f32 v[134:135], v[182:183], v[134:135]
	v_cndmask_b32_e32 v131, v211, v131, vcc
	v_lshlrev_b32_e32 v213, 2, v131
	ds_bpermute_b32 v131, v213, v130
	v_cvt_pk_bf16_f32 v132, v132, v133
	v_cvt_pk_bf16_f32 v133, v134, v135
	global_store_dwordx2 v[244:245], v[132:133], off offset:288
	s_and_saveexec_b64 s[0:1], s[4:5]
	s_cbranch_execz .LBB0_699
	v_lshl_add_u64 v[132:133], v[200:201], 2, s[18:19]
	s_waitcnt lgkmcnt(0)
	v_add_f32_e32 v130, v130, v131
	global_atomic_add_f32 v[132:133], v130, off
.LBB0_699:
	s_or_b64 exec, exec, s[0:1]
	v_or_b32_e32 v204, 32, v200
	v_ashrrev_i32_e32 v205, 31, v204
	v_add_u32_e32 v130, 0xffffc020, v200
	v_cmp_gt_i32_e32 vcc, s46, v204
	v_mov_b32_e32 v132, s15
	v_mov_b32_e32 v133, s13
	s_waitcnt lgkmcnt(0)
	v_cndmask_b32_e32 v131, 0, v205, vcc
	v_cndmask_b32_e32 v130, v130, v204, vcc
	v_cndmask_b32_e32 v133, v132, v133, vcc
	v_mov_b32_e32 v132, s14
	v_mov_b32_e32 v134, s12
	v_cndmask_b32_e32 v132, v132, v134, vcc
	v_lshlrev_b64 v[130:131], 13, v[130:131]
	v_lshl_add_u64 v[130:131], v[132:133], 0, v[130:131]
	v_lshl_add_u64 v[130:131], v[130:131], 0, v[198:199]
	global_load_dwordx4 v[142:145], v[130:131], off
	global_load_dwordx4 v[138:141], v[130:131], off offset:64
	global_load_dwordx4 v[134:137], v[130:131], off offset:512
	s_nop 0
	global_load_dwordx4 v[130:133], v[130:131], off offset:576
	v_lshlrev_b64 v[214:215], 13, v[202:203]
	v_lshl_add_u64 v[214:215], s[66:67], 0, v[214:215]
	v_pk_fma_f32 v[126:127], v[126:127], v[86:87], v[158:159]
	v_lshl_add_u64 v[214:215], v[214:215], 0, v[198:199]
	v_lshlrev_b64 v[216:217], 12, v[202:203]
	v_pk_fma_f32 v[128:129], v[128:129], v[88:89], v[160:161]
	v_mul_f32_e32 v158, v127, v127
	v_lshl_add_u64 v[216:217], s[88:89], 0, v[216:217]
	global_store_dwordx4 v[214:215], v[126:129], off sc1
	v_fmac_f32_e32 v158, v126, v126
	v_lshl_add_u64 v[216:217], v[178:179], 1, v[216:217]
	v_pk_mul_f32 v[126:127], v[196:197], v[126:127]
	v_fmac_f32_e32 v158, v128, v128
	v_cvt_pk_bf16_f32 v126, v126, v127
	v_pk_fma_f32 v[122:123], v[122:123], v[102:103], v[154:155]
	v_fmac_f32_e32 v158, v129, v129
	v_pk_mul_f32 v[128:129], v[194:195], v[128:129]
	v_pk_fma_f32 v[124:125], v[124:125], v[104:105], v[156:157]
	v_cvt_pk_bf16_f32 v127, v128, v129
	global_store_dwordx2 v[216:217], v[126:127], off
	v_mul_f32_e32 v126, v123, v123
	global_store_dwordx4 v[214:215], v[122:125], off offset:64 sc1
	v_fmac_f32_e32 v126, v122, v122
	v_fmac_f32_e32 v126, v124, v124
	v_pk_mul_f32 v[122:123], v[192:193], v[122:123]
	v_pk_fma_f32 v[118:119], v[118:119], v[94:95], v[150:151]
	v_cvt_pk_bf16_f32 v122, v122, v123
	v_fmac_f32_e32 v126, v125, v125
	v_pk_mul_f32 v[124:125], v[190:191], v[124:125]
	v_pk_fma_f32 v[120:121], v[120:121], v[96:97], v[152:153]
	v_cvt_pk_bf16_f32 v123, v124, v125
	global_store_dwordx2 v[216:217], v[122:123], off offset:32
	v_mul_f32_e32 v122, v119, v119
	v_fmac_f32_e32 v122, v118, v118
	v_fmac_f32_e32 v122, v120, v120
	v_add_f32_e32 v126, v158, v126
	global_store_dwordx4 v[214:215], v[118:121], off offset:512 sc1
	v_fmac_f32_e32 v122, v121, v121
	v_add_f32_e32 v123, v126, v122
	v_pk_mul_f32 v[118:119], v[188:189], v[118:119]
	v_pk_mul_f32 v[120:121], v[186:187], v[120:121]
	v_cvt_pk_bf16_f32 v122, v118, v119
	v_pk_fma_f32 v[118:119], v[116:117], v[84:85], v[148:149]
	v_pk_fma_f32 v[116:117], v[114:115], v[82:83], v[146:147]
	s_nop 0
	v_mul_f32_e32 v114, v117, v117
	v_fmac_f32_e32 v114, v116, v116
	v_fmac_f32_e32 v114, v118, v118
	v_fmac_f32_e32 v114, v119, v119
	v_add_f32_e32 v114, v123, v114
	ds_bpermute_b32 v115, v212, v114
	v_cvt_pk_bf16_f32 v123, v120, v121
	global_store_dwordx2 v[216:217], v[122:123], off offset:256
	global_store_dwordx4 v[214:215], v[116:119], off offset:576 sc1
	s_waitcnt lgkmcnt(0)
	v_add_f32_e32 v114, v114, v115
	ds_bpermute_b32 v115, v213, v114
	v_pk_mul_f32 v[116:117], v[180:181], v[116:117]
	v_pk_mul_f32 v[118:119], v[182:183], v[118:119]
	v_cvt_pk_bf16_f32 v116, v116, v117
	s_nop 0
	v_cvt_pk_bf16_f32 v117, v118, v119
	global_store_dwordx2 v[216:217], v[116:117], off offset:288
	s_and_saveexec_b64 s[0:1], s[4:5]
	s_cbranch_execz .LBB0_701
	v_lshl_add_u64 v[116:117], v[202:203], 2, s[18:19]
	s_waitcnt lgkmcnt(0)
	v_add_f32_e32 v114, v114, v115
	global_atomic_add_f32 v[116:117], v114, off
.LBB0_701:
	s_or_b64 exec, exec, s[0:1]
	v_or_b32_e32 v146, 48, v200
	v_ashrrev_i32_e32 v147, 31, v146
	v_add_u32_e32 v114, 0xffffc030, v200
	v_cmp_gt_i32_e32 vcc, s46, v146
	v_mov_b32_e32 v116, s15
	v_mov_b32_e32 v117, s13
	s_waitcnt lgkmcnt(0)
	v_cndmask_b32_e32 v115, 0, v147, vcc
	v_cndmask_b32_e32 v114, v114, v146, vcc
	v_cndmask_b32_e32 v117, v116, v117, vcc
	v_mov_b32_e32 v116, s14
	v_mov_b32_e32 v118, s12
	v_cndmask_b32_e32 v116, v116, v118, vcc
	v_lshlrev_b64 v[114:115], 13, v[114:115]
	v_lshl_add_u64 v[114:115], v[116:117], 0, v[114:115]
	v_lshl_add_u64 v[114:115], v[114:115], 0, v[198:199]
	global_load_dwordx4 v[126:129], v[114:115], off
	global_load_dwordx4 v[122:125], v[114:115], off offset:64
	global_load_dwordx4 v[118:121], v[114:115], off offset:512
	s_nop 0
	global_load_dwordx4 v[114:117], v[114:115], off offset:576
	v_lshlrev_b64 v[148:149], 13, v[204:205]
	v_lshl_add_u64 v[148:149], s[66:67], 0, v[148:149]
	s_waitcnt vmcnt(15)
	v_pk_fma_f32 v[110:111], v[110:111], v[86:87], v[142:143]
	v_lshl_add_u64 v[148:149], v[148:149], 0, v[198:199]
	v_lshlrev_b64 v[150:151], 12, v[204:205]
	v_pk_fma_f32 v[112:113], v[112:113], v[88:89], v[144:145]
	v_mul_f32_e32 v142, v111, v111
	v_lshl_add_u64 v[150:151], s[88:89], 0, v[150:151]
	global_store_dwordx4 v[148:149], v[110:113], off sc1
	v_fmac_f32_e32 v142, v110, v110
	v_lshl_add_u64 v[150:151], v[178:179], 1, v[150:151]
	v_pk_mul_f32 v[110:111], v[196:197], v[110:111]
	v_fmac_f32_e32 v142, v112, v112
	v_cvt_pk_bf16_f32 v110, v110, v111
	s_waitcnt vmcnt(15)
	v_pk_fma_f32 v[106:107], v[106:107], v[102:103], v[138:139]
	v_fmac_f32_e32 v142, v113, v113
	v_pk_mul_f32 v[112:113], v[194:195], v[112:113]
	v_pk_fma_f32 v[108:109], v[108:109], v[104:105], v[140:141]
	v_cvt_pk_bf16_f32 v111, v112, v113
	global_store_dwordx2 v[150:151], v[110:111], off
	v_mul_f32_e32 v110, v107, v107
	global_store_dwordx4 v[148:149], v[106:109], off offset:64 sc1
	v_fmac_f32_e32 v110, v106, v106
	v_fmac_f32_e32 v110, v108, v108
	v_pk_mul_f32 v[106:107], v[192:193], v[106:107]
	s_waitcnt vmcnt(16)
	v_pk_fma_f32 v[98:99], v[98:99], v[94:95], v[134:135]
	v_cvt_pk_bf16_f32 v106, v106, v107
	v_fmac_f32_e32 v110, v109, v109
	v_pk_mul_f32 v[108:109], v[190:191], v[108:109]
	v_pk_fma_f32 v[100:101], v[100:101], v[96:97], v[136:137]
	v_cvt_pk_bf16_f32 v107, v108, v109
	global_store_dwordx2 v[150:151], v[106:107], off offset:32
	v_mul_f32_e32 v106, v99, v99
	global_store_dwordx4 v[148:149], v[98:101], off offset:512 sc1
	v_fmac_f32_e32 v106, v98, v98
	v_fmac_f32_e32 v106, v100, v100
	v_pk_mul_f32 v[98:99], v[188:189], v[98:99]
	v_add_f32_e32 v110, v142, v110
	v_cvt_pk_bf16_f32 v108, v98, v99
	s_waitcnt vmcnt(17)
	v_pk_fma_f32 v[98:99], v[90:91], v[82:83], v[130:131]
	v_fmac_f32_e32 v106, v101, v101
	v_mul_f32_e32 v90, v99, v99
	v_add_f32_e32 v109, v110, v106
	v_pk_mul_f32 v[106:107], v[186:187], v[100:101]
	v_pk_fma_f32 v[100:101], v[92:93], v[84:85], v[132:133]
	v_fmac_f32_e32 v90, v98, v98
	v_fmac_f32_e32 v90, v100, v100
	v_fmac_f32_e32 v90, v101, v101
	v_add_f32_e32 v90, v109, v90
	ds_bpermute_b32 v91, v212, v90
	v_cvt_pk_bf16_f32 v109, v106, v107
	global_store_dwordx2 v[150:151], v[108:109], off offset:256
	global_store_dwordx4 v[148:149], v[98:101], off offset:576 sc1
	v_pk_mul_f32 v[92:93], v[182:183], v[100:101]
	s_waitcnt lgkmcnt(0)
	v_add_f32_e32 v90, v90, v91
	ds_bpermute_b32 v91, v213, v90
	v_pk_mul_f32 v[98:99], v[180:181], v[98:99]
	s_nop 0
	v_cvt_pk_bf16_f32 v98, v98, v99
	v_cvt_pk_bf16_f32 v99, v92, v93
	global_store_dwordx2 v[150:151], v[98:99], off offset:288
	s_and_saveexec_b64 s[0:1], s[4:5]
	s_cbranch_execz .LBB0_703
	v_lshl_add_u64 v[92:93], v[204:205], 2, s[18:19]
	s_waitcnt lgkmcnt(0)
	v_add_f32_e32 v90, v90, v91
	global_atomic_add_f32 v[92:93], v90, off
.LBB0_703:
	s_or_b64 exec, exec, s[0:1]
	v_add_u32_e32 v130, 0x80, v200
	v_ashrrev_i32_e32 v131, 31, v130
	v_add_u32_e32 v90, 0xffffc080, v200
	v_cmp_gt_i32_e32 vcc, s61, v200
	v_mov_b32_e32 v92, s15
	v_mov_b32_e32 v93, s13
	s_waitcnt lgkmcnt(0)
	v_cndmask_b32_e32 v91, 0, v131, vcc
	v_cndmask_b32_e32 v90, v90, v130, vcc
	v_cndmask_b32_e32 v93, v92, v93, vcc
	v_mov_b32_e32 v92, s14
	v_mov_b32_e32 v98, s12
	v_cndmask_b32_e32 v92, v92, v98, vcc
	v_lshlrev_b64 v[90:91], 13, v[90:91]
	v_lshl_add_u64 v[90:91], v[92:93], 0, v[90:91]
	v_lshl_add_u64 v[90:91], v[90:91], 0, v[198:199]
	global_load_dwordx4 v[110:113], v[90:91], off
	global_load_dwordx4 v[106:109], v[90:91], off offset:64
	global_load_dwordx4 v[98:101], v[90:91], off offset:512
	s_nop 0
	global_load_dwordx4 v[90:93], v[90:91], off offset:576
	v_lshlrev_b64 v[132:133], 13, v[146:147]
	v_lshl_add_u64 v[132:133], s[66:67], 0, v[132:133]
	s_waitcnt vmcnt(15)
	v_pk_fma_f32 v[78:79], v[78:79], v[86:87], v[126:127]
	v_lshl_add_u64 v[132:133], v[132:133], 0, v[198:199]
	v_lshlrev_b64 v[134:135], 12, v[146:147]
	v_pk_fma_f32 v[80:81], v[80:81], v[88:89], v[128:129]
	v_mul_f32_e32 v126, v79, v79
	v_lshl_add_u64 v[134:135], s[88:89], 0, v[134:135]
	global_store_dwordx4 v[132:133], v[78:81], off sc1
	v_fmac_f32_e32 v126, v78, v78
	v_lshl_add_u64 v[134:135], v[178:179], 1, v[134:135]
	v_pk_mul_f32 v[78:79], v[196:197], v[78:79]
	v_fmac_f32_e32 v126, v80, v80
	v_cvt_pk_bf16_f32 v78, v78, v79
	s_waitcnt vmcnt(15)
	v_pk_fma_f32 v[74:75], v[74:75], v[102:103], v[122:123]
	v_fmac_f32_e32 v126, v81, v81
	v_pk_mul_f32 v[80:81], v[194:195], v[80:81]
	v_pk_fma_f32 v[76:77], v[76:77], v[104:105], v[124:125]
	v_cvt_pk_bf16_f32 v79, v80, v81
	global_store_dwordx2 v[134:135], v[78:79], off
	v_mul_f32_e32 v78, v75, v75
	global_store_dwordx4 v[132:133], v[74:77], off offset:64 sc1
	v_fmac_f32_e32 v78, v74, v74
	v_fmac_f32_e32 v78, v76, v76
	v_pk_mul_f32 v[74:75], v[192:193], v[74:75]
	s_waitcnt vmcnt(16)
	v_pk_fma_f32 v[70:71], v[70:71], v[94:95], v[118:119]
	v_cvt_pk_bf16_f32 v74, v74, v75
	v_fmac_f32_e32 v78, v77, v77
	v_pk_mul_f32 v[76:77], v[190:191], v[76:77]
	v_pk_fma_f32 v[72:73], v[72:73], v[96:97], v[120:121]
	v_cvt_pk_bf16_f32 v75, v76, v77
	global_store_dwordx2 v[134:135], v[74:75], off offset:32
	v_mul_f32_e32 v74, v71, v71
	v_fmac_f32_e32 v74, v70, v70
	v_fmac_f32_e32 v74, v72, v72
	v_add_f32_e32 v78, v126, v78
	global_store_dwordx4 v[132:133], v[70:73], off offset:512 sc1
	v_fmac_f32_e32 v74, v73, v73
	v_add_f32_e32 v75, v78, v74
	v_pk_mul_f32 v[70:71], v[188:189], v[70:71]
	v_pk_mul_f32 v[72:73], v[186:187], v[72:73]
	v_cvt_pk_bf16_f32 v74, v70, v71
	s_waitcnt vmcnt(17)
	v_pk_fma_f32 v[70:71], v[68:69], v[84:85], v[116:117]
	v_pk_fma_f32 v[68:69], v[66:67], v[82:83], v[114:115]
	s_nop 0
	v_mul_f32_e32 v66, v69, v69
	v_fmac_f32_e32 v66, v68, v68
	v_fmac_f32_e32 v66, v70, v70
	v_fmac_f32_e32 v66, v71, v71
	v_add_f32_e32 v66, v75, v66
	ds_bpermute_b32 v67, v212, v66
	v_cvt_pk_bf16_f32 v75, v72, v73
	global_store_dwordx2 v[134:135], v[74:75], off offset:256
	global_store_dwordx4 v[132:133], v[68:71], off offset:576 sc1
	s_waitcnt lgkmcnt(0)
	v_add_f32_e32 v66, v66, v67
	ds_bpermute_b32 v67, v213, v66
	v_pk_mul_f32 v[68:69], v[180:181], v[68:69]
	v_pk_mul_f32 v[70:71], v[182:183], v[70:71]
	v_cvt_pk_bf16_f32 v68, v68, v69
	s_nop 0
	v_cvt_pk_bf16_f32 v69, v70, v71
	global_store_dwordx2 v[134:135], v[68:69], off offset:288
	s_and_saveexec_b64 s[0:1], s[4:5]
	s_cbranch_execz .LBB0_705
	v_lshl_add_u64 v[68:69], v[146:147], 2, s[18:19]
	s_waitcnt lgkmcnt(0)
	v_add_f32_e32 v66, v66, v67
	global_atomic_add_f32 v[68:69], v66, off
.LBB0_705:
	s_or_b64 exec, exec, s[0:1]
	v_or_b32_e32 v114, 16, v130
	v_ashrrev_i32_e32 v115, 31, v114
	v_add_u32_e32 v66, 0xffffc090, v200
	v_cmp_gt_i32_e32 vcc, s46, v114
	v_mov_b32_e32 v68, s15
	v_mov_b32_e32 v69, s13
	s_waitcnt lgkmcnt(0)
	v_cndmask_b32_e32 v67, 0, v115, vcc
	v_cndmask_b32_e32 v66, v66, v114, vcc
	v_cndmask_b32_e32 v69, v68, v69, vcc
	v_mov_b32_e32 v68, s14
	v_mov_b32_e32 v70, s12
	v_cndmask_b32_e32 v68, v68, v70, vcc
	v_lshlrev_b64 v[66:67], 13, v[66:67]
	v_lshl_add_u64 v[66:67], v[68:69], 0, v[66:67]
	v_lshl_add_u64 v[66:67], v[66:67], 0, v[198:199]
	global_load_dwordx4 v[78:81], v[66:67], off
	global_load_dwordx4 v[74:77], v[66:67], off offset:64
	global_load_dwordx4 v[70:73], v[66:67], off offset:512
	s_nop 0
	global_load_dwordx4 v[66:69], v[66:67], off offset:576
	v_lshlrev_b64 v[116:117], 13, v[130:131]
	v_lshl_add_u64 v[116:117], s[66:67], 0, v[116:117]
	s_waitcnt vmcnt(15)
	v_pk_fma_f32 v[62:63], v[62:63], v[86:87], v[110:111]
	v_lshl_add_u64 v[116:117], v[116:117], 0, v[198:199]
	v_lshlrev_b64 v[118:119], 12, v[130:131]
	v_pk_fma_f32 v[64:65], v[64:65], v[88:89], v[112:113]
	v_mul_f32_e32 v110, v63, v63
	v_lshl_add_u64 v[118:119], s[88:89], 0, v[118:119]
	global_store_dwordx4 v[116:117], v[62:65], off sc1
	v_fmac_f32_e32 v110, v62, v62
	v_lshl_add_u64 v[118:119], v[178:179], 1, v[118:119]
	v_pk_mul_f32 v[62:63], v[196:197], v[62:63]
	v_fmac_f32_e32 v110, v64, v64
	v_cvt_pk_bf16_f32 v62, v62, v63
	s_waitcnt vmcnt(15)
	v_pk_fma_f32 v[58:59], v[58:59], v[102:103], v[106:107]
	v_fmac_f32_e32 v110, v65, v65
	v_pk_mul_f32 v[64:65], v[194:195], v[64:65]
	v_pk_fma_f32 v[60:61], v[60:61], v[104:105], v[108:109]
	v_cvt_pk_bf16_f32 v63, v64, v65
	global_store_dwordx2 v[118:119], v[62:63], off
	v_mul_f32_e32 v62, v59, v59
	global_store_dwordx4 v[116:117], v[58:61], off offset:64 sc1
	v_fmac_f32_e32 v62, v58, v58
	v_fmac_f32_e32 v62, v60, v60
	v_pk_mul_f32 v[58:59], v[192:193], v[58:59]
	s_waitcnt vmcnt(16)
	v_pk_fma_f32 v[54:55], v[54:55], v[94:95], v[98:99]
	v_cvt_pk_bf16_f32 v58, v58, v59
	v_fmac_f32_e32 v62, v61, v61
	v_pk_mul_f32 v[60:61], v[190:191], v[60:61]
	v_pk_fma_f32 v[56:57], v[56:57], v[96:97], v[100:101]
	v_cvt_pk_bf16_f32 v59, v60, v61
	global_store_dwordx2 v[118:119], v[58:59], off offset:32
	v_mul_f32_e32 v58, v55, v55
	v_fmac_f32_e32 v58, v54, v54
	v_fmac_f32_e32 v58, v56, v56
	v_add_f32_e32 v62, v110, v62
	global_store_dwordx4 v[116:117], v[54:57], off offset:512 sc1
	v_fmac_f32_e32 v58, v57, v57
	v_add_f32_e32 v59, v62, v58
	v_pk_mul_f32 v[54:55], v[188:189], v[54:55]
	v_pk_mul_f32 v[56:57], v[186:187], v[56:57]
	v_cvt_pk_bf16_f32 v58, v54, v55
	s_waitcnt vmcnt(17)
	v_pk_fma_f32 v[54:55], v[52:53], v[84:85], v[92:93]
	v_pk_fma_f32 v[52:53], v[50:51], v[82:83], v[90:91]
	s_nop 0
	v_mul_f32_e32 v50, v53, v53
	v_fmac_f32_e32 v50, v52, v52
	v_fmac_f32_e32 v50, v54, v54
	v_fmac_f32_e32 v50, v55, v55
	v_add_f32_e32 v50, v59, v50
	ds_bpermute_b32 v51, v212, v50
	v_cvt_pk_bf16_f32 v59, v56, v57
	global_store_dwordx2 v[118:119], v[58:59], off offset:256
	global_store_dwordx4 v[116:117], v[52:55], off offset:576 sc1
	s_waitcnt lgkmcnt(0)
	v_add_f32_e32 v50, v50, v51
	ds_bpermute_b32 v51, v213, v50
	v_pk_mul_f32 v[52:53], v[180:181], v[52:53]
	v_pk_mul_f32 v[54:55], v[182:183], v[54:55]
	v_cvt_pk_bf16_f32 v52, v52, v53
	s_nop 0
	v_cvt_pk_bf16_f32 v53, v54, v55
	global_store_dwordx2 v[118:119], v[52:53], off offset:288
	s_and_saveexec_b64 s[0:1], s[4:5]
	s_cbranch_execz .LBB0_707
	v_lshl_add_u64 v[52:53], v[130:131], 2, s[18:19]
	s_waitcnt lgkmcnt(0)
	v_add_f32_e32 v50, v50, v51
	global_atomic_add_f32 v[52:53], v50, off
.LBB0_707:
	s_or_b64 exec, exec, s[0:1]
	v_or_b32_e32 v90, 32, v130
	v_ashrrev_i32_e32 v91, 31, v90
	v_add_u32_e32 v50, 0xffffc0a0, v200
	v_cmp_gt_i32_e32 vcc, s46, v90
	v_mov_b32_e32 v52, s15
	v_mov_b32_e32 v53, s13
	s_waitcnt lgkmcnt(0)
	v_cndmask_b32_e32 v51, 0, v91, vcc
	v_cndmask_b32_e32 v50, v50, v90, vcc
	v_cndmask_b32_e32 v53, v52, v53, vcc
	v_mov_b32_e32 v52, s14
	v_mov_b32_e32 v54, s12
	v_cndmask_b32_e32 v52, v52, v54, vcc
	v_lshlrev_b64 v[50:51], 13, v[50:51]
	v_lshl_add_u64 v[50:51], v[52:53], 0, v[50:51]
	v_lshl_add_u64 v[50:51], v[50:51], 0, v[198:199]
	global_load_dwordx4 v[62:65], v[50:51], off
	global_load_dwordx4 v[58:61], v[50:51], off offset:64
	global_load_dwordx4 v[54:57], v[50:51], off offset:512
	s_nop 0
	global_load_dwordx4 v[50:53], v[50:51], off offset:576
	v_lshlrev_b64 v[92:93], 13, v[114:115]
	v_lshl_add_u64 v[92:93], s[66:67], 0, v[92:93]
	s_waitcnt vmcnt(15)
	v_pk_fma_f32 v[46:47], v[46:47], v[86:87], v[78:79]
	v_lshl_add_u64 v[92:93], v[92:93], 0, v[198:199]
	v_lshlrev_b64 v[98:99], 12, v[114:115]
	v_pk_fma_f32 v[48:49], v[48:49], v[88:89], v[80:81]
	v_mul_f32_e32 v78, v47, v47
	v_lshl_add_u64 v[98:99], s[88:89], 0, v[98:99]
	global_store_dwordx4 v[92:93], v[46:49], off sc1
	v_fmac_f32_e32 v78, v46, v46
	v_lshl_add_u64 v[98:99], v[178:179], 1, v[98:99]
	v_pk_mul_f32 v[46:47], v[196:197], v[46:47]
	v_fmac_f32_e32 v78, v48, v48
	v_cvt_pk_bf16_f32 v46, v46, v47
	s_waitcnt vmcnt(15)
	v_pk_fma_f32 v[42:43], v[42:43], v[102:103], v[74:75]
	v_fmac_f32_e32 v78, v49, v49
	v_pk_mul_f32 v[48:49], v[194:195], v[48:49]
	v_pk_fma_f32 v[44:45], v[44:45], v[104:105], v[76:77]
	v_cvt_pk_bf16_f32 v47, v48, v49
	global_store_dwordx2 v[98:99], v[46:47], off
	v_mul_f32_e32 v46, v43, v43
	global_store_dwordx4 v[92:93], v[42:45], off offset:64 sc1
	v_fmac_f32_e32 v46, v42, v42
	v_fmac_f32_e32 v46, v44, v44
	v_pk_mul_f32 v[42:43], v[192:193], v[42:43]
	s_waitcnt vmcnt(16)
	v_pk_fma_f32 v[38:39], v[38:39], v[94:95], v[70:71]
	v_cvt_pk_bf16_f32 v42, v42, v43
	v_fmac_f32_e32 v46, v45, v45
	v_pk_mul_f32 v[44:45], v[190:191], v[44:45]
	v_pk_fma_f32 v[40:41], v[40:41], v[96:97], v[72:73]
	v_cvt_pk_bf16_f32 v43, v44, v45
	global_store_dwordx2 v[98:99], v[42:43], off offset:32
	v_mul_f32_e32 v42, v39, v39
	v_fmac_f32_e32 v42, v38, v38
	v_fmac_f32_e32 v42, v40, v40
	v_add_f32_e32 v46, v78, v46
	global_store_dwordx4 v[92:93], v[38:41], off offset:512 sc1
	v_fmac_f32_e32 v42, v41, v41
	v_add_f32_e32 v43, v46, v42
	v_pk_mul_f32 v[38:39], v[188:189], v[38:39]
	v_pk_mul_f32 v[40:41], v[186:187], v[40:41]
	v_cvt_pk_bf16_f32 v42, v38, v39
	s_waitcnt vmcnt(17)
	v_pk_fma_f32 v[38:39], v[36:37], v[84:85], v[68:69]
	v_pk_fma_f32 v[36:37], v[34:35], v[82:83], v[66:67]
	s_nop 0
	v_mul_f32_e32 v34, v37, v37
	v_fmac_f32_e32 v34, v36, v36
	v_fmac_f32_e32 v34, v38, v38
	v_fmac_f32_e32 v34, v39, v39
	v_add_f32_e32 v34, v43, v34
	ds_bpermute_b32 v35, v212, v34
	v_cvt_pk_bf16_f32 v43, v40, v41
	global_store_dwordx2 v[98:99], v[42:43], off offset:256
	global_store_dwordx4 v[92:93], v[36:39], off offset:576 sc1
	s_waitcnt lgkmcnt(0)
	v_add_f32_e32 v34, v34, v35
	ds_bpermute_b32 v35, v213, v34
	v_pk_mul_f32 v[36:37], v[180:181], v[36:37]
	v_pk_mul_f32 v[38:39], v[182:183], v[38:39]
	v_cvt_pk_bf16_f32 v36, v36, v37
	s_nop 0
	v_cvt_pk_bf16_f32 v37, v38, v39
	global_store_dwordx2 v[98:99], v[36:37], off offset:288
	s_and_saveexec_b64 s[0:1], s[4:5]
	s_cbranch_execz .LBB0_709
	v_lshl_add_u64 v[36:37], v[114:115], 2, s[18:19]
	s_waitcnt lgkmcnt(0)
	v_add_f32_e32 v34, v34, v35
	global_atomic_add_f32 v[36:37], v34, off
.LBB0_709:
	s_or_b64 exec, exec, s[0:1]
	v_or_b32_e32 v66, 48, v130
	v_ashrrev_i32_e32 v67, 31, v66
	v_add_u32_e32 v34, 0xffffc0b0, v200
	v_cmp_gt_i32_e32 vcc, s46, v66
	v_mov_b32_e32 v36, s15
	v_mov_b32_e32 v37, s13
	s_waitcnt lgkmcnt(0)
	v_cndmask_b32_e32 v35, 0, v67, vcc
	v_cndmask_b32_e32 v34, v34, v66, vcc
	v_cndmask_b32_e32 v37, v36, v37, vcc
	v_mov_b32_e32 v36, s14
	v_mov_b32_e32 v38, s12
	v_cndmask_b32_e32 v36, v36, v38, vcc
	v_lshlrev_b64 v[34:35], 13, v[34:35]
	v_lshl_add_u64 v[34:35], v[36:37], 0, v[34:35]
	v_lshl_add_u64 v[34:35], v[34:35], 0, v[198:199]
	global_load_dwordx4 v[46:49], v[34:35], off
	global_load_dwordx4 v[42:45], v[34:35], off offset:64
	global_load_dwordx4 v[38:41], v[34:35], off offset:512
	s_nop 0
	global_load_dwordx4 v[34:37], v[34:35], off offset:576
	v_lshlrev_b64 v[68:69], 13, v[90:91]
	v_lshl_add_u64 v[68:69], s[66:67], 0, v[68:69]
	s_waitcnt vmcnt(15)
	v_pk_fma_f32 v[30:31], v[30:31], v[86:87], v[62:63]
	v_lshl_add_u64 v[68:69], v[68:69], 0, v[198:199]
	v_lshlrev_b64 v[70:71], 12, v[90:91]
	v_pk_fma_f32 v[32:33], v[32:33], v[88:89], v[64:65]
	v_mul_f32_e32 v62, v31, v31
	v_lshl_add_u64 v[70:71], s[88:89], 0, v[70:71]
	global_store_dwordx4 v[68:69], v[30:33], off sc1
	v_fmac_f32_e32 v62, v30, v30
	v_lshl_add_u64 v[70:71], v[178:179], 1, v[70:71]
	v_pk_mul_f32 v[30:31], v[196:197], v[30:31]
	v_fmac_f32_e32 v62, v32, v32
	v_cvt_pk_bf16_f32 v30, v30, v31
	s_waitcnt vmcnt(15)
	v_pk_fma_f32 v[26:27], v[26:27], v[102:103], v[58:59]
	v_fmac_f32_e32 v62, v33, v33
	v_pk_mul_f32 v[32:33], v[194:195], v[32:33]
	v_pk_fma_f32 v[28:29], v[28:29], v[104:105], v[60:61]
	v_cvt_pk_bf16_f32 v31, v32, v33
	global_store_dwordx2 v[70:71], v[30:31], off
	v_mul_f32_e32 v30, v27, v27
	global_store_dwordx4 v[68:69], v[26:29], off offset:64 sc1
	v_fmac_f32_e32 v30, v26, v26
	v_fmac_f32_e32 v30, v28, v28
	v_pk_mul_f32 v[26:27], v[192:193], v[26:27]
	s_waitcnt vmcnt(16)
	v_pk_fma_f32 v[22:23], v[22:23], v[94:95], v[54:55]
	v_cvt_pk_bf16_f32 v26, v26, v27
	v_fmac_f32_e32 v30, v29, v29
	v_pk_mul_f32 v[28:29], v[190:191], v[28:29]
	v_pk_fma_f32 v[24:25], v[24:25], v[96:97], v[56:57]
	v_cvt_pk_bf16_f32 v27, v28, v29
	global_store_dwordx2 v[70:71], v[26:27], off offset:32
	v_mul_f32_e32 v26, v23, v23
	v_fmac_f32_e32 v26, v22, v22
	v_fmac_f32_e32 v26, v24, v24
	v_add_f32_e32 v30, v62, v30
	global_store_dwordx4 v[68:69], v[22:25], off offset:512 sc1
	v_fmac_f32_e32 v26, v25, v25
	v_add_f32_e32 v27, v30, v26
	v_pk_mul_f32 v[22:23], v[188:189], v[22:23]
	v_pk_mul_f32 v[24:25], v[186:187], v[24:25]
	v_cvt_pk_bf16_f32 v26, v22, v23
	s_waitcnt vmcnt(17)
	v_pk_fma_f32 v[22:23], v[20:21], v[84:85], v[52:53]
	v_pk_fma_f32 v[20:21], v[18:19], v[82:83], v[50:51]
	s_nop 0
	v_mul_f32_e32 v18, v21, v21
	v_fmac_f32_e32 v18, v20, v20
	v_fmac_f32_e32 v18, v22, v22
	v_fmac_f32_e32 v18, v23, v23
	v_add_f32_e32 v18, v27, v18
	ds_bpermute_b32 v19, v212, v18
	v_cvt_pk_bf16_f32 v27, v24, v25
	global_store_dwordx2 v[70:71], v[26:27], off offset:256
	global_store_dwordx4 v[68:69], v[20:23], off offset:576 sc1
	s_waitcnt lgkmcnt(0)
	v_add_f32_e32 v18, v18, v19
	ds_bpermute_b32 v19, v213, v18
	v_pk_mul_f32 v[20:21], v[180:181], v[20:21]
	v_pk_mul_f32 v[22:23], v[182:183], v[22:23]
	v_cvt_pk_bf16_f32 v20, v20, v21
	s_nop 0
	v_cvt_pk_bf16_f32 v21, v22, v23
	global_store_dwordx2 v[70:71], v[20:21], off offset:288
	s_and_saveexec_b64 s[0:1], s[4:5]
	s_cbranch_execz .LBB0_711
	v_lshl_add_u64 v[20:21], v[90:91], 2, s[18:19]
	s_waitcnt lgkmcnt(0)
	v_add_f32_e32 v18, v18, v19
	global_atomic_add_f32 v[20:21], v18, off
.LBB0_711:
	s_or_b64 exec, exec, s[0:1]
	s_waitcnt lgkmcnt(0)
	v_lshlrev_b64 v[18:19], 13, v[66:67]
	v_lshl_add_u64 v[18:19], s[66:67], 0, v[18:19]
	s_waitcnt vmcnt(11)
	v_pk_fma_f32 v[14:15], v[14:15], v[86:87], v[46:47]
	v_lshl_add_u64 v[18:19], v[178:179], 2, v[18:19]
	v_lshlrev_b64 v[20:21], 12, v[66:67]
	v_pk_fma_f32 v[16:17], v[16:17], v[88:89], v[48:49]
	v_mul_f32_e32 v22, v15, v15
	v_lshl_add_u64 v[20:21], s[88:89], 0, v[20:21]
	global_store_dwordx4 v[18:19], v[14:17], off sc1
	v_fmac_f32_e32 v22, v14, v14
	v_lshl_add_u64 v[20:21], v[178:179], 1, v[20:21]
	v_pk_mul_f32 v[14:15], v[196:197], v[14:15]
	v_fmac_f32_e32 v22, v16, v16
	v_cvt_pk_bf16_f32 v14, v14, v15
	s_waitcnt vmcnt(11)
	v_pk_fma_f32 v[10:11], v[10:11], v[102:103], v[42:43]
	v_fmac_f32_e32 v22, v17, v17
	v_pk_mul_f32 v[16:17], v[194:195], v[16:17]
	v_pk_fma_f32 v[12:13], v[12:13], v[104:105], v[44:45]
	v_cvt_pk_bf16_f32 v15, v16, v17
	global_store_dwordx2 v[20:21], v[14:15], off
	v_mul_f32_e32 v14, v11, v11
	global_store_dwordx4 v[18:19], v[10:13], off offset:64 sc1
	v_fmac_f32_e32 v14, v10, v10
	v_fmac_f32_e32 v14, v12, v12
	v_pk_mul_f32 v[10:11], v[192:193], v[10:11]
	s_waitcnt vmcnt(12)
	v_pk_fma_f32 v[6:7], v[6:7], v[94:95], v[38:39]
	v_cvt_pk_bf16_f32 v10, v10, v11
	v_fmac_f32_e32 v14, v13, v13
	v_pk_mul_f32 v[12:13], v[190:191], v[12:13]
	v_pk_fma_f32 v[8:9], v[8:9], v[96:97], v[40:41]
	v_cvt_pk_bf16_f32 v11, v12, v13
	global_store_dwordx2 v[20:21], v[10:11], off offset:32
	v_mul_f32_e32 v10, v7, v7
	v_fmac_f32_e32 v10, v6, v6
	v_fmac_f32_e32 v10, v8, v8
	v_add_f32_e32 v14, v22, v14
	global_store_dwordx4 v[18:19], v[6:9], off offset:512 sc1
	v_fmac_f32_e32 v10, v9, v9
	v_add_f32_e32 v11, v14, v10
	v_pk_mul_f32 v[6:7], v[188:189], v[6:7]
	v_pk_mul_f32 v[8:9], v[186:187], v[8:9]
	v_cvt_pk_bf16_f32 v10, v6, v7
	s_waitcnt vmcnt(13)
	v_pk_fma_f32 v[6:7], v[4:5], v[84:85], v[36:37]
	v_pk_fma_f32 v[4:5], v[2:3], v[82:83], v[34:35]
	s_nop 0
	v_mul_f32_e32 v2, v5, v5
	v_fmac_f32_e32 v2, v4, v4
	v_fmac_f32_e32 v2, v6, v6
	v_fmac_f32_e32 v2, v7, v7
	v_add_f32_e32 v2, v11, v2
	ds_bpermute_b32 v3, v212, v2
	v_cvt_pk_bf16_f32 v11, v8, v9
	global_store_dwordx2 v[20:21], v[10:11], off offset:256
	global_store_dwordx4 v[18:19], v[4:7], off offset:576 sc1
	s_waitcnt lgkmcnt(0)
	v_add_f32_e32 v2, v2, v3
	ds_bpermute_b32 v3, v213, v2
	v_pk_mul_f32 v[4:5], v[180:181], v[4:5]
	v_pk_mul_f32 v[6:7], v[182:183], v[6:7]
	v_cvt_pk_bf16_f32 v4, v4, v5
	s_nop 0
	v_cvt_pk_bf16_f32 v5, v6, v7
	global_store_dwordx2 v[20:21], v[4:5], off offset:288
	s_and_saveexec_b64 s[0:1], s[4:5]
	s_cbranch_execz .LBB0_686
	v_lshl_add_u64 v[4:5], v[66:67], 2, s[18:19]
	s_waitcnt lgkmcnt(0)
	v_add_f32_e32 v2, v2, v3
	global_atomic_add_f32 v[4:5], v2, off
	s_branch .LBB0_686

.LBB0_803:
	s_add_u32 s4, s12, 0xfff80080
	s_addc_u32 s20, s13, -1
	s_add_i32 s58, 0, 0x10000
	v_add_u32_e32 v140, s58, v161
	ds_read_b128 v[128:131], v140
	ds_read_b128 v[132:135], v140 offset:1024
	ds_read_b128 v[136:139], v140 offset:2048
	ds_read_b128 v[140:143], v140 offset:3072
	s_cmp_eq_u32 s57, 28
	s_cselect_b32 s25, s15, s20
	s_cselect_b32 s24, s45, s4
	s_cselect_b32 s21, s3, s56
	s_cselect_b32 s20, s52, s53
	v_lshl_add_u64 v[158:159], s[12:13], 0, v[150:151]
	s_add_i32 m0, s16, 0xc000
	ds_read_b128 v[154:157], v163
	ds_read_b128 v[164:167], v163 offset:1024
	ds_read_b128 v[168:171], v163 offset:2048
	ds_read_b128 v[172:175], v163 offset:3072
	ds_read_b128 v[176:179], v163 offset:4096
	ds_read_b128 v[180:183], v163 offset:5120
	ds_read_b128 v[196:199], v163 offset:6144
	ds_read_b128 v[200:203], v163 offset:7168
	global_load_lds_dwordx4 v[158:159], off
	v_lshl_add_u64 v[158:159], s[12:13], 0, v[152:153]
	s_add_i32 m0, s16, 0xe000
	s_nop 0
	global_load_lds_dwordx4 v[158:159], off
	v_add_u32_e32 v216, 0x14000, v161
	ds_read_b128 v[204:207], v216
	ds_read_b128 v[208:211], v216 offset:1024
	ds_read_b128 v[212:215], v216 offset:2048
	ds_read_b128 v[216:219], v216 offset:3072
	s_waitcnt vmcnt(8)
	s_waitcnt lgkmcnt(0)
	s_barrier
	s_setprio 1
	v_mfma_f32_16x16x32_bf16 v[124:127], v[128:131], v[154:157], v[124:127]
	v_mfma_f32_16x16x32_bf16 v[120:123], v[136:139], v[154:157], v[120:123]
	v_mfma_f32_16x16x32_bf16 v[108:111], v[128:131], v[168:171], v[108:111]
	v_mfma_f32_16x16x32_bf16 v[104:107], v[136:139], v[168:171], v[104:107]
	v_mfma_f32_16x16x32_bf16 v[92:95], v[128:131], v[176:179], v[92:95]
	v_mfma_f32_16x16x32_bf16 v[88:91], v[136:139], v[176:179], v[88:91]
	v_mfma_f32_16x16x32_bf16 v[76:79], v[128:131], v[196:199], v[76:79]
	v_mfma_f32_16x16x32_bf16 v[72:75], v[136:139], v[196:199], v[72:75]
	v_mfma_f32_16x16x32_bf16 v[124:127], v[132:135], v[164:167], v[124:127]
	v_mfma_f32_16x16x32_bf16 v[120:123], v[140:143], v[164:167], v[120:123]
	v_mfma_f32_16x16x32_bf16 v[108:111], v[132:135], v[172:175], v[108:111]
	v_mfma_f32_16x16x32_bf16 v[104:107], v[140:143], v[172:175], v[104:107]
	v_mfma_f32_16x16x32_bf16 v[92:95], v[132:135], v[180:183], v[92:95]
	v_mfma_f32_16x16x32_bf16 v[88:91], v[140:143], v[180:183], v[88:91]
	v_mfma_f32_16x16x32_bf16 v[76:79], v[132:135], v[200:203], v[76:79]
	v_mfma_f32_16x16x32_bf16 v[72:75], v[140:143], v[200:203], v[72:75]
	v_mfma_f32_16x16x32_bf16 v[116:119], v[204:207], v[154:157], v[116:119]
	v_mfma_f32_16x16x32_bf16 v[112:115], v[212:215], v[154:157], v[112:115]
	v_mfma_f32_16x16x32_bf16 v[100:103], v[204:207], v[168:171], v[100:103]
	v_mfma_f32_16x16x32_bf16 v[96:99], v[212:215], v[168:171], v[96:99]
	v_mfma_f32_16x16x32_bf16 v[84:87], v[204:207], v[176:179], v[84:87]
	v_mfma_f32_16x16x32_bf16 v[80:83], v[212:215], v[176:179], v[80:83]
	v_mfma_f32_16x16x32_bf16 v[68:71], v[204:207], v[196:199], v[68:71]
	v_mfma_f32_16x16x32_bf16 v[64:67], v[212:215], v[196:199], v[64:67]
	v_mfma_f32_16x16x32_bf16 v[116:119], v[208:211], v[164:167], v[116:119]
	v_mfma_f32_16x16x32_bf16 v[112:115], v[216:219], v[164:167], v[112:115]
	v_mfma_f32_16x16x32_bf16 v[100:103], v[208:211], v[172:175], v[100:103]
	v_mfma_f32_16x16x32_bf16 v[96:99], v[216:219], v[172:175], v[96:99]
	v_mfma_f32_16x16x32_bf16 v[84:87], v[208:211], v[180:183], v[84:87]
	v_mfma_f32_16x16x32_bf16 v[80:83], v[216:219], v[180:183], v[80:83]
	v_mfma_f32_16x16x32_bf16 v[68:71], v[208:211], v[200:203], v[68:71]
	v_mfma_f32_16x16x32_bf16 v[64:67], v[216:219], v[200:203], v[64:67]
	s_setprio 0
	s_barrier
	s_add_i32 s4, 0, 0x14000
	s_add_i32 s58, s58, s27
	v_lshl_add_u64 v[158:159], s[20:21], 0, v[186:187]
	s_mov_b32 m0, s58
	v_lshl_add_u64 v[220:221], s[20:21], 0, v[144:145]
	global_load_lds_dwordx4 v[158:159], off
	s_add_i32 m0, s58, 0x2000
	s_nop 0
	global_load_lds_dwordx4 v[220:221], off
	s_mov_b32 m0, s16
	v_lshl_add_u64 v[222:223], s[24:25], 0, v[148:149]
	ds_read_b128 v[154:157], v163 offset:16384
	ds_read_b128 v[164:167], v163 offset:17408
	ds_read_b128 v[168:171], v163 offset:18432
	ds_read_b128 v[172:175], v163 offset:19456
	ds_read_b128 v[176:179], v163 offset:20480
	ds_read_b128 v[180:183], v163 offset:21504
	ds_read_b128 v[196:199], v163 offset:22528
	ds_read_b128 v[200:203], v163 offset:23552
	global_load_lds_dwordx4 v[222:223], off
	v_lshl_add_u64 v[224:225], s[24:25], 0, v[146:147]
	s_mov_b32 m0, s17
	s_nop 0
	global_load_lds_dwordx4 v[224:225], off
	s_waitcnt vmcnt(6)
	s_waitcnt lgkmcnt(0)
	s_barrier
	s_setprio 1
	v_mfma_f32_16x16x32_bf16 v[60:63], v[128:131], v[154:157], v[60:63]
	v_mfma_f32_16x16x32_bf16 v[56:59], v[136:139], v[154:157], v[56:59]
	v_mfma_f32_16x16x32_bf16 v[44:47], v[128:131], v[168:171], v[44:47]
	v_mfma_f32_16x16x32_bf16 v[40:43], v[136:139], v[168:171], v[40:43]
	v_mfma_f32_16x16x32_bf16 v[28:31], v[128:131], v[176:179], v[28:31]
	v_mfma_f32_16x16x32_bf16 v[24:27], v[136:139], v[176:179], v[24:27]
	v_mfma_f32_16x16x32_bf16 v[12:15], v[128:131], v[196:199], v[12:15]
	v_mfma_f32_16x16x32_bf16 v[8:11], v[136:139], v[196:199], v[8:11]
	v_mfma_f32_16x16x32_bf16 v[60:63], v[132:135], v[164:167], v[60:63]
	v_mfma_f32_16x16x32_bf16 v[56:59], v[140:143], v[164:167], v[56:59]
	v_mfma_f32_16x16x32_bf16 v[44:47], v[132:135], v[172:175], v[44:47]
	v_mfma_f32_16x16x32_bf16 v[40:43], v[140:143], v[172:175], v[40:43]
	v_mfma_f32_16x16x32_bf16 v[28:31], v[132:135], v[180:183], v[28:31]
	v_mfma_f32_16x16x32_bf16 v[24:27], v[140:143], v[180:183], v[24:27]
	v_mfma_f32_16x16x32_bf16 v[12:15], v[132:135], v[200:203], v[12:15]
	v_mfma_f32_16x16x32_bf16 v[8:11], v[140:143], v[200:203], v[8:11]
	v_mfma_f32_16x16x32_bf16 v[52:55], v[204:207], v[154:157], v[52:55]
	v_mfma_f32_16x16x32_bf16 v[48:51], v[212:215], v[154:157], v[48:51]
	v_mfma_f32_16x16x32_bf16 v[36:39], v[204:207], v[168:171], v[36:39]
	v_mfma_f32_16x16x32_bf16 v[32:35], v[212:215], v[168:171], v[32:35]
	v_mfma_f32_16x16x32_bf16 v[20:23], v[204:207], v[176:179], v[20:23]
	v_mfma_f32_16x16x32_bf16 v[16:19], v[212:215], v[176:179], v[16:19]
	v_mfma_f32_16x16x32_bf16 v[4:7], v[204:207], v[196:199], v[4:7]
	v_mfma_f32_16x16x32_bf16 v[0:3], v[212:215], v[196:199], v[0:3]
	v_mfma_f32_16x16x32_bf16 v[52:55], v[208:211], v[164:167], v[52:55]
	v_mfma_f32_16x16x32_bf16 v[48:51], v[216:219], v[164:167], v[48:51]
	v_mfma_f32_16x16x32_bf16 v[36:39], v[208:211], v[172:175], v[36:39]
	v_mfma_f32_16x16x32_bf16 v[32:35], v[216:219], v[172:175], v[32:35]
	v_mfma_f32_16x16x32_bf16 v[20:23], v[208:211], v[180:183], v[20:23]
	v_mfma_f32_16x16x32_bf16 v[16:19], v[216:219], v[180:183], v[16:19]
	v_mfma_f32_16x16x32_bf16 v[4:7], v[208:211], v[200:203], v[4:7]
	v_mfma_f32_16x16x32_bf16 v[0:3], v[216:219], v[200:203], v[0:3]
	s_setprio 0
	s_barrier
	s_add_u32 s58, s20, 0x80000
	s_addc_u32 s59, s21, 0
	s_add_i32 s4, s4, s27
	v_lshl_add_u64 v[128:129], s[58:59], 0, v[186:187]
	s_mov_b32 m0, s4
	s_nop 0
	global_load_lds_dwordx4 v[128:129], off
	v_lshl_add_u64 v[128:129], s[58:59], 0, v[144:145]
	s_add_i32 m0, s4, 0x2000
	s_nop 0
	global_load_lds_dwordx4 v[128:129], off
	s_add_i32 s4, 0, 0x18000
	v_add_u32_e32 v140, s4, v161
	ds_read_b128 v[128:131], v140
	ds_read_b128 v[132:135], v140 offset:1024
	ds_read_b128 v[136:139], v140 offset:2048
	ds_read_b128 v[140:143], v140 offset:3072
	s_add_u32 s24, s24, 0x80000
	s_addc_u32 s25, s25, 0
	s_mov_b32 m0, s30
	v_lshl_add_u64 v[204:205], s[24:25], 0, v[148:149]
	ds_read_b128 v[154:157], v163 offset:32768
	ds_read_b128 v[164:167], v163 offset:33792
	ds_read_b128 v[168:171], v163 offset:34816
	ds_read_b128 v[172:175], v163 offset:35840
	ds_read_b128 v[176:179], v163 offset:36864
	ds_read_b128 v[180:183], v163 offset:37888
	ds_read_b128 v[196:199], v163 offset:38912
	ds_read_b128 v[200:203], v163 offset:39936
	global_load_lds_dwordx4 v[204:205], off
	v_lshl_add_u64 v[204:205], s[24:25], 0, v[146:147]
	s_mov_b32 m0, s31
	s_nop 0
	global_load_lds_dwordx4 v[204:205], off
	v_add_u32_e32 v216, 0x1c000, v161
	ds_read_b128 v[204:207], v216
	ds_read_b128 v[208:211], v216 offset:1024
	ds_read_b128 v[212:215], v216 offset:2048
	ds_read_b128 v[216:219], v216 offset:3072
	s_waitcnt vmcnt(8)
	s_waitcnt lgkmcnt(0)
	s_barrier
	s_setprio 1
	v_mfma_f32_16x16x32_bf16 v[124:127], v[128:131], v[154:157], v[124:127]
	v_mfma_f32_16x16x32_bf16 v[120:123], v[136:139], v[154:157], v[120:123]
	v_mfma_f32_16x16x32_bf16 v[108:111], v[128:131], v[168:171], v[108:111]
	v_mfma_f32_16x16x32_bf16 v[104:107], v[136:139], v[168:171], v[104:107]
	v_mfma_f32_16x16x32_bf16 v[92:95], v[128:131], v[176:179], v[92:95]
	v_mfma_f32_16x16x32_bf16 v[88:91], v[136:139], v[176:179], v[88:91]
	v_mfma_f32_16x16x32_bf16 v[76:79], v[128:131], v[196:199], v[76:79]
	v_mfma_f32_16x16x32_bf16 v[72:75], v[136:139], v[196:199], v[72:75]
	v_mfma_f32_16x16x32_bf16 v[124:127], v[132:135], v[164:167], v[124:127]
	v_mfma_f32_16x16x32_bf16 v[120:123], v[140:143], v[164:167], v[120:123]
	v_mfma_f32_16x16x32_bf16 v[108:111], v[132:135], v[172:175], v[108:111]
	v_mfma_f32_16x16x32_bf16 v[104:107], v[140:143], v[172:175], v[104:107]
	v_mfma_f32_16x16x32_bf16 v[92:95], v[132:135], v[180:183], v[92:95]
	v_mfma_f32_16x16x32_bf16 v[88:91], v[140:143], v[180:183], v[88:91]
	v_mfma_f32_16x16x32_bf16 v[76:79], v[132:135], v[200:203], v[76:79]
	v_mfma_f32_16x16x32_bf16 v[72:75], v[140:143], v[200:203], v[72:75]
	v_mfma_f32_16x16x32_bf16 v[116:119], v[204:207], v[154:157], v[116:119]
	v_mfma_f32_16x16x32_bf16 v[112:115], v[212:215], v[154:157], v[112:115]
	v_mfma_f32_16x16x32_bf16 v[100:103], v[204:207], v[168:171], v[100:103]
	v_mfma_f32_16x16x32_bf16 v[96:99], v[212:215], v[168:171], v[96:99]
	v_mfma_f32_16x16x32_bf16 v[84:87], v[204:207], v[176:179], v[84:87]
	v_mfma_f32_16x16x32_bf16 v[80:83], v[212:215], v[176:179], v[80:83]
	v_mfma_f32_16x16x32_bf16 v[68:71], v[204:207], v[196:199], v[68:71]
	v_mfma_f32_16x16x32_bf16 v[64:67], v[212:215], v[196:199], v[64:67]
	v_mfma_f32_16x16x32_bf16 v[116:119], v[208:211], v[164:167], v[116:119]
	v_mfma_f32_16x16x32_bf16 v[112:115], v[216:219], v[164:167], v[112:115]
	v_mfma_f32_16x16x32_bf16 v[100:103], v[208:211], v[172:175], v[100:103]
	v_mfma_f32_16x16x32_bf16 v[96:99], v[216:219], v[172:175], v[96:99]
	v_mfma_f32_16x16x32_bf16 v[84:87], v[208:211], v[180:183], v[84:87]
	v_mfma_f32_16x16x32_bf16 v[80:83], v[216:219], v[180:183], v[80:83]
	v_mfma_f32_16x16x32_bf16 v[68:71], v[208:211], v[200:203], v[68:71]
	v_mfma_f32_16x16x32_bf16 v[64:67], v[216:219], v[200:203], v[64:67]
	s_setprio 0
	s_barrier
	s_add_i32 s24, 0, 0x1c000
	s_add_i32 s4, s4, s27
	v_lshl_add_u64 v[158:159], v[158:159], 0, s[0:1]
	s_mov_b32 m0, s4
	global_load_lds_dwordx4 v[158:159], off
	v_lshl_add_u64 v[158:159], v[220:221], 0, s[0:1]
	s_add_i32 m0, s4, 0x2000
	s_nop 0
	global_load_lds_dwordx4 v[158:159], off
	s_mov_b32 m0, s38
	v_lshl_add_u64 v[158:159], v[222:223], 0, s[0:1]
	ds_read_b128 v[154:157], v163 offset:49152
	ds_read_b128 v[164:167], v163 offset:50176
	ds_read_b128 v[168:171], v163 offset:51200
	ds_read_b128 v[172:175], v163 offset:52224
	ds_read_b128 v[176:179], v163 offset:53248
	ds_read_b128 v[180:183], v163 offset:54272
	ds_read_b128 v[196:199], v163 offset:55296
	ds_read_b128 v[200:203], v163 offset:56320
	global_load_lds_dwordx4 v[158:159], off
	v_lshl_add_u64 v[158:159], v[224:225], 0, s[0:1]
	s_mov_b32 m0, s39
	s_nop 0
	global_load_lds_dwordx4 v[158:159], off
	s_add_u32 s20, s20, 0x80080
	s_addc_u32 s21, s21, 0
	s_add_i32 s4, s24, s27
	v_lshl_add_u64 v[158:159], s[20:21], 0, v[186:187]
	s_mov_b32 m0, s4
	s_nop 0
	global_load_lds_dwordx4 v[158:159], off
	v_lshl_add_u64 v[158:159], s[20:21], 0, v[144:145]
	s_add_i32 m0, s4, 0x2000
	s_nop 0
	global_load_lds_dwordx4 v[158:159], off
	s_waitcnt vmcnt(8)
	s_waitcnt lgkmcnt(0)
	s_barrier
	s_setprio 1
	v_mfma_f32_16x16x32_bf16 v[60:63], v[128:131], v[154:157], v[60:63]
	v_mfma_f32_16x16x32_bf16 v[56:59], v[136:139], v[154:157], v[56:59]
	v_mfma_f32_16x16x32_bf16 v[44:47], v[128:131], v[168:171], v[44:47]
	v_mfma_f32_16x16x32_bf16 v[40:43], v[136:139], v[168:171], v[40:43]
	v_mfma_f32_16x16x32_bf16 v[28:31], v[128:131], v[176:179], v[28:31]
	v_mfma_f32_16x16x32_bf16 v[24:27], v[136:139], v[176:179], v[24:27]
	v_mfma_f32_16x16x32_bf16 v[12:15], v[128:131], v[196:199], v[12:15]
	v_mfma_f32_16x16x32_bf16 v[8:11], v[136:139], v[196:199], v[8:11]
	v_mfma_f32_16x16x32_bf16 v[60:63], v[132:135], v[164:167], v[60:63]
	v_mfma_f32_16x16x32_bf16 v[56:59], v[140:143], v[164:167], v[56:59]
	v_mfma_f32_16x16x32_bf16 v[44:47], v[132:135], v[172:175], v[44:47]
	v_mfma_f32_16x16x32_bf16 v[40:43], v[140:143], v[172:175], v[40:43]
	v_mfma_f32_16x16x32_bf16 v[28:31], v[132:135], v[180:183], v[28:31]
	v_mfma_f32_16x16x32_bf16 v[24:27], v[140:143], v[180:183], v[24:27]
	v_mfma_f32_16x16x32_bf16 v[12:15], v[132:135], v[200:203], v[12:15]
	v_mfma_f32_16x16x32_bf16 v[8:11], v[140:143], v[200:203], v[8:11]
	v_mfma_f32_16x16x32_bf16 v[52:55], v[204:207], v[154:157], v[52:55]
	v_mfma_f32_16x16x32_bf16 v[48:51], v[212:215], v[154:157], v[48:51]
	v_mfma_f32_16x16x32_bf16 v[36:39], v[204:207], v[168:171], v[36:39]
	v_mfma_f32_16x16x32_bf16 v[32:35], v[212:215], v[168:171], v[32:35]
	v_mfma_f32_16x16x32_bf16 v[20:23], v[204:207], v[176:179], v[20:23]
	v_mfma_f32_16x16x32_bf16 v[16:19], v[212:215], v[176:179], v[16:19]
	v_mfma_f32_16x16x32_bf16 v[4:7], v[204:207], v[196:199], v[4:7]
	v_mfma_f32_16x16x32_bf16 v[0:3], v[212:215], v[196:199], v[0:3]
	v_mfma_f32_16x16x32_bf16 v[52:55], v[208:211], v[164:167], v[52:55]
	v_mfma_f32_16x16x32_bf16 v[48:51], v[216:219], v[164:167], v[48:51]
	v_mfma_f32_16x16x32_bf16 v[36:39], v[208:211], v[172:175], v[36:39]
	v_mfma_f32_16x16x32_bf16 v[32:35], v[216:219], v[172:175], v[32:35]
	v_mfma_f32_16x16x32_bf16 v[20:23], v[208:211], v[180:183], v[20:23]
	v_mfma_f32_16x16x32_bf16 v[16:19], v[216:219], v[180:183], v[16:19]
	v_mfma_f32_16x16x32_bf16 v[4:7], v[208:211], v[200:203], v[4:7]
	v_mfma_f32_16x16x32_bf16 v[0:3], v[216:219], v[200:203], v[0:3]
	s_setprio 0
	s_add_i32 s57, s57, 2
	s_add_u32 s12, s12, 0x100
	s_addc_u32 s13, s13, 0
	s_add_u32 s53, s53, 0x100
	s_addc_u32 s56, s56, 0
	s_cmp_gt_u32 s57, 29
	s_barrier
	s_cbranch_scc0 .LBB0_803
	s_lshl_b32 s3, s44, 8
	s_add_i32 s4, s3, s35
	v_add_u32_e32 v156, s3, v160
	s_min_i32 s3, s4, 0x4000
	v_add_u32_e32 v128, s35, v156
	s_ashr_i32 s12, s3, 11
	v_ashrrev_i32_e32 v129, 31, v128
	s_ashr_i32 s13, s12, 31
	v_lshl_add_u64 v[128:129], v[128:129], 2, s[48:49]
	s_lshl_b64 s[12:13], s[12:13], 15
	global_load_dword v167, v[128:129], off
	global_load_dword v170, v[128:129], off offset:64
	global_load_dword v171, v[128:129], off offset:128
	global_load_dword v172, v[128:129], off offset:192
	global_load_dword v173, v[128:129], off offset:512
	global_load_dword v166, v[128:129], off offset:576
	global_load_dword v165, v[128:129], off offset:640
	v_lshl_or_b32 v154, s41, 8, v162
	s_add_u32 s12, s37, s12
	s_addc_u32 s13, s6, s13
	v_ashrrev_i32_e32 v155, 31, v154
	global_load_dword v164, v[128:129], off offset:704
	v_lshl_add_u64 v[128:129], v[154:155], 2, s[12:13]
	global_load_dwordx4 v[140:143], v[128:129], off
	global_load_dwordx4 v[136:139], v[128:129], off offset:16
	global_load_dwordx4 v[132:135], v[128:129], off offset:512
	s_nop 0
	global_load_dwordx4 v[128:131], v[128:129], off offset:528
	v_ashrrev_i32_e32 v157, 31, v156
	v_lshlrev_b64 v[158:159], 1, v[154:155]
	v_lshlrev_b64 v[154:155], 14, v[156:157]
	v_lshl_add_u64 v[154:155], s[54:55], 0, v[154:155]
	v_lshl_add_u64 v[154:155], v[154:155], 0, v[158:159]
	v_or_b32_e32 v168, 16, v156
	v_ashrrev_i32_e32 v169, 31, v168
	s_mov_b32 s3, 0x200000
	s_mov_b64 s[12:13], 0x200000
	s_mov_b32 s41, s2
	s_mov_b32 s44, s14
	s_mov_b64 s[20:21], s[28:29]
	s_waitcnt vmcnt(0)
	s_nop 0
	v_fmamk_f32 v157, v167, 0x3a000000, v229
	v_mul_f32_e32 v167, 0x4b800000, v157
	v_cmp_gt_f32_e32 vcc, s5, v157
	s_nop 1
	v_cndmask_b32_e32 v157, v157, v167, vcc
	v_rsq_f32_e32 v157, v157
	v_fmamk_f32 v167, v170, 0x3a000000, v229
	v_mul_f32_e32 v170, 0x45800000, v157
	v_cndmask_b32_e32 v170, v157, v170, vcc
	v_pk_fma_f32 v[124:125], v[124:125], v[170:171], v[140:141] op_sel_hi:[1,0,1]
	v_pk_fma_f32 v[112:113], v[112:113], v[170:171], v[128:129] op_sel_hi:[1,0,1]
	v_pk_fma_f32 v[126:127], v[126:127], v[170:171], v[142:143] op_sel_hi:[1,0,1]
	v_pk_fma_f32 v[122:123], v[122:123], v[170:171], v[138:139] op_sel_hi:[1,0,1]
	v_pk_fma_f32 v[120:121], v[120:121], v[170:171], v[136:137] op_sel_hi:[1,0,1]
	v_pk_fma_f32 v[116:117], v[116:117], v[170:171], v[132:133] op_sel_hi:[1,0,1]
	v_pk_fma_f32 v[114:115], v[114:115], v[170:171], v[130:131] op_sel_hi:[1,0,1]
	v_max_f32_e32 v124, 0, v124
	v_max_f32_e32 v125, 0, v125
	v_max_f32_e32 v112, 0, v112
	v_pk_fma_f32 v[118:119], v[118:119], v[170:171], v[134:135] op_sel_hi:[1,0,1]
	v_max_f32_e32 v120, 0, v120
	v_max_f32_e32 v121, 0, v121
	v_max_f32_e32 v126, 0, v126
	v_max_f32_e32 v122, 0, v122
	v_max_f32_e32 v127, 0, v127
	v_max_f32_e32 v123, 0, v123
	v_max_f32_e32 v116, 0, v116
	v_max_f32_e32 v117, 0, v117
	v_max_f32_e32 v113, 0, v113
	v_max_f32_e32 v114, 0, v114
	v_max_f32_e32 v115, 0, v115
	v_mul_f32_e32 v124, v124, v124
	v_mul_f32_e32 v125, v125, v125
	v_mul_f32_e32 v157, v112, v112
	v_cvt_pk_bf16_f32 v112, v124, v125
	v_mul_f32_e32 v174, 0x4b800000, v167
	v_max_f32_e32 v118, 0, v118
	v_max_f32_e32 v119, 0, v119
	v_mul_f32_e32 v120, v120, v120
	v_mul_f32_e32 v121, v121, v121
	v_mul_f32_e32 v126, v126, v126
	v_mul_f32_e32 v122, v122, v122
	v_mul_f32_e32 v127, v127, v127
	v_mul_f32_e32 v123, v123, v123
	v_mul_f32_e32 v116, v116, v116
	v_mul_f32_e32 v117, v117, v117
	v_mul_f32_e32 v170, v113, v113
	v_mul_f32_e32 v175, v114, v114
	v_mul_f32_e32 v176, v115, v115
	v_cvt_pk_bf16_f32 v113, v126, v127
	v_cvt_pk_bf16_f32 v114, v120, v121
	v_cvt_pk_bf16_f32 v115, v122, v123
	global_store_dwordx4 v[154:155], v[112:115], off sc1
	v_cmp_gt_f32_e32 vcc, s5, v167
	v_mul_f32_e32 v118, v118, v118
	v_cvt_pk_bf16_f32 v112, v116, v117
	v_mul_f32_e32 v119, v119, v119
	v_cvt_pk_bf16_f32 v113, v118, v119
	v_cvt_pk_bf16_f32 v114, v157, v170
	v_cvt_pk_bf16_f32 v115, v175, v176
	global_store_dwordx4 v[154:155], v[112:115], off offset:256 sc1
	s_nop 1
	v_cndmask_b32_e32 v112, v167, v174, vcc
	v_rsq_f32_e32 v114, v112
	v_lshlrev_b64 v[112:113], 14, v[168:169]
	v_lshl_add_u64 v[112:113], s[54:55], 0, v[112:113]
	v_lshl_add_u64 v[112:113], v[112:113], 0, v[158:159]
	v_mul_f32_e32 v115, 0x45800000, v114
	v_cndmask_b32_e32 v114, v114, v115, vcc
	v_pk_fma_f32 v[104:105], v[104:105], v[114:115], v[136:137] op_sel_hi:[1,0,1]
	v_pk_fma_f32 v[108:109], v[108:109], v[114:115], v[140:141] op_sel_hi:[1,0,1]
	v_pk_fma_f32 v[106:107], v[106:107], v[114:115], v[138:139] op_sel_hi:[1,0,1]
	v_max_f32_e32 v104, 0, v104
	v_pk_fma_f32 v[110:111], v[110:111], v[114:115], v[142:143] op_sel_hi:[1,0,1]
	v_mul_f32_e32 v115, v104, v104
	v_max_f32_e32 v104, 0, v109
	v_max_f32_e32 v105, 0, v105
	v_max_f32_e32 v106, 0, v106
	v_max_f32_e32 v108, 0, v108
	v_mul_f32_e32 v104, v104, v104
	v_mul_f32_e32 v109, v105, v105
	v_max_f32_e32 v105, 0, v110
	v_mul_f32_e32 v110, v106, v106
	v_max_f32_e32 v106, 0, v111
	v_max_f32_e32 v107, 0, v107
	v_pk_fma_f32 v[98:99], v[98:99], v[114:115], v[130:131] op_sel_hi:[1,0,1]
	v_pk_fma_f32 v[96:97], v[96:97], v[114:115], v[128:129] op_sel_hi:[1,0,1]
	v_mul_f32_e32 v108, v108, v108
	v_mul_f32_e32 v105, v105, v105
	v_mul_f32_e32 v106, v106, v106
	v_mul_f32_e32 v107, v107, v107
	v_cvt_pk_bf16_f32 v104, v108, v104
	v_pk_fma_f32 v[102:103], v[102:103], v[114:115], v[134:135] op_sel_hi:[1,0,1]
	v_pk_fma_f32 v[100:101], v[100:101], v[114:115], v[132:133] op_sel_hi:[1,0,1]
	v_max_f32_e32 v96, 0, v96
	v_max_f32_e32 v97, 0, v97
	v_max_f32_e32 v98, 0, v98
	v_cvt_pk_bf16_f32 v105, v105, v106
	v_cvt_pk_bf16_f32 v106, v115, v109
	v_cvt_pk_bf16_f32 v107, v110, v107
	global_store_dwordx4 v[112:113], v[104:107], off sc1
	v_max_f32_e32 v100, 0, v100
	v_max_f32_e32 v99, 0, v99
	v_mul_f32_e32 v104, v96, v96
	v_max_f32_e32 v96, 0, v101
	v_mul_f32_e32 v101, v97, v97
	v_max_f32_e32 v97, 0, v102
	v_mul_f32_e32 v102, v98, v98
	v_max_f32_e32 v98, 0, v103
	v_mul_f32_e32 v96, v96, v96
	v_mul_f32_e32 v97, v97, v97
	v_mul_f32_e32 v98, v98, v98
	v_mul_f32_e32 v100, v100, v100
	v_mul_f32_e32 v99, v99, v99
	v_cvt_pk_bf16_f32 v96, v100, v96
	v_cvt_pk_bf16_f32 v97, v97, v98
	v_cvt_pk_bf16_f32 v98, v104, v101
	v_cvt_pk_bf16_f32 v99, v102, v99
	global_store_dwordx4 v[112:113], v[96:99], off offset:256 sc1
	s_nop 1
	v_fmamk_f32 v98, v171, 0x3a000000, v229
	v_mul_f32_e32 v99, 0x4b800000, v98
	v_cmp_gt_f32_e32 vcc, s5, v98
	v_or_b32_e32 v96, 32, v156
	v_ashrrev_i32_e32 v97, 31, v96
	v_cndmask_b32_e32 v98, v98, v99, vcc
	v_rsq_f32_e32 v98, v98
	v_lshlrev_b64 v[96:97], 14, v[96:97]
	v_lshl_add_u64 v[96:97], s[54:55], 0, v[96:97]
	v_lshl_add_u64 v[96:97], v[96:97], 0, v[158:159]
	v_mul_f32_e32 v99, 0x45800000, v98
	v_cndmask_b32_e32 v98, v98, v99, vcc
	v_pk_fma_f32 v[88:89], v[88:89], v[98:99], v[136:137] op_sel_hi:[1,0,1]
	v_pk_fma_f32 v[92:93], v[92:93], v[98:99], v[140:141] op_sel_hi:[1,0,1]
	v_pk_fma_f32 v[90:91], v[90:91], v[98:99], v[138:139] op_sel_hi:[1,0,1]
	v_max_f32_e32 v88, 0, v88
	v_pk_fma_f32 v[94:95], v[94:95], v[98:99], v[142:143] op_sel_hi:[1,0,1]
	v_mul_f32_e32 v99, v88, v88
	v_max_f32_e32 v88, 0, v93
	v_max_f32_e32 v89, 0, v89
	v_max_f32_e32 v90, 0, v90
	v_max_f32_e32 v92, 0, v92
	v_mul_f32_e32 v88, v88, v88
	v_mul_f32_e32 v93, v89, v89
	v_max_f32_e32 v89, 0, v94
	v_mul_f32_e32 v94, v90, v90
	v_max_f32_e32 v90, 0, v95
	v_max_f32_e32 v91, 0, v91
	v_pk_fma_f32 v[82:83], v[82:83], v[98:99], v[130:131] op_sel_hi:[1,0,1]
	v_pk_fma_f32 v[80:81], v[80:81], v[98:99], v[128:129] op_sel_hi:[1,0,1]
	v_mul_f32_e32 v92, v92, v92
	v_mul_f32_e32 v89, v89, v89
	v_mul_f32_e32 v90, v90, v90
	v_mul_f32_e32 v91, v91, v91
	v_cvt_pk_bf16_f32 v88, v92, v88
	v_pk_fma_f32 v[86:87], v[86:87], v[98:99], v[134:135] op_sel_hi:[1,0,1]
	v_pk_fma_f32 v[84:85], v[84:85], v[98:99], v[132:133] op_sel_hi:[1,0,1]
	v_max_f32_e32 v80, 0, v80
	v_max_f32_e32 v81, 0, v81
	v_max_f32_e32 v82, 0, v82
	v_cvt_pk_bf16_f32 v89, v89, v90
	v_cvt_pk_bf16_f32 v90, v99, v93
	v_cvt_pk_bf16_f32 v91, v94, v91
	global_store_dwordx4 v[96:97], v[88:91], off sc1
	v_max_f32_e32 v84, 0, v84
	v_max_f32_e32 v83, 0, v83
	v_mul_f32_e32 v88, v80, v80
	v_max_f32_e32 v80, 0, v85
	v_mul_f32_e32 v85, v81, v81
	v_max_f32_e32 v81, 0, v86
	v_mul_f32_e32 v86, v82, v82
	v_max_f32_e32 v82, 0, v87
	v_mul_f32_e32 v80, v80, v80
	v_mul_f32_e32 v81, v81, v81
	v_mul_f32_e32 v82, v82, v82
	v_mul_f32_e32 v84, v84, v84
	v_mul_f32_e32 v83, v83, v83
	v_cvt_pk_bf16_f32 v80, v84, v80
	v_cvt_pk_bf16_f32 v81, v81, v82
	v_cvt_pk_bf16_f32 v82, v88, v85
	v_cvt_pk_bf16_f32 v83, v86, v83
	global_store_dwordx4 v[96:97], v[80:83], off offset:256 sc1
	s_nop 1
	v_fmamk_f32 v82, v172, 0x3a000000, v229
	v_mul_f32_e32 v83, 0x4b800000, v82
	v_cmp_gt_f32_e32 vcc, s5, v82
	v_or_b32_e32 v80, 48, v156
	v_ashrrev_i32_e32 v81, 31, v80
	v_cndmask_b32_e32 v82, v82, v83, vcc
	v_rsq_f32_e32 v82, v82
	v_lshlrev_b64 v[80:81], 14, v[80:81]
	v_lshl_add_u64 v[80:81], s[54:55], 0, v[80:81]
	v_lshl_add_u64 v[80:81], v[80:81], 0, v[158:159]
	v_mul_f32_e32 v83, 0x45800000, v82
	v_cndmask_b32_e32 v82, v82, v83, vcc
	v_pk_fma_f32 v[72:73], v[72:73], v[82:83], v[136:137] op_sel_hi:[1,0,1]
	v_pk_fma_f32 v[76:77], v[76:77], v[82:83], v[140:141] op_sel_hi:[1,0,1]
	v_pk_fma_f32 v[74:75], v[74:75], v[82:83], v[138:139] op_sel_hi:[1,0,1]
	v_max_f32_e32 v72, 0, v72
	v_pk_fma_f32 v[78:79], v[78:79], v[82:83], v[142:143] op_sel_hi:[1,0,1]
	v_mul_f32_e32 v83, v72, v72
	v_max_f32_e32 v72, 0, v77
	v_max_f32_e32 v73, 0, v73
	v_max_f32_e32 v74, 0, v74
	v_max_f32_e32 v76, 0, v76
	v_mul_f32_e32 v72, v72, v72
	v_mul_f32_e32 v77, v73, v73
	v_max_f32_e32 v73, 0, v78
	v_mul_f32_e32 v78, v74, v74
	v_max_f32_e32 v74, 0, v79
	v_max_f32_e32 v75, 0, v75
	v_pk_fma_f32 v[64:65], v[64:65], v[82:83], v[128:129] op_sel_hi:[1,0,1]
	v_mul_f32_e32 v76, v76, v76
	v_mul_f32_e32 v73, v73, v73
	v_mul_f32_e32 v74, v74, v74
	v_mul_f32_e32 v75, v75, v75
	v_cvt_pk_bf16_f32 v72, v76, v72
	v_pk_fma_f32 v[68:69], v[68:69], v[82:83], v[132:133] op_sel_hi:[1,0,1]
	v_pk_fma_f32 v[66:67], v[66:67], v[82:83], v[130:131] op_sel_hi:[1,0,1]
	v_max_f32_e32 v64, 0, v64
	v_cvt_pk_bf16_f32 v73, v73, v74
	v_cvt_pk_bf16_f32 v74, v83, v77
	v_cvt_pk_bf16_f32 v75, v78, v75
	global_store_dwordx4 v[80:81], v[72:75], off sc1
	v_pk_fma_f32 v[70:71], v[70:71], v[82:83], v[134:135] op_sel_hi:[1,0,1]
	v_max_f32_e32 v68, 0, v68
	v_mul_f32_e32 v72, v64, v64
	v_max_f32_e32 v64, 0, v69
	v_max_f32_e32 v65, 0, v65
	v_max_f32_e32 v66, 0, v66
	v_mul_f32_e32 v68, v68, v68
	v_mul_f32_e32 v64, v64, v64
	v_mul_f32_e32 v69, v65, v65
	v_max_f32_e32 v65, 0, v70
	v_mul_f32_e32 v70, v66, v66
	v_max_f32_e32 v66, 0, v71
	v_mul_f32_e32 v65, v65, v65
	v_mul_f32_e32 v66, v66, v66
	v_cvt_pk_bf16_f32 v64, v68, v64
	v_fmamk_f32 v68, v173, 0x3a000000, v229
	v_cvt_pk_bf16_f32 v65, v65, v66
	v_cvt_pk_bf16_f32 v66, v72, v69
	v_mul_f32_e32 v69, 0x4b800000, v68
	v_cmp_gt_f32_e32 vcc, s5, v68
	v_max_f32_e32 v67, 0, v67
	v_mul_f32_e32 v67, v67, v67
	v_cndmask_b32_e32 v68, v68, v69, vcc
	v_rsq_f32_e32 v68, v68
	v_cvt_pk_bf16_f32 v67, v70, v67
	global_store_dwordx4 v[80:81], v[64:67], off offset:256 sc1
	s_nop 1
	v_mul_f32_e32 v66, 0x45800000, v68
	v_cndmask_b32_e32 v66, v68, v66, vcc
	v_pk_fma_f32 v[56:57], v[56:57], v[66:67], v[136:137] op_sel_hi:[1,0,1]
	v_pk_fma_f32 v[60:61], v[60:61], v[66:67], v[140:141] op_sel_hi:[1,0,1]
	v_pk_fma_f32 v[58:59], v[58:59], v[66:67], v[138:139] op_sel_hi:[1,0,1]
	v_max_f32_e32 v56, 0, v56
	v_pk_fma_f32 v[62:63], v[62:63], v[66:67], v[142:143] op_sel_hi:[1,0,1]
	v_max_f32_e32 v60, 0, v60
	v_mul_f32_e32 v67, v56, v56
	v_max_f32_e32 v56, 0, v61
	v_max_f32_e32 v57, 0, v57
	v_max_f32_e32 v58, 0, v58
	v_mul_f32_e32 v60, v60, v60
	v_mul_f32_e32 v56, v56, v56
	v_mul_f32_e32 v61, v57, v57
	v_max_f32_e32 v57, 0, v62
	v_mul_f32_e32 v62, v58, v58
	v_max_f32_e32 v58, 0, v63
	v_mul_f32_e32 v57, v57, v57
	v_max_f32_e32 v59, 0, v59
	v_mul_f32_e32 v58, v58, v58
	v_cvt_pk_bf16_f32 v56, v60, v56
	v_add_co_u32_e32 v60, vcc, s3, v154
	v_pk_fma_f32 v[48:49], v[48:49], v[66:67], v[128:129] op_sel_hi:[1,0,1]
	v_mul_f32_e32 v59, v59, v59
	v_cvt_pk_bf16_f32 v57, v57, v58
	v_cvt_pk_bf16_f32 v58, v67, v61
	v_addc_co_u32_e32 v61, vcc, 0, v155, vcc
	v_pk_fma_f32 v[52:53], v[52:53], v[66:67], v[132:133] op_sel_hi:[1,0,1]
	v_pk_fma_f32 v[50:51], v[50:51], v[66:67], v[130:131] op_sel_hi:[1,0,1]
	v_max_f32_e32 v48, 0, v48
	v_cvt_pk_bf16_f32 v59, v62, v59
	global_store_dwordx4 v[60:61], v[56:59], off sc1
	v_pk_fma_f32 v[54:55], v[54:55], v[66:67], v[134:135] op_sel_hi:[1,0,1]
	v_max_f32_e32 v52, 0, v52
	v_mul_f32_e32 v56, v48, v48
	v_max_f32_e32 v48, 0, v53
	v_max_f32_e32 v49, 0, v49
	v_max_f32_e32 v50, 0, v50
	v_mul_f32_e32 v52, v52, v52
	v_mul_f32_e32 v48, v48, v48
	v_mul_f32_e32 v53, v49, v49
	v_max_f32_e32 v49, 0, v54
	v_mul_f32_e32 v54, v50, v50
	v_max_f32_e32 v50, 0, v55
	v_mul_f32_e32 v49, v49, v49
	v_mul_f32_e32 v50, v50, v50
	v_cvt_pk_bf16_f32 v48, v52, v48
	v_fmamk_f32 v52, v166, 0x3a000000, v229
	v_cvt_pk_bf16_f32 v49, v49, v50
	v_cvt_pk_bf16_f32 v50, v56, v53
	v_mul_f32_e32 v53, 0x4b800000, v52
	v_cmp_gt_f32_e32 vcc, s5, v52
	v_max_f32_e32 v51, 0, v51
	v_lshl_add_u64 v[64:65], v[154:155], 0, s[12:13]
	v_cndmask_b32_e32 v52, v52, v53, vcc
	v_rsq_f32_e32 v52, v52
	v_mul_f32_e32 v51, v51, v51
	v_cvt_pk_bf16_f32 v51, v54, v51
	global_store_dwordx4 v[64:65], v[48:51], off offset:256 sc1
	s_mov_b32 s3, 0x240000
	s_mov_b64 s[12:13], 0x240000
	v_mul_f32_e32 v50, 0x45800000, v52
	v_cndmask_b32_e32 v50, v52, v50, vcc
	v_pk_fma_f32 v[40:41], v[40:41], v[50:51], v[136:137] op_sel_hi:[1,0,1]
	v_pk_fma_f32 v[44:45], v[44:45], v[50:51], v[140:141] op_sel_hi:[1,0,1]
	v_pk_fma_f32 v[42:43], v[42:43], v[50:51], v[138:139] op_sel_hi:[1,0,1]
	v_max_f32_e32 v40, 0, v40
	v_pk_fma_f32 v[46:47], v[46:47], v[50:51], v[142:143] op_sel_hi:[1,0,1]
	v_max_f32_e32 v44, 0, v44
	v_mul_f32_e32 v51, v40, v40
	v_max_f32_e32 v40, 0, v45
	v_max_f32_e32 v41, 0, v41
	v_max_f32_e32 v42, 0, v42
	v_mul_f32_e32 v44, v44, v44
	v_mul_f32_e32 v40, v40, v40
	v_mul_f32_e32 v45, v41, v41
	v_max_f32_e32 v41, 0, v46
	v_mul_f32_e32 v46, v42, v42
	v_max_f32_e32 v42, 0, v47
	v_mul_f32_e32 v41, v41, v41
	v_max_f32_e32 v43, 0, v43
	v_mul_f32_e32 v42, v42, v42
	v_cvt_pk_bf16_f32 v40, v44, v40
	v_add_co_u32_e32 v44, vcc, s3, v154
	v_pk_fma_f32 v[32:33], v[32:33], v[50:51], v[128:129] op_sel_hi:[1,0,1]
	v_mul_f32_e32 v43, v43, v43
	v_cvt_pk_bf16_f32 v41, v41, v42
	v_cvt_pk_bf16_f32 v42, v51, v45
	v_addc_co_u32_e32 v45, vcc, 0, v155, vcc
	v_pk_fma_f32 v[36:37], v[36:37], v[50:51], v[132:133] op_sel_hi:[1,0,1]
	v_pk_fma_f32 v[34:35], v[34:35], v[50:51], v[130:131] op_sel_hi:[1,0,1]
	v_max_f32_e32 v32, 0, v32
	v_cvt_pk_bf16_f32 v43, v46, v43
	global_store_dwordx4 v[44:45], v[40:43], off sc1
	v_pk_fma_f32 v[38:39], v[38:39], v[50:51], v[134:135] op_sel_hi:[1,0,1]
	v_max_f32_e32 v36, 0, v36
	v_mul_f32_e32 v40, v32, v32
	v_max_f32_e32 v32, 0, v37
	v_max_f32_e32 v33, 0, v33
	v_max_f32_e32 v34, 0, v34
	v_mul_f32_e32 v36, v36, v36
	v_mul_f32_e32 v32, v32, v32
	v_mul_f32_e32 v37, v33, v33
	v_max_f32_e32 v33, 0, v38
	v_mul_f32_e32 v38, v34, v34
	v_max_f32_e32 v34, 0, v39
	v_mul_f32_e32 v33, v33, v33
	v_mul_f32_e32 v34, v34, v34
	v_cvt_pk_bf16_f32 v32, v36, v32
	v_fmamk_f32 v36, v165, 0x3a000000, v229
	v_cvt_pk_bf16_f32 v33, v33, v34
	v_cvt_pk_bf16_f32 v34, v40, v37
	v_mul_f32_e32 v37, 0x4b800000, v36
	v_cmp_gt_f32_e32 vcc, s5, v36
	v_max_f32_e32 v35, 0, v35
	v_lshl_add_u64 v[48:49], v[154:155], 0, s[12:13]
	v_cndmask_b32_e32 v36, v36, v37, vcc
	v_rsq_f32_e32 v36, v36
	v_mul_f32_e32 v35, v35, v35
	v_cvt_pk_bf16_f32 v35, v38, v35
	global_store_dwordx4 v[48:49], v[32:35], off offset:256 sc1
	s_mov_b32 s3, 0x280000
	s_mov_b64 s[12:13], 0x280000
	v_mul_f32_e32 v34, 0x45800000, v36
	v_cndmask_b32_e32 v34, v36, v34, vcc
	v_pk_fma_f32 v[24:25], v[24:25], v[34:35], v[136:137] op_sel_hi:[1,0,1]
	v_pk_fma_f32 v[28:29], v[28:29], v[34:35], v[140:141] op_sel_hi:[1,0,1]
	v_pk_fma_f32 v[26:27], v[26:27], v[34:35], v[138:139] op_sel_hi:[1,0,1]
	v_max_f32_e32 v24, 0, v24
	v_pk_fma_f32 v[30:31], v[30:31], v[34:35], v[142:143] op_sel_hi:[1,0,1]
	v_max_f32_e32 v28, 0, v28
	v_mul_f32_e32 v35, v24, v24
	v_max_f32_e32 v24, 0, v29
	v_max_f32_e32 v25, 0, v25
	v_max_f32_e32 v26, 0, v26
	v_mul_f32_e32 v28, v28, v28
	v_mul_f32_e32 v24, v24, v24
	v_mul_f32_e32 v29, v25, v25
	v_max_f32_e32 v25, 0, v30
	v_mul_f32_e32 v30, v26, v26
	v_max_f32_e32 v26, 0, v31
	v_mul_f32_e32 v25, v25, v25
	v_max_f32_e32 v27, 0, v27
	v_mul_f32_e32 v26, v26, v26
	v_cvt_pk_bf16_f32 v24, v28, v24
	v_add_co_u32_e32 v28, vcc, s3, v154
	v_pk_fma_f32 v[16:17], v[16:17], v[34:35], v[128:129] op_sel_hi:[1,0,1]
	v_mul_f32_e32 v27, v27, v27
	v_cvt_pk_bf16_f32 v25, v25, v26
	v_cvt_pk_bf16_f32 v26, v35, v29
	v_addc_co_u32_e32 v29, vcc, 0, v155, vcc
	v_pk_fma_f32 v[20:21], v[20:21], v[34:35], v[132:133] op_sel_hi:[1,0,1]
	v_pk_fma_f32 v[18:19], v[18:19], v[34:35], v[130:131] op_sel_hi:[1,0,1]
	v_max_f32_e32 v16, 0, v16
	v_cvt_pk_bf16_f32 v27, v30, v27
	global_store_dwordx4 v[28:29], v[24:27], off sc1
	v_pk_fma_f32 v[22:23], v[22:23], v[34:35], v[134:135] op_sel_hi:[1,0,1]
	v_max_f32_e32 v20, 0, v20
	v_mul_f32_e32 v24, v16, v16
	v_max_f32_e32 v16, 0, v21
	v_max_f32_e32 v17, 0, v17
	v_max_f32_e32 v18, 0, v18
	v_mul_f32_e32 v20, v20, v20
	v_mul_f32_e32 v16, v16, v16
	v_mul_f32_e32 v21, v17, v17
	v_max_f32_e32 v17, 0, v22
	v_mul_f32_e32 v22, v18, v18
	v_max_f32_e32 v18, 0, v23
	v_mul_f32_e32 v17, v17, v17
	v_mul_f32_e32 v18, v18, v18
	v_cvt_pk_bf16_f32 v16, v20, v16
	v_fmamk_f32 v20, v164, 0x3a000000, v229
	v_cvt_pk_bf16_f32 v17, v17, v18
	v_cvt_pk_bf16_f32 v18, v24, v21
	v_mul_f32_e32 v21, 0x4b800000, v20
	v_cmp_gt_f32_e32 vcc, s5, v20
	v_max_f32_e32 v19, 0, v19
	v_lshl_add_u64 v[32:33], v[154:155], 0, s[12:13]
	v_cndmask_b32_e32 v20, v20, v21, vcc
	v_rsq_f32_e32 v20, v20
	v_mul_f32_e32 v19, v19, v19
	v_cvt_pk_bf16_f32 v19, v22, v19
	global_store_dwordx4 v[32:33], v[16:19], off offset:256 sc1
	s_mov_b32 s3, 0x2c0000
	s_mov_b64 s[12:13], 0x2c0000
	v_mul_f32_e32 v18, 0x45800000, v20
	v_cndmask_b32_e32 v18, v20, v18, vcc
	v_pk_fma_f32 v[8:9], v[8:9], v[18:19], v[136:137] op_sel_hi:[1,0,1]
	v_pk_fma_f32 v[12:13], v[12:13], v[18:19], v[140:141] op_sel_hi:[1,0,1]
	v_pk_fma_f32 v[10:11], v[10:11], v[18:19], v[138:139] op_sel_hi:[1,0,1]
	v_max_f32_e32 v8, 0, v8
	v_pk_fma_f32 v[14:15], v[14:15], v[18:19], v[142:143] op_sel_hi:[1,0,1]
	v_max_f32_e32 v12, 0, v12
	v_mul_f32_e32 v19, v8, v8
	v_max_f32_e32 v8, 0, v13
	v_max_f32_e32 v9, 0, v9
	v_max_f32_e32 v10, 0, v10
	v_mul_f32_e32 v12, v12, v12
	v_mul_f32_e32 v8, v8, v8
	v_mul_f32_e32 v13, v9, v9
	v_max_f32_e32 v9, 0, v14
	v_mul_f32_e32 v14, v10, v10
	v_max_f32_e32 v10, 0, v15
	v_mul_f32_e32 v9, v9, v9
	v_max_f32_e32 v11, 0, v11
	v_mul_f32_e32 v10, v10, v10
	v_cvt_pk_bf16_f32 v8, v12, v8
	v_add_co_u32_e32 v12, vcc, s3, v154
	v_pk_fma_f32 v[2:3], v[2:3], v[18:19], v[130:131] op_sel_hi:[1,0,1]
	v_pk_fma_f32 v[0:1], v[0:1], v[18:19], v[128:129] op_sel_hi:[1,0,1]
	v_mul_f32_e32 v11, v11, v11
	v_cvt_pk_bf16_f32 v9, v9, v10
	v_cvt_pk_bf16_f32 v10, v19, v13
	v_addc_co_u32_e32 v13, vcc, 0, v155, vcc
	v_pk_fma_f32 v[6:7], v[6:7], v[18:19], v[134:135] op_sel_hi:[1,0,1]
	v_pk_fma_f32 v[4:5], v[4:5], v[18:19], v[132:133] op_sel_hi:[1,0,1]
	v_max_f32_e32 v0, 0, v0
	v_max_f32_e32 v1, 0, v1
	v_max_f32_e32 v2, 0, v2
	v_cvt_pk_bf16_f32 v11, v14, v11
	global_store_dwordx4 v[12:13], v[8:11], off sc1
	v_max_f32_e32 v3, 0, v3
	v_lshl_add_u64 v[16:17], v[154:155], 0, s[12:13]
	v_mul_f32_e32 v8, v0, v0
	v_max_f32_e32 v0, 0, v5
	v_mul_f32_e32 v5, v1, v1
	v_max_f32_e32 v1, 0, v6
	v_mul_f32_e32 v6, v2, v2
	v_max_f32_e32 v2, 0, v7
	v_max_f32_e32 v4, 0, v4
	v_mul_f32_e32 v0, v0, v0
	v_mul_f32_e32 v1, v1, v1
	v_mul_f32_e32 v2, v2, v2
	v_mul_f32_e32 v3, v3, v3
	s_and_b64 vcc, exec, s[42:43]
	s_mov_b64 s[12:13], s[18:19]
	v_mul_f32_e32 v4, v4, v4
	v_cvt_pk_bf16_f32 v0, v4, v0
	v_cvt_pk_bf16_f32 v1, v1, v2
	v_cvt_pk_bf16_f32 v2, v8, v5
	v_cvt_pk_bf16_f32 v3, v6, v3
	global_store_dwordx4 v[16:17], v[0:3], off offset:256 sc1
	s_cbranch_vccz .LBB0_796
	s_waitcnt vmcnt(0)
	s_cmpk_gt_u32 s22, 0xff
	v_readlane_b32 s35, v252, 37
	s_cbranch_scc1 .LBB0_807
	s_barrier

.LBB0_881:
	s_or_b64 exec, exec, s[12:13]
	v_lshl_add_u64 v[20:21], v[16:17], 0, v[154:155]
	v_lshl_add_u64 v[16:17], s[66:67], 0, v[18:19]
	v_lshl_add_u64 v[22:23], v[16:17], 0, v[154:155]
	global_load_dwordx4 v[16:19], v[20:21], off
	s_and_b64 vcc, exec, s[44:45]
	s_mov_b32 s53, s18
	s_mov_b32 s56, s28
	s_mov_b64 s[20:21], s[2:3]
	s_mov_b64 s[12:13], s[38:39]
	s_waitcnt vmcnt(0)
	v_pk_fma_f32 v[14:15], v[14:15], v[126:127], v[18:19]
	v_pk_fma_f32 v[12:13], v[12:13], v[124:125], v[16:17]
	global_store_dwordx4 v[22:23], v[12:15], off sc1
	global_load_dwordx4 v[12:15], v[20:21], off offset:64
	s_waitcnt vmcnt(0)
	v_pk_fma_f32 v[10:11], v[10:11], v[118:119], v[14:15]
	v_pk_fma_f32 v[8:9], v[8:9], v[116:117], v[12:13]
	global_store_dwordx4 v[22:23], v[8:11], off offset:64 sc1
	global_load_dwordx4 v[8:11], v[20:21], off offset:512
	s_waitcnt vmcnt(0)
	v_pk_fma_f32 v[6:7], v[6:7], v[110:111], v[10:11]
	v_pk_fma_f32 v[4:5], v[4:5], v[108:109], v[8:9]
	global_store_dwordx4 v[22:23], v[4:7], off offset:512 sc1
	global_load_dwordx4 v[4:7], v[20:21], off offset:576
	s_waitcnt vmcnt(0)
	v_pk_fma_f32 v[2:3], v[2:3], v[106:107], v[6:7]
	v_pk_fma_f32 v[0:1], v[0:1], v[104:105], v[4:5]
	global_store_dwordx4 v[22:23], v[0:3], off offset:576 sc1
	s_cbranch_vccnz .LBB0_922

.LBB0_889:
	s_add_u32 s4, s12, 0xffe00080
	s_addc_u32 s20, s13, -1
	s_add_i32 s58, 0, 0x10000
	v_add_u32_e32 v124, s58, v161
	ds_read_b128 v[104:107], v124
	ds_read_b128 v[108:111], v124 offset:1024
	ds_read_b128 v[116:119], v124 offset:2048
	ds_read_b128 v[124:127], v124 offset:3072
	s_cmpk_eq_i32 vcc_hi, 0x7c
	s_cselect_b32 s25, s29, s20
	s_cselect_b32 s24, s57, s4
	s_cselect_b32 s21, s19, vcc_lo
	s_cselect_b32 s20, s68, s69
	v_lshl_add_u64 v[200:201], s[12:13], 0, v[148:149]
	s_add_i32 m0, s22, 0xc000
	ds_read_b128 v[152:155], v163
	ds_read_b128 v[156:159], v163 offset:1024
	ds_read_b128 v[164:167], v163 offset:2048
	ds_read_b128 v[168:171], v163 offset:3072
	ds_read_b128 v[172:175], v163 offset:4096
	ds_read_b128 v[176:179], v163 offset:5120
	ds_read_b128 v[180:183], v163 offset:6144
	ds_read_b128 v[196:199], v163 offset:7168
	global_load_lds_dwordx4 v[200:201], off
	v_lshl_add_u64 v[200:201], s[12:13], 0, v[150:151]
	s_add_i32 m0, s22, 0xe000
	s_nop 0
	global_load_lds_dwordx4 v[200:201], off
	v_add_u32_e32 v212, 0x14000, v161
	ds_read_b128 v[200:203], v212
	ds_read_b128 v[204:207], v212 offset:1024
	ds_read_b128 v[208:211], v212 offset:2048
	ds_read_b128 v[212:215], v212 offset:3072
	s_waitcnt vmcnt(8)
	s_waitcnt lgkmcnt(0)
	s_barrier
	s_setprio 1
	v_mfma_f32_16x16x32_bf16 v[140:143], v[104:107], v[152:155], v[140:143]
	v_mfma_f32_16x16x32_bf16 v[136:139], v[116:119], v[152:155], v[136:139]
	v_mfma_f32_16x16x32_bf16 v[120:123], v[104:107], v[164:167], v[120:123]
	v_mfma_f32_16x16x32_bf16 v[112:115], v[116:119], v[164:167], v[112:115]
	v_mfma_f32_16x16x32_bf16 v[92:95], v[104:107], v[172:175], v[92:95]
	v_mfma_f32_16x16x32_bf16 v[88:91], v[116:119], v[172:175], v[88:91]
	v_mfma_f32_16x16x32_bf16 v[76:79], v[104:107], v[180:183], v[76:79]
	v_mfma_f32_16x16x32_bf16 v[72:75], v[116:119], v[180:183], v[72:75]
	v_mfma_f32_16x16x32_bf16 v[140:143], v[108:111], v[156:159], v[140:143]
	v_mfma_f32_16x16x32_bf16 v[136:139], v[124:127], v[156:159], v[136:139]
	v_mfma_f32_16x16x32_bf16 v[120:123], v[108:111], v[168:171], v[120:123]
	v_mfma_f32_16x16x32_bf16 v[112:115], v[124:127], v[168:171], v[112:115]
	v_mfma_f32_16x16x32_bf16 v[92:95], v[108:111], v[176:179], v[92:95]
	v_mfma_f32_16x16x32_bf16 v[88:91], v[124:127], v[176:179], v[88:91]
	v_mfma_f32_16x16x32_bf16 v[76:79], v[108:111], v[196:199], v[76:79]
	v_mfma_f32_16x16x32_bf16 v[72:75], v[124:127], v[196:199], v[72:75]
	v_mfma_f32_16x16x32_bf16 v[132:135], v[200:203], v[152:155], v[132:135]
	v_mfma_f32_16x16x32_bf16 v[128:131], v[208:211], v[152:155], v[128:131]
	v_mfma_f32_16x16x32_bf16 v[100:103], v[200:203], v[164:167], v[100:103]
	v_mfma_f32_16x16x32_bf16 v[96:99], v[208:211], v[164:167], v[96:99]
	v_mfma_f32_16x16x32_bf16 v[84:87], v[200:203], v[172:175], v[84:87]
	v_mfma_f32_16x16x32_bf16 v[80:83], v[208:211], v[172:175], v[80:83]
	v_mfma_f32_16x16x32_bf16 v[68:71], v[200:203], v[180:183], v[68:71]
	v_mfma_f32_16x16x32_bf16 v[64:67], v[208:211], v[180:183], v[64:67]
	v_mfma_f32_16x16x32_bf16 v[132:135], v[204:207], v[156:159], v[132:135]
	v_mfma_f32_16x16x32_bf16 v[128:131], v[212:215], v[156:159], v[128:131]
	v_mfma_f32_16x16x32_bf16 v[100:103], v[204:207], v[168:171], v[100:103]
	v_mfma_f32_16x16x32_bf16 v[96:99], v[212:215], v[168:171], v[96:99]
	v_mfma_f32_16x16x32_bf16 v[84:87], v[204:207], v[176:179], v[84:87]
	v_mfma_f32_16x16x32_bf16 v[80:83], v[212:215], v[176:179], v[80:83]
	v_mfma_f32_16x16x32_bf16 v[68:71], v[204:207], v[196:199], v[68:71]
	v_mfma_f32_16x16x32_bf16 v[64:67], v[212:215], v[196:199], v[64:67]
	s_setprio 0
	s_barrier
	s_add_i32 s4, 0, 0x14000
	s_add_i32 s58, s58, s27
	v_lshl_add_u64 v[216:217], s[20:21], 0, v[146:147]
	s_mov_b32 m0, s58
	global_load_lds_dwordx4 v[216:217], off
	v_lshl_add_u64 v[218:219], s[20:21], 0, v[144:145]
	s_add_i32 m0, s58, 0x2000
	s_nop 0
	global_load_lds_dwordx4 v[218:219], off
	s_mov_b32 m0, s22
	v_lshl_add_u64 v[220:221], s[24:25], 0, v[146:147]
	ds_read_b128 v[152:155], v163 offset:16384
	ds_read_b128 v[156:159], v163 offset:17408
	ds_read_b128 v[164:167], v163 offset:18432
	ds_read_b128 v[168:171], v163 offset:19456
	ds_read_b128 v[172:175], v163 offset:20480
	ds_read_b128 v[176:179], v163 offset:21504
	ds_read_b128 v[180:183], v163 offset:22528
	ds_read_b128 v[196:199], v163 offset:23552
	global_load_lds_dwordx4 v[220:221], off
	v_lshl_add_u64 v[222:223], s[24:25], 0, v[144:145]
	s_mov_b32 m0, s23
	s_nop 0
	global_load_lds_dwordx4 v[222:223], off
	s_waitcnt vmcnt(6)
	s_waitcnt lgkmcnt(0)
	s_barrier
	s_setprio 1
	v_mfma_f32_16x16x32_bf16 v[60:63], v[104:107], v[152:155], v[60:63]
	v_mfma_f32_16x16x32_bf16 v[56:59], v[116:119], v[152:155], v[56:59]
	v_mfma_f32_16x16x32_bf16 v[44:47], v[104:107], v[164:167], v[44:47]
	v_mfma_f32_16x16x32_bf16 v[40:43], v[116:119], v[164:167], v[40:43]
	v_mfma_f32_16x16x32_bf16 v[28:31], v[104:107], v[172:175], v[28:31]
	v_mfma_f32_16x16x32_bf16 v[24:27], v[116:119], v[172:175], v[24:27]
	v_mfma_f32_16x16x32_bf16 v[12:15], v[104:107], v[180:183], v[12:15]
	v_mfma_f32_16x16x32_bf16 v[8:11], v[116:119], v[180:183], v[8:11]
	v_mfma_f32_16x16x32_bf16 v[60:63], v[108:111], v[156:159], v[60:63]
	v_mfma_f32_16x16x32_bf16 v[56:59], v[124:127], v[156:159], v[56:59]
	v_mfma_f32_16x16x32_bf16 v[44:47], v[108:111], v[168:171], v[44:47]
	v_mfma_f32_16x16x32_bf16 v[40:43], v[124:127], v[168:171], v[40:43]
	v_mfma_f32_16x16x32_bf16 v[28:31], v[108:111], v[176:179], v[28:31]
	v_mfma_f32_16x16x32_bf16 v[24:27], v[124:127], v[176:179], v[24:27]
	v_mfma_f32_16x16x32_bf16 v[12:15], v[108:111], v[196:199], v[12:15]
	v_mfma_f32_16x16x32_bf16 v[8:11], v[124:127], v[196:199], v[8:11]
	v_mfma_f32_16x16x32_bf16 v[52:55], v[200:203], v[152:155], v[52:55]
	v_mfma_f32_16x16x32_bf16 v[48:51], v[208:211], v[152:155], v[48:51]
	v_mfma_f32_16x16x32_bf16 v[36:39], v[200:203], v[164:167], v[36:39]
	v_mfma_f32_16x16x32_bf16 v[32:35], v[208:211], v[164:167], v[32:35]
	v_mfma_f32_16x16x32_bf16 v[20:23], v[200:203], v[172:175], v[20:23]
	v_mfma_f32_16x16x32_bf16 v[16:19], v[208:211], v[172:175], v[16:19]
	v_mfma_f32_16x16x32_bf16 v[4:7], v[200:203], v[180:183], v[4:7]
	v_mfma_f32_16x16x32_bf16 v[0:3], v[208:211], v[180:183], v[0:3]
	v_mfma_f32_16x16x32_bf16 v[52:55], v[204:207], v[156:159], v[52:55]
	v_mfma_f32_16x16x32_bf16 v[48:51], v[212:215], v[156:159], v[48:51]
	v_mfma_f32_16x16x32_bf16 v[36:39], v[204:207], v[168:171], v[36:39]
	v_mfma_f32_16x16x32_bf16 v[32:35], v[212:215], v[168:171], v[32:35]
	v_mfma_f32_16x16x32_bf16 v[20:23], v[204:207], v[176:179], v[20:23]
	v_mfma_f32_16x16x32_bf16 v[16:19], v[212:215], v[176:179], v[16:19]
	v_mfma_f32_16x16x32_bf16 v[4:7], v[204:207], v[196:199], v[4:7]
	v_mfma_f32_16x16x32_bf16 v[0:3], v[212:215], v[196:199], v[0:3]
	s_setprio 0
	s_barrier
	s_add_u32 s58, s20, 0x200000
	s_addc_u32 s59, s21, 0
	s_add_i32 s4, s4, s27
	v_lshl_add_u64 v[104:105], s[58:59], 0, v[146:147]
	s_mov_b32 m0, s4
	s_nop 0
	global_load_lds_dwordx4 v[104:105], off
	v_lshl_add_u64 v[104:105], s[58:59], 0, v[144:145]
	s_add_i32 m0, s4, 0x2000
	s_nop 0
	global_load_lds_dwordx4 v[104:105], off
	s_add_i32 s4, 0, 0x18000
	v_add_u32_e32 v124, s4, v161
	ds_read_b128 v[104:107], v124
	ds_read_b128 v[108:111], v124 offset:1024
	ds_read_b128 v[116:119], v124 offset:2048
	ds_read_b128 v[124:127], v124 offset:3072
	s_add_u32 s24, s24, 0x200000
	s_addc_u32 s25, s25, 0
	s_mov_b32 m0, s30
	v_lshl_add_u64 v[200:201], s[24:25], 0, v[146:147]
	ds_read_b128 v[152:155], v163 offset:32768
	ds_read_b128 v[156:159], v163 offset:33792
	ds_read_b128 v[164:167], v163 offset:34816
	ds_read_b128 v[168:171], v163 offset:35840
	ds_read_b128 v[172:175], v163 offset:36864
	ds_read_b128 v[176:179], v163 offset:37888
	ds_read_b128 v[180:183], v163 offset:38912
	ds_read_b128 v[196:199], v163 offset:39936
	global_load_lds_dwordx4 v[200:201], off
	v_lshl_add_u64 v[200:201], s[24:25], 0, v[144:145]
	s_mov_b32 m0, s31
	s_nop 0
	global_load_lds_dwordx4 v[200:201], off
	v_add_u32_e32 v212, 0x1c000, v161
	ds_read_b128 v[200:203], v212
	ds_read_b128 v[204:207], v212 offset:1024
	ds_read_b128 v[208:211], v212 offset:2048
	ds_read_b128 v[212:215], v212 offset:3072
	s_waitcnt vmcnt(8)
	s_waitcnt lgkmcnt(0)
	s_barrier
	s_setprio 1
	v_mfma_f32_16x16x32_bf16 v[140:143], v[104:107], v[152:155], v[140:143]
	v_mfma_f32_16x16x32_bf16 v[136:139], v[116:119], v[152:155], v[136:139]
	v_mfma_f32_16x16x32_bf16 v[120:123], v[104:107], v[164:167], v[120:123]
	v_mfma_f32_16x16x32_bf16 v[112:115], v[116:119], v[164:167], v[112:115]
	v_mfma_f32_16x16x32_bf16 v[92:95], v[104:107], v[172:175], v[92:95]
	v_mfma_f32_16x16x32_bf16 v[88:91], v[116:119], v[172:175], v[88:91]
	v_mfma_f32_16x16x32_bf16 v[76:79], v[104:107], v[180:183], v[76:79]
	v_mfma_f32_16x16x32_bf16 v[72:75], v[116:119], v[180:183], v[72:75]
	v_mfma_f32_16x16x32_bf16 v[140:143], v[108:111], v[156:159], v[140:143]
	v_mfma_f32_16x16x32_bf16 v[136:139], v[124:127], v[156:159], v[136:139]
	v_mfma_f32_16x16x32_bf16 v[120:123], v[108:111], v[168:171], v[120:123]
	v_mfma_f32_16x16x32_bf16 v[112:115], v[124:127], v[168:171], v[112:115]
	v_mfma_f32_16x16x32_bf16 v[92:95], v[108:111], v[176:179], v[92:95]
	v_mfma_f32_16x16x32_bf16 v[88:91], v[124:127], v[176:179], v[88:91]
	v_mfma_f32_16x16x32_bf16 v[76:79], v[108:111], v[196:199], v[76:79]
	v_mfma_f32_16x16x32_bf16 v[72:75], v[124:127], v[196:199], v[72:75]
	v_mfma_f32_16x16x32_bf16 v[132:135], v[200:203], v[152:155], v[132:135]
	v_mfma_f32_16x16x32_bf16 v[128:131], v[208:211], v[152:155], v[128:131]
	v_mfma_f32_16x16x32_bf16 v[100:103], v[200:203], v[164:167], v[100:103]
	v_mfma_f32_16x16x32_bf16 v[96:99], v[208:211], v[164:167], v[96:99]
	v_mfma_f32_16x16x32_bf16 v[84:87], v[200:203], v[172:175], v[84:87]
	v_mfma_f32_16x16x32_bf16 v[80:83], v[208:211], v[172:175], v[80:83]
	v_mfma_f32_16x16x32_bf16 v[68:71], v[200:203], v[180:183], v[68:71]
	v_mfma_f32_16x16x32_bf16 v[64:67], v[208:211], v[180:183], v[64:67]
	v_mfma_f32_16x16x32_bf16 v[132:135], v[204:207], v[156:159], v[132:135]
	v_mfma_f32_16x16x32_bf16 v[128:131], v[212:215], v[156:159], v[128:131]
	v_mfma_f32_16x16x32_bf16 v[100:103], v[204:207], v[168:171], v[100:103]
	v_mfma_f32_16x16x32_bf16 v[96:99], v[212:215], v[168:171], v[96:99]
	v_mfma_f32_16x16x32_bf16 v[84:87], v[204:207], v[176:179], v[84:87]
	v_mfma_f32_16x16x32_bf16 v[80:83], v[212:215], v[176:179], v[80:83]
	v_mfma_f32_16x16x32_bf16 v[68:71], v[204:207], v[196:199], v[68:71]
	v_mfma_f32_16x16x32_bf16 v[64:67], v[212:215], v[196:199], v[64:67]
	s_setprio 0
	s_barrier
	s_add_i32 s24, 0, 0x1c000
	s_add_i32 s4, s4, s27
	v_lshl_add_u64 v[216:217], v[216:217], 0, s[0:1]
	s_mov_b32 m0, s4
	global_load_lds_dwordx4 v[216:217], off
	v_lshl_add_u64 v[216:217], v[218:219], 0, s[0:1]
	s_add_i32 m0, s4, 0x2000
	s_nop 0
	global_load_lds_dwordx4 v[216:217], off
	s_mov_b32 m0, s16
	v_lshl_add_u64 v[216:217], v[220:221], 0, s[0:1]
	ds_read_b128 v[152:155], v163 offset:49152
	ds_read_b128 v[156:159], v163 offset:50176
	ds_read_b128 v[164:167], v163 offset:51200
	ds_read_b128 v[168:171], v163 offset:52224
	ds_read_b128 v[172:175], v163 offset:53248
	ds_read_b128 v[176:179], v163 offset:54272
	ds_read_b128 v[180:183], v163 offset:55296
	ds_read_b128 v[196:199], v163 offset:56320
	global_load_lds_dwordx4 v[216:217], off
	v_lshl_add_u64 v[216:217], v[222:223], 0, s[0:1]
	s_mov_b32 m0, s17
	s_nop 0
	global_load_lds_dwordx4 v[216:217], off
	s_add_u32 s20, s20, 0x200080
	s_addc_u32 s21, s21, 0
	s_add_i32 s4, s24, s27
	v_lshl_add_u64 v[216:217], s[20:21], 0, v[146:147]
	s_mov_b32 m0, s4
	s_nop 0
	global_load_lds_dwordx4 v[216:217], off
	v_lshl_add_u64 v[216:217], s[20:21], 0, v[144:145]
	s_add_i32 m0, s4, 0x2000
	s_nop 0
	global_load_lds_dwordx4 v[216:217], off
	s_waitcnt vmcnt(8)
	s_waitcnt lgkmcnt(0)
	s_barrier
	s_setprio 1
	v_mfma_f32_16x16x32_bf16 v[60:63], v[104:107], v[152:155], v[60:63]
	v_mfma_f32_16x16x32_bf16 v[56:59], v[116:119], v[152:155], v[56:59]
	v_mfma_f32_16x16x32_bf16 v[44:47], v[104:107], v[164:167], v[44:47]
	v_mfma_f32_16x16x32_bf16 v[40:43], v[116:119], v[164:167], v[40:43]
	v_mfma_f32_16x16x32_bf16 v[28:31], v[104:107], v[172:175], v[28:31]
	v_mfma_f32_16x16x32_bf16 v[24:27], v[116:119], v[172:175], v[24:27]
	v_mfma_f32_16x16x32_bf16 v[12:15], v[104:107], v[180:183], v[12:15]
	v_mfma_f32_16x16x32_bf16 v[8:11], v[116:119], v[180:183], v[8:11]
	v_mfma_f32_16x16x32_bf16 v[60:63], v[108:111], v[156:159], v[60:63]
	v_mfma_f32_16x16x32_bf16 v[56:59], v[124:127], v[156:159], v[56:59]
	v_mfma_f32_16x16x32_bf16 v[44:47], v[108:111], v[168:171], v[44:47]
	v_mfma_f32_16x16x32_bf16 v[40:43], v[124:127], v[168:171], v[40:43]
	v_mfma_f32_16x16x32_bf16 v[28:31], v[108:111], v[176:179], v[28:31]
	v_mfma_f32_16x16x32_bf16 v[24:27], v[124:127], v[176:179], v[24:27]
	v_mfma_f32_16x16x32_bf16 v[12:15], v[108:111], v[196:199], v[12:15]
	v_mfma_f32_16x16x32_bf16 v[8:11], v[124:127], v[196:199], v[8:11]
	v_mfma_f32_16x16x32_bf16 v[52:55], v[200:203], v[152:155], v[52:55]
	v_mfma_f32_16x16x32_bf16 v[48:51], v[208:211], v[152:155], v[48:51]
	v_mfma_f32_16x16x32_bf16 v[36:39], v[200:203], v[164:167], v[36:39]
	v_mfma_f32_16x16x32_bf16 v[32:35], v[208:211], v[164:167], v[32:35]
	v_mfma_f32_16x16x32_bf16 v[20:23], v[200:203], v[172:175], v[20:23]
	v_mfma_f32_16x16x32_bf16 v[16:19], v[208:211], v[172:175], v[16:19]
	v_mfma_f32_16x16x32_bf16 v[4:7], v[200:203], v[180:183], v[4:7]
	v_mfma_f32_16x16x32_bf16 v[0:3], v[208:211], v[180:183], v[0:3]
	v_mfma_f32_16x16x32_bf16 v[52:55], v[204:207], v[156:159], v[52:55]
	v_mfma_f32_16x16x32_bf16 v[48:51], v[212:215], v[156:159], v[48:51]
	v_mfma_f32_16x16x32_bf16 v[36:39], v[204:207], v[168:171], v[36:39]
	v_mfma_f32_16x16x32_bf16 v[32:35], v[212:215], v[168:171], v[32:35]
	v_mfma_f32_16x16x32_bf16 v[20:23], v[204:207], v[176:179], v[20:23]
	v_mfma_f32_16x16x32_bf16 v[16:19], v[212:215], v[176:179], v[16:19]
	v_mfma_f32_16x16x32_bf16 v[4:7], v[204:207], v[196:199], v[4:7]
	v_mfma_f32_16x16x32_bf16 v[0:3], v[212:215], v[196:199], v[0:3]
	s_setprio 0
	s_add_i32 vcc_hi, vcc_hi, 2
	s_add_u32 s12, s12, 0x100
	s_addc_u32 s13, s13, 0
	s_add_u32 s69, s69, 0x100
	s_addc_u32 vcc_lo, vcc_lo, 0
	s_cmpk_gt_u32 vcc_hi, 0x7d
	s_barrier
	s_cbranch_scc0 .LBB0_889
	s_lshl_b32 s4, s56, 8
	s_add_i32 s4, s4, s35
	s_min_i32 s12, s4, 0x4000
	s_ashr_i32 s12, s12, 11
	s_mul_hi_i32 s13, s12, 0xc000
	s_mul_i32 s12, s12, 0xc000
	v_lshl_or_b32 v154, s53, 8, v162
	s_add_u32 s12, s8, s12
	s_addc_u32 s13, s9, s13
	v_ashrrev_i32_e32 v155, 31, v154
	v_lshl_add_u64 v[104:105], v[154:155], 2, s[12:13]
	global_load_dwordx4 v[124:127], v[104:105], off
	global_load_dwordx4 v[116:119], v[104:105], off offset:64
	global_load_dwordx4 v[108:111], v[104:105], off offset:512
	s_nop 0
	global_load_dwordx4 v[104:107], v[104:105], off offset:576
	v_add_u32_e32 v152, s4, v160
	s_movk_i32 s4, 0x3fff
	v_cmp_lt_i32_e32 vcc, s4, v152
	s_and_saveexec_b64 s[12:13], vcc
	s_xor_b64 s[12:13], exec, s[12:13]
	v_add_u32_e32 v186, 0xffffc000, v152
	v_lshlrev_b64 v[156:157], 13, v[186:187]
	v_mov_b32_e32 v153, v187
	v_lshl_add_u64 v[158:159], s[10:11], 0, v[156:157]
	v_lshlrev_b64 v[156:157], 13, v[152:153]
	s_andn2_saveexec_b64 s[12:13], s[12:13]
	v_ashrrev_i32_e32 v153, 31, v152
	v_lshlrev_b64 v[156:157], 13, v[152:153]
	v_lshl_add_u64 v[158:159], s[66:67], 0, v[156:157]
	s_or_b64 exec, exec, s[12:13]
	v_lshlrev_b64 v[154:155], 2, v[154:155]
	v_lshl_add_u64 v[158:159], v[158:159], 0, v[154:155]
	global_load_dwordx4 v[164:167], v[158:159], off
	v_lshl_add_u64 v[156:157], s[66:67], 0, v[156:157]
	v_lshl_add_u64 v[156:157], v[156:157], 0, v[154:155]
	s_movk_i32 s4, 0x3fef
	v_cmp_lt_i32_e32 vcc, s4, v152
	s_waitcnt vmcnt(0)
	v_pk_fma_f32 v[142:143], v[142:143], v[126:127], v[166:167]
	v_pk_fma_f32 v[140:141], v[140:141], v[124:125], v[164:165]
	global_store_dwordx4 v[156:157], v[140:143], off sc1
	global_load_dwordx4 v[140:143], v[158:159], off offset:64
	s_waitcnt vmcnt(0)
	v_pk_fma_f32 v[138:139], v[138:139], v[118:119], v[142:143]
	v_pk_fma_f32 v[136:137], v[136:137], v[116:117], v[140:141]
	global_store_dwordx4 v[156:157], v[136:139], off offset:64 sc1
	global_load_dwordx4 v[136:139], v[158:159], off offset:512
	s_waitcnt vmcnt(0)
	v_pk_fma_f32 v[134:135], v[134:135], v[110:111], v[138:139]
	v_pk_fma_f32 v[132:133], v[132:133], v[108:109], v[136:137]
	global_store_dwordx4 v[156:157], v[132:135], off offset:512 sc1
	global_load_dwordx4 v[134:137], v[158:159], off offset:576
	s_waitcnt vmcnt(0)
	v_pk_fma_f32 v[130:131], v[130:131], v[106:107], v[136:137]
	v_or_b32_e32 v132, 16, v152
	v_pk_fma_f32 v[128:129], v[128:129], v[104:105], v[134:135]
	global_store_dwordx4 v[156:157], v[128:131], off offset:576 sc1
	s_and_saveexec_b64 s[12:13], vcc
	s_xor_b64 s[12:13], exec, s[12:13]
	v_add_u32_e32 v186, 0xffffc010, v152
	v_lshlrev_b64 v[128:129], 13, v[186:187]
	v_mov_b32_e32 v133, v187
	v_lshl_add_u64 v[130:131], s[10:11], 0, v[128:129]
	v_lshlrev_b64 v[128:129], 13, v[132:133]
	s_andn2_saveexec_b64 s[12:13], s[12:13]
	v_ashrrev_i32_e32 v133, 31, v132
	v_lshlrev_b64 v[128:129], 13, v[132:133]
	v_lshl_add_u64 v[130:131], s[66:67], 0, v[128:129]
	s_or_b64 exec, exec, s[12:13]
	v_lshl_add_u64 v[134:135], v[130:131], 0, v[154:155]
	global_load_dwordx4 v[130:133], v[134:135], off
	v_lshl_add_u64 v[128:129], s[66:67], 0, v[128:129]
	v_lshl_add_u64 v[128:129], v[128:129], 0, v[154:155]
	s_movk_i32 s4, 0x3fdf
	v_cmp_lt_i32_e32 vcc, s4, v152
	s_waitcnt vmcnt(0)
	v_pk_fma_f32 v[122:123], v[122:123], v[126:127], v[132:133]
	v_pk_fma_f32 v[120:121], v[120:121], v[124:125], v[130:131]
	global_store_dwordx4 v[128:129], v[120:123], off sc1
	global_load_dwordx4 v[120:123], v[134:135], off offset:64
	s_waitcnt vmcnt(0)
	v_pk_fma_f32 v[114:115], v[114:115], v[118:119], v[122:123]
	v_pk_fma_f32 v[112:113], v[112:113], v[116:117], v[120:121]
	global_store_dwordx4 v[128:129], v[112:115], off offset:64 sc1
	global_load_dwordx4 v[112:115], v[134:135], off offset:512
	s_waitcnt vmcnt(0)
	v_pk_fma_f32 v[102:103], v[102:103], v[110:111], v[114:115]
	v_pk_fma_f32 v[100:101], v[100:101], v[108:109], v[112:113]
	global_store_dwordx4 v[128:129], v[100:103], off offset:512 sc1
	global_load_dwordx4 v[112:115], v[134:135], off offset:576
	s_waitcnt vmcnt(0)
	v_pk_fma_f32 v[98:99], v[98:99], v[106:107], v[114:115]
	v_or_b32_e32 v100, 32, v152
	v_pk_fma_f32 v[96:97], v[96:97], v[104:105], v[112:113]
	global_store_dwordx4 v[128:129], v[96:99], off offset:576 sc1
	s_and_saveexec_b64 s[12:13], vcc
	s_xor_b64 s[12:13], exec, s[12:13]
	v_add_u32_e32 v186, 0xffffc020, v152
	v_lshlrev_b64 v[96:97], 13, v[186:187]
	v_mov_b32_e32 v101, v187
	v_lshl_add_u64 v[98:99], s[10:11], 0, v[96:97]
	v_lshlrev_b64 v[96:97], 13, v[100:101]
	s_andn2_saveexec_b64 s[12:13], s[12:13]
	v_ashrrev_i32_e32 v101, 31, v100
	v_lshlrev_b64 v[96:97], 13, v[100:101]
	v_lshl_add_u64 v[98:99], s[66:67], 0, v[96:97]
	s_or_b64 exec, exec, s[12:13]
	v_lshl_add_u64 v[102:103], v[98:99], 0, v[154:155]
	global_load_dwordx4 v[98:101], v[102:103], off
	v_lshl_add_u64 v[96:97], s[66:67], 0, v[96:97]
	v_lshl_add_u64 v[96:97], v[96:97], 0, v[154:155]
	s_movk_i32 s4, 0x3fcf
	v_cmp_lt_i32_e32 vcc, s4, v152
	s_waitcnt vmcnt(0)
	v_pk_fma_f32 v[94:95], v[94:95], v[126:127], v[100:101]
	v_pk_fma_f32 v[92:93], v[92:93], v[124:125], v[98:99]
	global_store_dwordx4 v[96:97], v[92:95], off sc1
	global_load_dwordx4 v[92:95], v[102:103], off offset:64
	s_waitcnt vmcnt(0)
	v_pk_fma_f32 v[90:91], v[90:91], v[118:119], v[94:95]
	v_pk_fma_f32 v[88:89], v[88:89], v[116:117], v[92:93]
	global_store_dwordx4 v[96:97], v[88:91], off offset:64 sc1
	global_load_dwordx4 v[88:91], v[102:103], off offset:512
	s_waitcnt vmcnt(0)
	v_pk_fma_f32 v[86:87], v[86:87], v[110:111], v[90:91]
	v_pk_fma_f32 v[84:85], v[84:85], v[108:109], v[88:89]
	global_store_dwordx4 v[96:97], v[84:87], off offset:512 sc1
	global_load_dwordx4 v[86:89], v[102:103], off offset:576
	s_waitcnt vmcnt(0)
	v_pk_fma_f32 v[82:83], v[82:83], v[106:107], v[88:89]
	v_or_b32_e32 v84, 48, v152
	v_pk_fma_f32 v[80:81], v[80:81], v[104:105], v[86:87]
	global_store_dwordx4 v[96:97], v[80:83], off offset:576 sc1
	s_and_saveexec_b64 s[12:13], vcc
	s_xor_b64 s[12:13], exec, s[12:13]
	v_add_u32_e32 v186, 0xffffc030, v152
	v_lshlrev_b64 v[80:81], 13, v[186:187]
	v_mov_b32_e32 v85, v187
	v_lshl_add_u64 v[82:83], s[10:11], 0, v[80:81]
	v_lshlrev_b64 v[80:81], 13, v[84:85]
	s_andn2_saveexec_b64 s[12:13], s[12:13]
	v_ashrrev_i32_e32 v85, 31, v84
	v_lshlrev_b64 v[80:81], 13, v[84:85]
	v_lshl_add_u64 v[82:83], s[66:67], 0, v[80:81]
	s_or_b64 exec, exec, s[12:13]
	v_lshl_add_u64 v[86:87], v[82:83], 0, v[154:155]
	global_load_dwordx4 v[82:85], v[86:87], off
	v_lshl_add_u64 v[80:81], s[66:67], 0, v[80:81]
	v_lshl_add_u64 v[80:81], v[80:81], 0, v[154:155]
	s_movk_i32 s4, 0x3f7f
	v_cmp_lt_i32_e32 vcc, s4, v152
	s_waitcnt vmcnt(0)
	v_pk_fma_f32 v[78:79], v[78:79], v[126:127], v[84:85]
	v_pk_fma_f32 v[76:77], v[76:77], v[124:125], v[82:83]
	global_store_dwordx4 v[80:81], v[76:79], off sc1
	global_load_dwordx4 v[76:79], v[86:87], off offset:64
	s_waitcnt vmcnt(0)
	v_pk_fma_f32 v[74:75], v[74:75], v[118:119], v[78:79]
	v_pk_fma_f32 v[72:73], v[72:73], v[116:117], v[76:77]
	global_store_dwordx4 v[80:81], v[72:75], off offset:64 sc1
	global_load_dwordx4 v[72:75], v[86:87], off offset:512
	s_waitcnt vmcnt(0)
	v_pk_fma_f32 v[70:71], v[70:71], v[110:111], v[74:75]
	v_pk_fma_f32 v[68:69], v[68:69], v[108:109], v[72:73]
	global_store_dwordx4 v[80:81], v[68:71], off offset:512 sc1
	global_load_dwordx4 v[70:73], v[86:87], off offset:576
	s_waitcnt vmcnt(0)
	v_pk_fma_f32 v[66:67], v[66:67], v[106:107], v[72:73]
	v_add_u32_e32 v68, 0x80, v152
	v_pk_fma_f32 v[64:65], v[64:65], v[104:105], v[70:71]
	global_store_dwordx4 v[80:81], v[64:67], off offset:576 sc1
	s_and_saveexec_b64 s[12:13], vcc
	s_xor_b64 s[12:13], exec, s[12:13]
	v_add_u32_e32 v186, 0xffffc080, v152
	v_lshlrev_b64 v[64:65], 13, v[186:187]
	v_mov_b32_e32 v69, v187
	v_lshl_add_u64 v[66:67], s[10:11], 0, v[64:65]
	v_lshlrev_b64 v[64:65], 13, v[68:69]
	s_andn2_saveexec_b64 s[12:13], s[12:13]
	v_ashrrev_i32_e32 v69, 31, v68
	v_lshlrev_b64 v[64:65], 13, v[68:69]
	v_lshl_add_u64 v[66:67], s[66:67], 0, v[64:65]
	s_or_b64 exec, exec, s[12:13]
	v_lshl_add_u64 v[70:71], v[66:67], 0, v[154:155]
	global_load_dwordx4 v[66:69], v[70:71], off
	v_lshl_add_u64 v[64:65], s[66:67], 0, v[64:65]
	v_lshl_add_u64 v[64:65], v[64:65], 0, v[154:155]
	s_movk_i32 s4, 0x3f6f
	v_cmp_lt_i32_e32 vcc, s4, v152
	s_waitcnt vmcnt(0)
	v_pk_fma_f32 v[62:63], v[62:63], v[126:127], v[68:69]
	v_pk_fma_f32 v[60:61], v[60:61], v[124:125], v[66:67]
	global_store_dwordx4 v[64:65], v[60:63], off sc1
	global_load_dwordx4 v[60:63], v[70:71], off offset:64
	s_waitcnt vmcnt(0)
	v_pk_fma_f32 v[58:59], v[58:59], v[118:119], v[62:63]
	v_pk_fma_f32 v[56:57], v[56:57], v[116:117], v[60:61]
	global_store_dwordx4 v[64:65], v[56:59], off offset:64 sc1
	global_load_dwordx4 v[56:59], v[70:71], off offset:512
	s_waitcnt vmcnt(0)
	v_pk_fma_f32 v[54:55], v[54:55], v[110:111], v[58:59]
	v_pk_fma_f32 v[52:53], v[52:53], v[108:109], v[56:57]
	global_store_dwordx4 v[64:65], v[52:55], off offset:512 sc1
	global_load_dwordx4 v[54:57], v[70:71], off offset:576
	s_waitcnt vmcnt(0)
	v_pk_fma_f32 v[50:51], v[50:51], v[106:107], v[56:57]
	v_add_u32_e32 v52, 0x90, v152
	v_pk_fma_f32 v[48:49], v[48:49], v[104:105], v[54:55]
	global_store_dwordx4 v[64:65], v[48:51], off offset:576 sc1
	s_and_saveexec_b64 s[12:13], vcc
	s_xor_b64 s[12:13], exec, s[12:13]
	v_add_u32_e32 v186, 0xffffc090, v152
	v_lshlrev_b64 v[48:49], 13, v[186:187]
	v_mov_b32_e32 v53, v187
	v_lshl_add_u64 v[50:51], s[10:11], 0, v[48:49]
	v_lshlrev_b64 v[48:49], 13, v[52:53]
	s_andn2_saveexec_b64 s[12:13], s[12:13]
	v_ashrrev_i32_e32 v53, 31, v52
	v_lshlrev_b64 v[48:49], 13, v[52:53]
	v_lshl_add_u64 v[50:51], s[66:67], 0, v[48:49]
	s_or_b64 exec, exec, s[12:13]
	v_lshl_add_u64 v[54:55], v[50:51], 0, v[154:155]
	global_load_dwordx4 v[50:53], v[54:55], off
	v_lshl_add_u64 v[48:49], s[66:67], 0, v[48:49]
	v_lshl_add_u64 v[48:49], v[48:49], 0, v[154:155]
	s_movk_i32 s4, 0x3f5f
	v_cmp_lt_i32_e32 vcc, s4, v152
	s_waitcnt vmcnt(0)
	v_pk_fma_f32 v[46:47], v[46:47], v[126:127], v[52:53]
	v_pk_fma_f32 v[44:45], v[44:45], v[124:125], v[50:51]
	global_store_dwordx4 v[48:49], v[44:47], off sc1
	global_load_dwordx4 v[44:47], v[54:55], off offset:64
	s_waitcnt vmcnt(0)
	v_pk_fma_f32 v[42:43], v[42:43], v[118:119], v[46:47]
	v_pk_fma_f32 v[40:41], v[40:41], v[116:117], v[44:45]
	global_store_dwordx4 v[48:49], v[40:43], off offset:64 sc1
	global_load_dwordx4 v[40:43], v[54:55], off offset:512
	s_waitcnt vmcnt(0)
	v_pk_fma_f32 v[38:39], v[38:39], v[110:111], v[42:43]
	v_pk_fma_f32 v[36:37], v[36:37], v[108:109], v[40:41]
	global_store_dwordx4 v[48:49], v[36:39], off offset:512 sc1
	global_load_dwordx4 v[38:41], v[54:55], off offset:576
	s_waitcnt vmcnt(0)
	v_pk_fma_f32 v[34:35], v[34:35], v[106:107], v[40:41]
	v_add_u32_e32 v36, 0xa0, v152
	v_pk_fma_f32 v[32:33], v[32:33], v[104:105], v[38:39]
	global_store_dwordx4 v[48:49], v[32:35], off offset:576 sc1
	s_and_saveexec_b64 s[12:13], vcc
	s_xor_b64 s[12:13], exec, s[12:13]
	v_add_u32_e32 v186, 0xffffc0a0, v152
	v_lshlrev_b64 v[32:33], 13, v[186:187]
	v_mov_b32_e32 v37, v187
	v_lshl_add_u64 v[34:35], s[10:11], 0, v[32:33]
	v_lshlrev_b64 v[32:33], 13, v[36:37]
	s_andn2_saveexec_b64 s[12:13], s[12:13]
	v_ashrrev_i32_e32 v37, 31, v36
	v_lshlrev_b64 v[32:33], 13, v[36:37]
	v_lshl_add_u64 v[34:35], s[66:67], 0, v[32:33]
	s_or_b64 exec, exec, s[12:13]
	v_lshl_add_u64 v[38:39], v[34:35], 0, v[154:155]
	global_load_dwordx4 v[34:37], v[38:39], off
	v_lshl_add_u64 v[32:33], s[66:67], 0, v[32:33]
	v_lshl_add_u64 v[32:33], v[32:33], 0, v[154:155]
	s_movk_i32 s4, 0x3f4f
	v_cmp_lt_i32_e32 vcc, s4, v152
	s_waitcnt vmcnt(0)
	v_pk_fma_f32 v[30:31], v[30:31], v[126:127], v[36:37]
	v_pk_fma_f32 v[28:29], v[28:29], v[124:125], v[34:35]
	global_store_dwordx4 v[32:33], v[28:31], off sc1
	global_load_dwordx4 v[28:31], v[38:39], off offset:64
	s_waitcnt vmcnt(0)
	v_pk_fma_f32 v[26:27], v[26:27], v[118:119], v[30:31]
	v_pk_fma_f32 v[24:25], v[24:25], v[116:117], v[28:29]
	global_store_dwordx4 v[32:33], v[24:27], off offset:64 sc1
	global_load_dwordx4 v[24:27], v[38:39], off offset:512
	s_waitcnt vmcnt(0)
	v_pk_fma_f32 v[22:23], v[22:23], v[110:111], v[26:27]
	v_pk_fma_f32 v[20:21], v[20:21], v[108:109], v[24:25]
	global_store_dwordx4 v[32:33], v[20:23], off offset:512 sc1
	global_load_dwordx4 v[22:25], v[38:39], off offset:576
	s_waitcnt vmcnt(0)
	v_pk_fma_f32 v[18:19], v[18:19], v[106:107], v[24:25]
	v_add_u32_e32 v20, 0xb0, v152
	v_pk_fma_f32 v[16:17], v[16:17], v[104:105], v[22:23]
	global_store_dwordx4 v[32:33], v[16:19], off offset:576 sc1
	s_and_saveexec_b64 s[12:13], vcc
	s_xor_b64 s[12:13], exec, s[12:13]
	v_add_u32_e32 v186, 0xffffc0b0, v152
	v_lshlrev_b64 v[16:17], 13, v[186:187]
	v_mov_b32_e32 v21, v187
	v_lshl_add_u64 v[16:17], s[10:11], 0, v[16:17]
	v_lshlrev_b64 v[18:19], 13, v[20:21]
	s_andn2_saveexec_b64 s[12:13], s[12:13]
	s_cbranch_execz .LBB0_881
	v_ashrrev_i32_e32 v21, 31, v20
	v_lshlrev_b64 v[18:19], 13, v[20:21]
	v_lshl_add_u64 v[16:17], s[66:67], 0, v[18:19]
	s_branch .LBB0_881

.LBB0_1017:
	s_or_b64 exec, exec, s[2:3]
	v_lshl_add_u64 v[0:1], s[64:65], 0, v[196:197]
	s_waitcnt lgkmcnt(0)
	s_barrier
	global_load_dwordx4 v[12:15], v[0:1], off
	global_load_dwordx4 v[8:11], v[0:1], off offset:64
	global_load_dwordx4 v[4:7], v[0:1], off offset:512
	s_nop 0
	global_load_dwordx4 v[0:3], v[0:1], off offset:576
	v_lshl_add_u32 v58, v233, 2, 0
	v_add_u32_e32 v64, 0x1000, v58
	ds_read2_b32 v[58:59], v64 offset1:16
	s_waitcnt lgkmcnt(0)
	v_pk_mul_f32 v[62:63], v[204:205], v[58:59] op_sel_hi:[1,0]
	v_pk_mul_f32 v[66:67], v[202:203], v[58:59] op_sel_hi:[1,0]
	s_waitcnt vmcnt(3)
	v_pk_mul_f32 v[68:69], v[14:15], v[66:67]
	v_pk_mul_f32 v[66:67], v[12:13], v[62:63]
	global_store_dwordx4 v[200:201], v[66:69], off sc1
	v_pk_mul_f32 v[62:63], v[208:209], v[58:59] op_sel_hi:[1,0]
	s_nop 0
	v_pk_mul_f32 v[66:67], v[206:207], v[58:59] op_sel_hi:[1,0]
	s_waitcnt vmcnt(3)
	v_pk_mul_f32 v[68:69], v[10:11], v[66:67]
	v_pk_mul_f32 v[66:67], v[8:9], v[62:63]
	global_store_dwordx4 v[200:201], v[66:69], off offset:64 sc1
	v_pk_mul_f32 v[62:63], v[180:181], v[58:59] op_sel_hi:[1,0]
	s_nop 0
	v_pk_mul_f32 v[66:67], v[182:183], v[58:59] op_sel_hi:[1,0]
	s_waitcnt vmcnt(3)
	v_pk_mul_f32 v[68:69], v[6:7], v[66:67]
	v_pk_mul_f32 v[66:67], v[4:5], v[62:63]
	global_store_dwordx4 v[200:201], v[66:69], off offset:512 sc1
	v_pk_mul_f32 v[62:63], v[216:217], v[58:59] op_sel_hi:[1,0]
	s_nop 0
	v_pk_mul_f32 v[66:67], v[212:213], v[58:59] op_sel_hi:[1,0]
	v_mov_b32_e32 v58, v59
	s_waitcnt vmcnt(3)
	v_pk_mul_f32 v[68:69], v[2:3], v[66:67]
	v_pk_mul_f32 v[66:67], v[0:1], v[62:63]
	v_add_u32_e32 v62, 16, v198
	v_ashrrev_i32_e32 v63, 31, v62
	v_lshlrev_b64 v[62:63], 13, v[62:63]
	global_store_dwordx4 v[200:201], v[66:69], off offset:576 sc1
	v_lshl_add_u64 v[62:63], s[66:67], 0, v[62:63]
	v_lshl_add_u64 v[62:63], v[62:63], 0, v[196:197]
	v_pk_mul_f32 v[66:67], v[178:179], v[58:59] op_sel_hi:[1,0]
	v_pk_mul_f32 v[68:69], v[176:177], v[58:59] op_sel_hi:[1,0]
	v_pk_mul_f32 v[66:67], v[12:13], v[66:67]
	v_pk_mul_f32 v[68:69], v[14:15], v[68:69]
	global_store_dwordx4 v[62:63], v[66:69], off sc1
	s_nop 1
	v_pk_mul_f32 v[66:67], v[214:215], v[58:59] op_sel_hi:[1,0]
	v_pk_mul_f32 v[68:69], v[210:211], v[58:59] op_sel_hi:[1,0]
	v_pk_mul_f32 v[66:67], v[8:9], v[66:67]
	v_pk_mul_f32 v[68:69], v[10:11], v[68:69]
	global_store_dwordx4 v[62:63], v[66:69], off offset:64 sc1
	s_nop 1
	v_pk_mul_f32 v[66:67], v[220:221], v[58:59] op_sel_hi:[1,0]
	v_pk_mul_f32 v[68:69], v[218:219], v[58:59] op_sel_hi:[1,0]
	v_pk_mul_f32 v[66:67], v[4:5], v[66:67]
	v_pk_mul_f32 v[68:69], v[6:7], v[68:69]
	global_store_dwordx4 v[62:63], v[66:69], off offset:512 sc1
	s_nop 1
	v_pk_mul_f32 v[66:67], v[224:225], v[58:59] op_sel_hi:[1,0]
	v_pk_mul_f32 v[58:59], v[222:223], v[58:59] op_sel_hi:[1,0]
	v_pk_mul_f32 v[66:67], v[0:1], v[66:67]
	v_pk_mul_f32 v[68:69], v[2:3], v[58:59]
	ds_read2_b32 v[58:59], v64 offset0:32 offset1:48
	global_store_dwordx4 v[62:63], v[66:69], off offset:576 sc1
	v_add_u32_e32 v62, 32, v198
	v_ashrrev_i32_e32 v63, 31, v62
	v_lshlrev_b64 v[62:63], 13, v[62:63]
	v_lshl_add_u64 v[62:63], s[66:67], 0, v[62:63]
	s_waitcnt lgkmcnt(0)
	v_pk_mul_f32 v[66:67], v[172:173], v[58:59] op_sel_hi:[1,0]
	v_pk_mul_f32 v[68:69], v[174:175], v[58:59] op_sel_hi:[1,0]
	v_lshl_add_u64 v[62:63], v[62:63], 0, v[196:197]
	v_pk_mul_f32 v[68:69], v[14:15], v[68:69]
	v_pk_mul_f32 v[66:67], v[12:13], v[66:67]
	global_store_dwordx4 v[62:63], v[66:69], off sc1
	s_nop 1
	v_pk_mul_f32 v[66:67], v[168:169], v[58:59] op_sel_hi:[1,0]
	v_pk_mul_f32 v[68:69], v[170:171], v[58:59] op_sel_hi:[1,0]
	v_pk_mul_f32 v[66:67], v[8:9], v[66:67]
	v_pk_mul_f32 v[68:69], v[10:11], v[68:69]
	global_store_dwordx4 v[62:63], v[66:69], off offset:64 sc1
	s_nop 1
	v_pk_mul_f32 v[66:67], v[158:159], v[58:59] op_sel_hi:[1,0]
	v_pk_mul_f32 v[68:69], v[156:157], v[58:59] op_sel_hi:[1,0]
	v_pk_mul_f32 v[66:67], v[4:5], v[66:67]
	v_pk_mul_f32 v[68:69], v[6:7], v[68:69]
	global_store_dwordx4 v[62:63], v[66:69], off offset:512 sc1
	s_nop 1
	v_pk_mul_f32 v[66:67], v[154:155], v[58:59] op_sel_hi:[1,0]
	v_pk_mul_f32 v[68:69], v[152:153], v[58:59] op_sel_hi:[1,0]
	v_pk_mul_f32 v[66:67], v[0:1], v[66:67]
	v_pk_mul_f32 v[68:69], v[2:3], v[68:69]
	global_store_dwordx4 v[62:63], v[66:69], off offset:576 sc1
	v_add_u32_e32 v62, 48, v198
	v_ashrrev_i32_e32 v63, 31, v62
	v_lshlrev_b64 v[62:63], 13, v[62:63]
	v_mov_b32_e32 v58, v59
	v_lshl_add_u64 v[62:63], s[66:67], 0, v[62:63]
	v_pk_mul_f32 v[66:67], v[124:125], v[58:59] op_sel_hi:[1,0]
	v_pk_mul_f32 v[68:69], v[126:127], v[58:59] op_sel_hi:[1,0]
	v_lshl_add_u64 v[62:63], v[62:63], 0, v[196:197]
	v_pk_mul_f32 v[68:69], v[14:15], v[68:69]
	v_pk_mul_f32 v[66:67], v[12:13], v[66:67]
	global_store_dwordx4 v[62:63], v[66:69], off sc1
	s_nop 1
	v_pk_mul_f32 v[66:67], v[120:121], v[58:59] op_sel_hi:[1,0]
	v_pk_mul_f32 v[68:69], v[122:123], v[58:59] op_sel_hi:[1,0]
	v_pk_mul_f32 v[66:67], v[8:9], v[66:67]
	v_pk_mul_f32 v[68:69], v[10:11], v[68:69]
	global_store_dwordx4 v[62:63], v[66:69], off offset:64 sc1
	s_nop 1
	v_pk_mul_f32 v[66:67], v[116:117], v[58:59] op_sel_hi:[1,0]
	v_pk_mul_f32 v[68:69], v[118:119], v[58:59] op_sel_hi:[1,0]
	v_pk_mul_f32 v[66:67], v[4:5], v[66:67]
	v_pk_mul_f32 v[68:69], v[6:7], v[68:69]
	global_store_dwordx4 v[62:63], v[66:69], off offset:512 sc1
	s_nop 1
	v_pk_mul_f32 v[66:67], v[148:149], v[58:59] op_sel_hi:[1,0]
	v_pk_mul_f32 v[58:59], v[114:115], v[58:59] op_sel_hi:[1,0]
	v_pk_mul_f32 v[66:67], v[0:1], v[66:67]
	v_pk_mul_f32 v[68:69], v[2:3], v[58:59]
	ds_read2_b32 v[58:59], v64 offset0:128 offset1:144
	global_store_dwordx4 v[62:63], v[66:69], off offset:576 sc1
	s_waitcnt lgkmcnt(0)
	v_pk_mul_f32 v[62:63], v[108:109], v[58:59] op_sel_hi:[1,0]
	v_pk_mul_f32 v[66:67], v[110:111], v[58:59] op_sel_hi:[1,0]
	s_nop 0
	v_pk_mul_f32 v[68:69], v[14:15], v[66:67]
	v_pk_mul_f32 v[66:67], v[12:13], v[62:63]
	global_store_dwordx4 v[144:145], v[66:69], off sc1
	v_pk_mul_f32 v[62:63], v[104:105], v[58:59] op_sel_hi:[1,0]
	s_nop 0
	v_pk_mul_f32 v[66:67], v[106:107], v[58:59] op_sel_hi:[1,0]
	s_nop 0
	v_pk_mul_f32 v[68:69], v[10:11], v[66:67]
	v_pk_mul_f32 v[66:67], v[8:9], v[62:63]
	global_store_dwordx4 v[144:145], v[66:69], off offset:64 sc1
	v_pk_mul_f32 v[62:63], v[100:101], v[58:59] op_sel_hi:[1,0]
	s_nop 0
	v_pk_mul_f32 v[66:67], v[102:103], v[58:59] op_sel_hi:[1,0]
	s_nop 0
	v_pk_mul_f32 v[68:69], v[6:7], v[66:67]
	v_pk_mul_f32 v[66:67], v[4:5], v[62:63]
	global_store_dwordx4 v[144:145], v[66:69], off offset:512 sc1
	v_pk_mul_f32 v[62:63], v[150:151], v[58:59] op_sel_hi:[1,0]
	s_nop 0
	v_pk_mul_f32 v[66:67], v[98:99], v[58:59] op_sel_hi:[1,0]
	v_mov_b32_e32 v58, v59
	v_pk_mul_f32 v[36:37], v[36:37], v[58:59] op_sel_hi:[1,0]
	v_pk_mul_f32 v[38:39], v[38:39], v[58:59] op_sel_hi:[1,0]
	v_pk_mul_f32 v[36:37], v[4:5], v[36:37]
	v_pk_mul_f32 v[38:39], v[6:7], v[38:39]
	global_store_dwordx4 v[146:147], v[36:39], off offset:512 sc1
	v_pk_mul_f32 v[44:45], v[44:45], v[58:59] op_sel_hi:[1,0]
	v_pk_mul_f32 v[46:47], v[46:47], v[58:59] op_sel_hi:[1,0]
	v_pk_mul_f32 v[36:37], v[80:81], v[58:59] op_sel_hi:[1,0]
	v_pk_mul_f32 v[38:39], v[82:83], v[58:59] op_sel_hi:[1,0]
	v_pk_mul_f32 v[36:37], v[0:1], v[36:37]
	v_pk_mul_f32 v[38:39], v[2:3], v[38:39]
	global_store_dwordx4 v[146:147], v[36:39], off offset:576 sc1
	ds_read2_b32 v[36:37], v64 offset0:160 offset1:176
	v_pk_mul_f32 v[46:47], v[14:15], v[46:47]
	v_pk_mul_f32 v[44:45], v[12:13], v[44:45]
	v_pk_mul_f32 v[40:41], v[40:41], v[58:59] op_sel_hi:[1,0]
	v_pk_mul_f32 v[42:43], v[42:43], v[58:59] op_sel_hi:[1,0]
	s_waitcnt lgkmcnt(0)
	v_pk_mul_f32 v[20:21], v[20:21], v[36:37] op_sel_hi:[1,0]
	v_pk_mul_f32 v[22:23], v[22:23], v[36:37] op_sel_hi:[1,0]
	v_pk_mul_f32 v[20:21], v[4:5], v[20:21]
	v_pk_mul_f32 v[22:23], v[6:7], v[22:23]
	global_store_dwordx4 v[112:113], v[20:23], off offset:512 sc1
	v_pk_mul_f32 v[38:39], v[30:31], v[36:37] op_sel_hi:[1,0]
	v_pk_mul_f32 v[28:29], v[28:29], v[36:37] op_sel_hi:[1,0]
	v_pk_mul_f32 v[20:21], v[34:35], v[36:37] op_sel_hi:[1,0]
	v_pk_mul_f32 v[22:23], v[32:33], v[36:37] op_sel_hi:[1,0]
	v_pk_mul_f32 v[20:21], v[0:1], v[20:21]
	v_pk_mul_f32 v[22:23], v[2:3], v[22:23]
	global_store_dwordx4 v[112:113], v[20:23], off offset:576 sc1
	v_pk_mul_f32 v[30:31], v[14:15], v[28:29]
	v_pk_mul_f32 v[28:29], v[12:13], v[38:39]
	v_mov_b32_e32 v20, v37
	v_pk_mul_f32 v[22:23], v[60:61], v[20:21] op_sel_hi:[1,0]
	v_pk_mul_f32 v[18:19], v[18:19], v[20:21] op_sel_hi:[1,0]
	v_pk_mul_f32 v[12:13], v[12:13], v[22:23]
	v_pk_mul_f32 v[14:15], v[14:15], v[18:19]
	v_pk_mul_f32 v[24:25], v[24:25], v[36:37] op_sel_hi:[1,0]
	v_pk_mul_f32 v[26:27], v[26:27], v[36:37] op_sel_hi:[1,0]
	global_store_dwordx4 v[96:97], v[12:15], off sc1
	v_pk_mul_f32 v[42:43], v[10:11], v[42:43]
	v_pk_mul_f32 v[40:41], v[8:9], v[40:41]
	v_pk_mul_f32 v[12:13], v[56:57], v[20:21] op_sel_hi:[1,0]
	v_pk_mul_f32 v[14:15], v[16:17], v[20:21] op_sel_hi:[1,0]
	v_pk_mul_f32 v[26:27], v[10:11], v[26:27]
	v_pk_mul_f32 v[24:25], v[8:9], v[24:25]
	v_pk_mul_f32 v[10:11], v[10:11], v[14:15]
	v_pk_mul_f32 v[8:9], v[8:9], v[12:13]
	global_store_dwordx4 v[96:97], v[8:11], off offset:64 sc1
	v_pk_mul_f32 v[68:69], v[2:3], v[66:67]
	v_pk_mul_f32 v[66:67], v[0:1], v[62:63]
	v_pk_mul_f32 v[8:9], v[52:53], v[20:21] op_sel_hi:[1,0]
	v_pk_mul_f32 v[10:11], v[54:55], v[20:21] op_sel_hi:[1,0]
	v_pk_mul_f32 v[4:5], v[4:5], v[8:9]
	v_pk_mul_f32 v[6:7], v[6:7], v[10:11]
	global_store_dwordx4 v[96:97], v[4:7], off offset:512 sc1
	global_store_dwordx4 v[144:145], v[66:69], off offset:576 sc1
	global_store_dwordx4 v[146:147], v[44:47], off sc1
	v_pk_mul_f32 v[4:5], v[48:49], v[20:21] op_sel_hi:[1,0]
	v_pk_mul_f32 v[6:7], v[50:51], v[20:21] op_sel_hi:[1,0]
	v_pk_mul_f32 v[0:1], v[0:1], v[4:5]
	v_pk_mul_f32 v[2:3], v[2:3], v[6:7]
	global_store_dwordx4 v[146:147], v[40:43], off offset:64 sc1
	global_store_dwordx4 v[112:113], v[28:31], off sc1
	global_store_dwordx4 v[112:113], v[24:27], off offset:64 sc1
	global_store_dwordx4 v[96:97], v[0:3], off offset:576 sc1

.LBB0_1088:
	v_lshl_add_u64 v[54:55], v[52:53], 0, s[6:7]
	v_lshl_add_u64 v[56:57], v[50:51], 0, s[6:7]
	v_add_co_u32_e32 v128, vcc, 0x1000, v54
	global_load_dwordx4 v[64:67], v[56:57], off
	global_load_dwordx4 v[68:71], v[54:55], off
	global_load_dwordx4 v[72:75], v[56:57], off offset:1024
	global_load_dwordx4 v[76:79], v[54:55], off offset:1024
	global_load_dwordx4 v[80:83], v[56:57], off offset:2048
	global_load_dwordx4 v[84:87], v[54:55], off offset:2048
	global_load_dwordx4 v[88:91], v[56:57], off offset:3072
	global_load_dwordx4 v[92:95], v[54:55], off offset:3072
	v_addc_co_u32_e32 v129, vcc, 0, v55, vcc
	v_add_co_u32_e32 v130, vcc, 0x1000, v56
	global_load_dwordx4 v[96:99], v[128:129], off
	global_load_dwordx4 v[100:103], v[128:129], off offset:1024
	global_load_dwordx4 v[104:107], v[128:129], off offset:2048
	global_load_dwordx4 v[108:111], v[128:129], off offset:3072
	v_addc_co_u32_e32 v131, vcc, 0, v57, vcc
	global_load_dwordx4 v[112:115], v[130:131], off
	global_load_dwordx4 v[116:119], v[130:131], off offset:1024
	global_load_dwordx4 v[120:123], v[130:131], off offset:2048
	global_load_dwordx4 v[124:127], v[130:131], off offset:3072
	s_add_u32 s6, s6, 0x4000
	s_addc_u32 s7, s7, 0
	s_cmp_eq_u32 s6, 0x20000
	s_waitcnt vmcnt(0)
	v_mov_b32_e32 v134, v65
	v_mov_b32_e32 v135, v69
	v_mov_b32_e32 v142, v73
	v_mov_b32_e32 v143, v77
	v_mov_b32_e32 v150, v81
	v_mov_b32_e32 v151, v85
	v_mov_b32_e32 v158, v89
	v_mov_b32_e32 v159, v93
	v_mov_b32_e32 v132, v64
	v_mov_b32_e32 v133, v68
	v_mov_b32_e32 v140, v72
	v_mov_b32_e32 v141, v76
	v_mov_b32_e32 v148, v80
	v_mov_b32_e32 v149, v84
	v_mov_b32_e32 v156, v88
	v_mov_b32_e32 v157, v92
	v_pk_mul_f32 v[134:135], v[134:135], v[134:135]
	v_pk_mul_f32 v[142:143], v[142:143], v[142:143]
	v_pk_mul_f32 v[150:151], v[150:151], v[150:151]
	v_pk_mul_f32 v[158:159], v[158:159], v[158:159]
	v_mov_b32_e32 v166, v97
	v_mov_b32_e32 v167, v101
	v_mov_b32_e32 v136, v66
	v_mov_b32_e32 v137, v70
	v_mov_b32_e32 v144, v74
	v_mov_b32_e32 v145, v78
	v_mov_b32_e32 v152, v82
	v_mov_b32_e32 v153, v86
	v_mov_b32_e32 v160, v90
	v_mov_b32_e32 v161, v94
	v_mov_b32_e32 v164, v96
	v_mov_b32_e32 v165, v100
	v_pk_fma_f32 v[132:133], v[132:133], v[132:133], v[134:135]
	v_pk_fma_f32 v[134:135], v[140:141], v[140:141], v[142:143]
	v_pk_fma_f32 v[140:141], v[148:149], v[148:149], v[150:151]
	v_pk_fma_f32 v[142:143], v[156:157], v[156:157], v[158:159]
	v_pk_mul_f32 v[148:149], v[166:167], v[166:167]
	v_mov_b32_e32 v158, v113
	v_mov_b32_e32 v159, v117
	v_mov_b32_e32 v138, v67
	v_mov_b32_e32 v139, v71
	v_mov_b32_e32 v146, v75
	v_mov_b32_e32 v147, v79
	v_mov_b32_e32 v162, v91
	v_mov_b32_e32 v163, v95
	v_mov_b32_e32 v168, v98
	v_mov_b32_e32 v169, v102
	v_mov_b32_e32 v156, v112
	v_mov_b32_e32 v157, v116
	v_pk_fma_f32 v[132:133], v[136:137], v[136:137], v[132:133]
	v_pk_fma_f32 v[134:135], v[144:145], v[144:145], v[134:135]
	v_pk_fma_f32 v[136:137], v[152:153], v[152:153], v[140:141]
	v_pk_fma_f32 v[140:141], v[160:161], v[160:161], v[142:143]
	v_mov_b32_e32 v144, v121
	v_mov_b32_e32 v145, v125
	v_pk_fma_f32 v[148:149], v[164:165], v[164:165], v[148:149]
	v_pk_mul_f32 v[158:159], v[158:159], v[158:159]
	v_mov_b32_e32 v154, v83
	v_mov_b32_e32 v155, v87
	v_mov_b32_e32 v170, v99
	v_mov_b32_e32 v171, v103
	v_mov_b32_e32 v174, v105
	v_mov_b32_e32 v175, v109
	v_mov_b32_e32 v166, v114
	v_mov_b32_e32 v167, v118
	v_mov_b32_e32 v142, v120
	v_mov_b32_e32 v143, v124
	v_pk_fma_f32 v[132:133], v[138:139], v[138:139], v[132:133]
	v_pk_fma_f32 v[134:135], v[146:147], v[146:147], v[134:135]
	v_pk_fma_f32 v[138:139], v[162:163], v[162:163], v[140:141]
	v_pk_mul_f32 v[140:141], v[144:145], v[144:145]
	v_pk_fma_f32 v[144:145], v[168:169], v[168:169], v[148:149]
	v_pk_fma_f32 v[148:149], v[156:157], v[156:157], v[158:159]
	v_mov_b32_e32 v172, v104
	v_mov_b32_e32 v173, v108
	v_pk_mul_f32 v[150:151], v[174:175], v[174:175]
	v_mov_b32_e32 v174, v115
	v_mov_b32_e32 v175, v119
	v_pk_fma_f32 v[136:137], v[154:155], v[154:155], v[136:137]
	v_pk_add_f32 v[132:133], v[132:133], v[134:135]
	v_pk_fma_f32 v[134:135], v[142:143], v[142:143], v[140:141]
	v_pk_fma_f32 v[140:141], v[170:171], v[170:171], v[144:145]
	v_pk_fma_f32 v[144:145], v[166:167], v[166:167], v[148:149]
	v_mov_b32_e32 v176, v106
	v_mov_b32_e32 v177, v110
	v_mov_b32_e32 v152, v122
	v_mov_b32_e32 v153, v126
	v_pk_fma_f32 v[150:151], v[172:173], v[172:173], v[150:151]
	v_pk_add_f32 v[132:133], v[132:133], v[136:137]
	v_pk_fma_f32 v[136:137], v[174:175], v[174:175], v[144:145]
	v_mov_b32_e32 v178, v107
	v_mov_b32_e32 v179, v111
	v_mov_b32_e32 v160, v123
	v_mov_b32_e32 v161, v127
	v_pk_fma_f32 v[146:147], v[176:177], v[176:177], v[150:151]
	v_pk_fma_f32 v[134:135], v[152:153], v[152:153], v[134:135]
	v_pk_add_f32 v[132:133], v[132:133], v[138:139]
	v_mov_b32_e32 v139, v140
	v_mov_b32_e32 v138, v136
	v_pk_fma_f32 v[142:143], v[178:179], v[178:179], v[146:147]
	v_pk_fma_f32 v[134:135], v[160:161], v[160:161], v[134:135]
	v_mov_b32_e32 v140, v137
	v_pk_add_f32 v[132:133], v[132:133], v[138:139]
	v_mov_b32_e32 v145, v142
	v_mov_b32_e32 v144, v134
	v_pk_add_f32 v[132:133], v[132:133], v[140:141]
	v_mov_b32_e32 v142, v135
	v_pk_add_f32 v[132:133], v[132:133], v[144:145]
	s_nop 0
	v_pk_add_f32 v[132:133], v[132:133], v[142:143]
	ds_bpermute_b32 v135, v58, v133
	ds_bpermute_b32 v134, v58, v132
	s_waitcnt lgkmcnt(0)
	v_pk_add_f32 v[132:133], v[132:133], v[134:135]
	ds_bpermute_b32 v135, v59, v133
	ds_bpermute_b32 v134, v59, v132
	s_waitcnt lgkmcnt(0)
	v_pk_add_f32 v[132:133], v[132:133], v[134:135]
	ds_bpermute_b32 v135, v60, v133
	ds_bpermute_b32 v134, v60, v132
	s_waitcnt lgkmcnt(0)
	v_pk_add_f32 v[132:133], v[132:133], v[134:135]
	ds_bpermute_b32 v135, v61, v133
	ds_bpermute_b32 v134, v61, v132
	s_waitcnt lgkmcnt(0)
	v_pk_add_f32 v[132:133], v[132:133], v[134:135]
	ds_bpermute_b32 v135, v62, v133
	ds_bpermute_b32 v134, v62, v132
	s_waitcnt lgkmcnt(0)
	v_pk_add_f32 v[132:133], v[132:133], v[134:135]
	ds_bpermute_b32 v135, v63, v133
	ds_bpermute_b32 v134, v63, v132
	s_waitcnt lgkmcnt(0)
	v_pk_add_f32 v[132:133], v[132:133], v[134:135]
	s_nop 0
	v_pk_fma_f32 v[132:133], v[132:133], s[4:5], v[48:49] op_sel_hi:[1,0,0]
	s_nop 0
	v_mul_f32_e32 v45, 0x4b800000, v133
	v_cmp_gt_f32_e64 s[0:1], s9, v133
	v_mul_f32_e32 v47, 0x4b800000, v132
	v_cmp_gt_f32_e32 vcc, s9, v132
	v_cndmask_b32_e64 v45, v133, v45, s[0:1]
	v_rsq_f32_e32 v45, v45
	v_cndmask_b32_e32 v47, v132, v47, vcc
	v_rsq_f32_e32 v47, v47
	v_mul_f32_e32 v132, 0x45800000, v45
	v_cndmask_b32_e64 v132, v45, v132, s[0:1]
	v_mul_f32_e32 v133, 0x45800000, v47
	v_cndmask_b32_e32 v134, v47, v133, vcc
	v_pk_mul_f32 v[68:69], v[68:69], v[132:133] op_sel_hi:[1,0]
	v_pk_mul_f32 v[70:71], v[70:71], v[132:133] op_sel_hi:[1,0]
	v_pk_mul_f32 v[76:77], v[76:77], v[132:133] op_sel_hi:[1,0]
	v_pk_mul_f32 v[78:79], v[78:79], v[132:133] op_sel_hi:[1,0]
	v_pk_mul_f32 v[84:85], v[84:85], v[132:133] op_sel_hi:[1,0]
	v_pk_mul_f32 v[86:87], v[86:87], v[132:133] op_sel_hi:[1,0]
	v_pk_mul_f32 v[92:93], v[92:93], v[132:133] op_sel_hi:[1,0]
	v_pk_mul_f32 v[94:95], v[94:95], v[132:133] op_sel_hi:[1,0]
	v_pk_mul_f32 v[96:97], v[96:97], v[132:133] op_sel_hi:[1,0]
	v_pk_mul_f32 v[98:99], v[98:99], v[132:133] op_sel_hi:[1,0]
	v_pk_mul_f32 v[100:101], v[100:101], v[132:133] op_sel_hi:[1,0]
	v_pk_mul_f32 v[102:103], v[102:103], v[132:133] op_sel_hi:[1,0]
	v_pk_mul_f32 v[104:105], v[104:105], v[132:133] op_sel_hi:[1,0]
	v_pk_mul_f32 v[106:107], v[106:107], v[132:133] op_sel_hi:[1,0]
	v_pk_mul_f32 v[108:109], v[108:109], v[132:133] op_sel_hi:[1,0]
	v_pk_mul_f32 v[110:111], v[110:111], v[132:133] op_sel_hi:[1,0]
	v_pk_mul_f32 v[132:133], v[64:65], v[134:135] op_sel_hi:[1,0]
	v_pk_mul_f32 v[136:137], v[66:67], v[134:135] op_sel_hi:[1,0]
	v_pk_mul_f32 v[138:139], v[72:73], v[134:135] op_sel_hi:[1,0]
	v_pk_mul_f32 v[140:141], v[74:75], v[134:135] op_sel_hi:[1,0]
	v_pk_mul_f32 v[142:143], v[80:81], v[134:135] op_sel_hi:[1,0]
	v_pk_mul_f32 v[144:145], v[82:83], v[134:135] op_sel_hi:[1,0]
	v_pk_mul_f32 v[146:147], v[88:89], v[134:135] op_sel_hi:[1,0]
	v_pk_mul_f32 v[148:149], v[90:91], v[134:135] op_sel_hi:[1,0]
	v_pk_mul_f32 v[112:113], v[112:113], v[134:135] op_sel_hi:[1,0]
	v_pk_mul_f32 v[114:115], v[114:115], v[134:135] op_sel_hi:[1,0]
	v_pk_mul_f32 v[116:117], v[116:117], v[134:135] op_sel_hi:[1,0]
	v_pk_mul_f32 v[118:119], v[118:119], v[134:135] op_sel_hi:[1,0]
	v_pk_mul_f32 v[120:121], v[120:121], v[134:135] op_sel_hi:[1,0]
	v_pk_mul_f32 v[122:123], v[122:123], v[134:135] op_sel_hi:[1,0]
	v_pk_mul_f32 v[124:125], v[124:125], v[134:135] op_sel_hi:[1,0]
	v_pk_mul_f32 v[126:127], v[126:127], v[134:135] op_sel_hi:[1,0]
	v_pk_fma_f32 v[66:67], v[2:3], v[70:71], 0 op_sel_hi:[1,1,0]
	v_pk_fma_f32 v[64:65], v[0:1], v[68:69], 0 op_sel_hi:[1,1,0]
	v_pk_fma_f32 v[70:71], v[6:7], v[78:79], 0 op_sel_hi:[1,1,0]
	v_pk_fma_f32 v[68:69], v[4:5], v[76:77], 0 op_sel_hi:[1,1,0]
	v_pk_fma_f32 v[74:75], v[10:11], v[86:87], 0 op_sel_hi:[1,1,0]
	v_pk_fma_f32 v[72:73], v[8:9], v[84:85], 0 op_sel_hi:[1,1,0]
	v_pk_fma_f32 v[78:79], v[14:15], v[94:95], 0 op_sel_hi:[1,1,0]
	v_pk_fma_f32 v[76:77], v[12:13], v[92:93], 0 op_sel_hi:[1,1,0]
	v_pk_fma_f32 v[82:83], v[18:19], v[98:99], 0 op_sel_hi:[1,1,0]
	v_pk_fma_f32 v[80:81], v[16:17], v[96:97], 0 op_sel_hi:[1,1,0]
	v_pk_fma_f32 v[86:87], v[22:23], v[102:103], 0 op_sel_hi:[1,1,0]
	v_pk_fma_f32 v[84:85], v[20:21], v[100:101], 0 op_sel_hi:[1,1,0]
	v_pk_fma_f32 v[90:91], v[26:27], v[106:107], 0 op_sel_hi:[1,1,0]
	v_pk_fma_f32 v[88:89], v[24:25], v[104:105], 0 op_sel_hi:[1,1,0]
	v_pk_fma_f32 v[94:95], v[30:31], v[110:111], 0 op_sel_hi:[1,1,0]
	v_pk_fma_f32 v[92:93], v[28:29], v[108:109], 0 op_sel_hi:[1,1,0]
	v_pk_fma_f32 v[98:99], v[2:3], v[136:137], 0 op_sel_hi:[1,1,0]
	v_pk_fma_f32 v[96:97], v[0:1], v[132:133], 0 op_sel_hi:[1,1,0]
	v_pk_fma_f32 v[102:103], v[6:7], v[140:141], 0 op_sel_hi:[1,1,0]
	v_pk_fma_f32 v[100:101], v[4:5], v[138:139], 0 op_sel_hi:[1,1,0]
	v_pk_fma_f32 v[106:107], v[10:11], v[144:145], 0 op_sel_hi:[1,1,0]
	v_pk_fma_f32 v[104:105], v[8:9], v[142:143], 0 op_sel_hi:[1,1,0]
	v_pk_fma_f32 v[110:111], v[14:15], v[148:149], 0 op_sel_hi:[1,1,0]
	v_pk_fma_f32 v[108:109], v[12:13], v[146:147], 0 op_sel_hi:[1,1,0]
	v_pk_fma_f32 v[114:115], v[18:19], v[114:115], 0 op_sel_hi:[1,1,0]
	v_pk_fma_f32 v[112:113], v[16:17], v[112:113], 0 op_sel_hi:[1,1,0]
	v_pk_fma_f32 v[118:119], v[22:23], v[118:119], 0 op_sel_hi:[1,1,0]
	v_pk_fma_f32 v[116:117], v[20:21], v[116:117], 0 op_sel_hi:[1,1,0]
	v_pk_fma_f32 v[122:123], v[26:27], v[122:123], 0 op_sel_hi:[1,1,0]
	v_pk_fma_f32 v[120:121], v[24:25], v[120:121], 0 op_sel_hi:[1,1,0]
	v_pk_fma_f32 v[126:127], v[30:31], v[126:127], 0 op_sel_hi:[1,1,0]
	v_pk_fma_f32 v[124:125], v[28:29], v[124:125], 0 op_sel_hi:[1,1,0]
	global_store_dwordx4 v[54:55], v[64:67], off sc1
	global_store_dwordx4 v[54:55], v[68:71], off offset:1024 sc1
	global_store_dwordx4 v[54:55], v[72:75], off offset:2048 sc1
	global_store_dwordx4 v[54:55], v[76:79], off offset:3072 sc1
	global_store_dwordx4 v[128:129], v[80:83], off sc1
	global_store_dwordx4 v[128:129], v[84:87], off offset:1024 sc1
	global_store_dwordx4 v[128:129], v[88:91], off offset:2048 sc1
	global_store_dwordx4 v[128:129], v[92:95], off offset:3072 sc1
	global_store_dwordx4 v[56:57], v[96:99], off sc1
	global_store_dwordx4 v[56:57], v[100:103], off offset:1024 sc1
	global_store_dwordx4 v[56:57], v[104:107], off offset:2048 sc1
	global_store_dwordx4 v[56:57], v[108:111], off offset:3072 sc1
	global_store_dwordx4 v[130:131], v[112:115], off sc1
	global_store_dwordx4 v[130:131], v[116:119], off offset:1024 sc1
	global_store_dwordx4 v[130:131], v[120:123], off offset:2048 sc1
	global_store_dwordx4 v[130:131], v[124:127], off offset:3072 sc1
	s_cbranch_scc0 .LBB0_1088
	v_add_u32_e32 v49, s5, v49
	v_cmp_lt_i32_e32 vcc, s10, v49
	v_add_u32_e32 v46, s8, v46
	s_or_b64 s[2:3], vcc, s[2:3]
	v_add_u32_e32 v44, s8, v44
	s_andn2_b64 exec, exec, s[2:3]
	s_cbranch_execnz .LBB0_1087
